# permlane16_swap for 83 xor-16 exchange sites (adds non-in-place combines whose source is dead)
# speedup vs baseline: 1.0273x; 1.0017x over previous
.LBB0_251:
	v_lshl_add_u32 v177, s38, 8, v172
	v_add_u32_e32 v48, v177, v174
	v_add_u32_e32 v140, 0x40a0, v48
	v_mov_b32_e32 v141, v49
	v_lshl_add_u64 v[138:139], v[48:49], 2, s[22:23]
	v_lshl_add_u64 v[140:141], v[140:141], 2, s[22:23]
	global_load_dword v168, v[138:139], off
	global_load_dword v152, v[140:141], off
	v_add_u32_e32 v138, 0x4000, v48
	v_mov_b32_e32 v139, v49
	v_add_u32_e32 v156, 0x40b0, v48
	v_mov_b32_e32 v157, v49
	v_lshl_add_u64 v[138:139], v[138:139], 2, s[22:23]
	v_lshl_add_u64 v[156:157], v[156:157], 2, s[22:23]
	global_load_dword v170, v[138:139], off
	v_add_u32_e32 v140, 0x80a0, v48
	global_load_dword v156, v[156:157], off
	v_add_u32_e32 v138, 0x8000, v48
	v_mov_b32_e32 v139, v49
	v_lshl_add_u64 v[138:139], v[138:139], 2, s[22:23]
	global_load_dword v169, v[138:139], off
	v_add_u32_e32 v138, 0xc000, v48
	v_mov_b32_e32 v139, v49
	v_lshl_add_u64 v[138:139], v[138:139], 2, s[22:23]
	global_load_dword v171, v[138:139], off
	v_or_b32_e32 v138, 16, v48
	v_mov_b32_e32 v139, v49
	v_lshl_add_u64 v[138:139], v[138:139], 2, s[22:23]
	global_load_dword v150, v[138:139], off
	v_add_u32_e32 v138, 0x4010, v48
	v_mov_b32_e32 v139, v49
	v_lshl_add_u64 v[138:139], v[138:139], 2, s[22:23]
	global_load_dword v166, v[138:139], off
	v_add_u32_e32 v138, 0x8010, v48
	v_mov_b32_e32 v139, v49
	v_lshl_add_u64 v[138:139], v[138:139], 2, s[22:23]
	global_load_dword v151, v[138:139], off
	v_add_u32_e32 v138, 0xc010, v48
	v_mov_b32_e32 v139, v49
	v_lshl_add_u64 v[138:139], v[138:139], 2, s[22:23]
	global_load_dword v167, v[138:139], off
	v_or_b32_e32 v138, 32, v48
	v_mov_b32_e32 v139, v49
	v_lshl_add_u64 v[138:139], v[138:139], 2, s[22:23]
	global_load_dword v146, v[138:139], off
	v_add_u32_e32 v138, 0x4020, v48
	v_mov_b32_e32 v139, v49
	v_lshl_add_u64 v[138:139], v[138:139], 2, s[22:23]
	global_load_dword v162, v[138:139], off
	v_add_u32_e32 v138, 0x8020, v48
	v_mov_b32_e32 v139, v49
	v_lshl_add_u64 v[138:139], v[138:139], 2, s[22:23]
	global_load_dword v147, v[138:139], off
	v_add_u32_e32 v138, 0xc020, v48
	v_mov_b32_e32 v139, v49
	v_lshl_add_u64 v[138:139], v[138:139], 2, s[22:23]
	global_load_dword v163, v[138:139], off
	v_or_b32_e32 v138, 48, v48
	v_mov_b32_e32 v139, v49
	v_lshl_add_u64 v[138:139], v[138:139], 2, s[22:23]
	global_load_dword v148, v[138:139], off
	v_add_u32_e32 v138, 0x4030, v48
	v_mov_b32_e32 v139, v49
	v_lshl_add_u64 v[138:139], v[138:139], 2, s[22:23]
	global_load_dword v164, v[138:139], off
	v_add_u32_e32 v138, 0x8030, v48
	v_mov_b32_e32 v139, v49
	v_lshl_add_u64 v[138:139], v[138:139], 2, s[22:23]
	global_load_dword v149, v[138:139], off
	v_add_u32_e32 v138, 0xc030, v48
	v_mov_b32_e32 v139, v49
	v_lshl_add_u64 v[138:139], v[138:139], 2, s[22:23]
	global_load_dword v165, v[138:139], off
	v_add_u32_e32 v138, 0x80, v48
	v_mov_b32_e32 v139, v49
	v_lshl_add_u64 v[138:139], v[138:139], 2, s[22:23]
	global_load_dword v142, v[138:139], off
	v_add_u32_e32 v138, 0x4080, v48
	v_mov_b32_e32 v139, v49
	v_lshl_add_u64 v[138:139], v[138:139], 2, s[22:23]
	global_load_dword v158, v[138:139], off
	v_add_u32_e32 v138, 0x8080, v48
	v_mov_b32_e32 v139, v49
	v_lshl_add_u64 v[138:139], v[138:139], 2, s[22:23]
	global_load_dword v143, v[138:139], off
	v_add_u32_e32 v138, 0xc080, v48
	v_mov_b32_e32 v139, v49
	v_lshl_add_u64 v[138:139], v[138:139], 2, s[22:23]
	global_load_dword v159, v[138:139], off
	v_add_u32_e32 v138, 0x90, v48
	v_mov_b32_e32 v139, v49
	v_lshl_add_u64 v[138:139], v[138:139], 2, s[22:23]
	global_load_dword v144, v[138:139], off
	v_add_u32_e32 v138, 0x4090, v48
	v_mov_b32_e32 v139, v49
	v_lshl_add_u64 v[138:139], v[138:139], 2, s[22:23]
	global_load_dword v160, v[138:139], off
	v_add_u32_e32 v138, 0x8090, v48
	v_mov_b32_e32 v139, v49
	v_lshl_add_u64 v[138:139], v[138:139], 2, s[22:23]
	global_load_dword v145, v[138:139], off
	v_add_u32_e32 v138, 0xc090, v48
	v_mov_b32_e32 v139, v49
	v_lshl_add_u64 v[138:139], v[138:139], 2, s[22:23]
	global_load_dword v161, v[138:139], off
	v_add_u32_e32 v138, 0xa0, v48
	v_mov_b32_e32 v139, v49
	v_mov_b32_e32 v141, v49
	v_lshl_add_u64 v[138:139], v[138:139], 2, s[22:23]
	v_lshl_add_u64 v[140:141], v[140:141], 2, s[22:23]
	global_load_dword v138, v[138:139], off
	v_add_u32_e32 v178, 0x80b0, v48
	global_load_dword v139, v[140:141], off
	v_add_u32_e32 v140, 0xc0a0, v48
	v_mov_b32_e32 v141, v49
	v_lshl_add_u64 v[140:141], v[140:141], 2, s[22:23]
	global_load_dword v153, v[140:141], off
	v_add_u32_e32 v140, 0xb0, v48
	v_mov_b32_e32 v141, v49
	v_mov_b32_e32 v179, v49
	v_lshl_add_u64 v[140:141], v[140:141], 2, s[22:23]
	v_lshl_add_u64 v[178:179], v[178:179], 2, s[22:23]
	v_add_u32_e32 v48, 0xc0b0, v48
	global_load_dword v140, v[140:141], off
	s_waitcnt vmcnt(0)
	v_pk_add_f32 v[168:169], v[168:169], v[170:171]
	global_load_dword v141, v[178:179], off
	v_lshl_add_u64 v[178:179], v[48:49], 2, s[22:23]
	global_load_dword v157, v[178:179], off
	v_and_b32_e32 v178, 64, v205
	v_xor_b32_e32 v48, 16, v205
	v_add_u32_e32 v178, 64, v178
	v_cmp_lt_i32_e32 vcc, v48, v178
	v_pk_add_f32 v[150:151], v[150:151], v[166:167]
	s_mov_b32 s6, 0x358637bd
	v_cndmask_b32_e32 v48, v205, v48, vcc
	v_lshlrev_b32_e32 v178, 2, v48
	v_add_f32_e32 v48, v168, v169
	ds_bpermute_b32 v168, v178, v48
	v_pk_add_f32 v[146:147], v[146:147], v[162:163]
	v_mov_b64_e32 v[166:167], s[6:7]
	v_add_f32_e32 v146, v146, v147
	ds_bpermute_b32 v147, v178, v146
	s_waitcnt lgkmcnt(1)
	v_add_f32_e32 v169, v48, v168
	v_add_f32_e32 v48, v150, v151
	ds_bpermute_b32 v150, v178, v48
	v_mov_b32_e32 v171, v169
	s_waitcnt lgkmcnt(1)
	v_add_f32_e32 v147, v146, v147
	v_permlane32_swap_b32_e32 v169, v171
	s_waitcnt lgkmcnt(0)
	v_add_f32_e32 v168, v48, v150
	v_mov_b32_e32 v170, v168
	s_nop 1
	v_permlane32_swap_b32_e32 v168, v170
	v_pk_add_f32 v[148:149], v[148:149], v[164:165]
	v_pk_add_f32 v[150:151], v[168:169], v[170:171]
	v_add_f32_e32 v146, v148, v149
	v_pk_fma_f32 v[168:169], v[150:151], s[36:37], v[166:167] op_sel_hi:[1,0,0]
	v_mov_b32_e32 v163, v147
	v_mul_f32_e32 v48, 0x4b800000, v169
	v_cmp_gt_f32_e64 s[38:39], s75, v169
	s_waitcnt lgkmcnt(0)
	v_mov_b32_e32 v148, v146
	s_nop 1
	v_permlane16_swap_b32_e32 v146, v148
	v_add_f32_e32 v146, v146, v148
	v_mov_b32_e32 v162, v146
	v_cndmask_b32_e64 v48, v169, v48, s[38:39]
	v_rsq_f32_e32 v48, v48
	v_permlane32_swap_b32_e32 v147, v163
	v_permlane32_swap_b32_e32 v146, v162
	v_pk_add_f32 v[142:143], v[142:143], v[158:159]
	v_pk_add_f32 v[146:147], v[146:147], v[162:163]
	v_add_f32_e32 v142, v142, v143
	v_mul_f32_e32 v150, 0x45800000, v48
	v_pk_fma_f32 v[146:147], v[146:147], s[36:37], v[166:167] op_sel_hi:[1,0,0]
	v_cmp_gt_f32_e32 vcc, s75, v168
	v_cndmask_b32_e64 v150, v48, v150, s[38:39]
	s_waitcnt lgkmcnt(0)
	v_mov_b32_e32 v143, v142
	s_nop 1
	v_permlane16_swap_b32_e32 v142, v143
	v_add_f32_e32 v143, v142, v143
	v_mul_f32_e32 v48, 0x4b800000, v168
	v_mul_f32_e32 v148, 0x4b800000, v147
	v_cmp_gt_f32_e64 s[38:39], s75, v147
	v_cndmask_b32_e32 v48, v168, v48, vcc
	v_rsq_f32_e32 v48, v48
	v_cndmask_b32_e64 v147, v147, v148, s[38:39]
	v_pk_add_f32 v[144:145], v[144:145], v[160:161]
	v_rsq_f32_e32 v147, v147
	v_add_f32_e32 v142, v144, v145
	v_mov_b32_e32 v159, v143
	s_nop 1
	v_permlane32_swap_b32_e32 v143, v159
	v_mul_f32_e32 v151, 0x45800000, v48
	s_waitcnt lgkmcnt(0)
	v_mov_b32_e32 v144, v142
	s_nop 1
	v_permlane16_swap_b32_e32 v142, v144
	v_add_f32_e32 v142, v142, v144
	v_mov_b32_e32 v158, v142
	s_nop 1
	v_permlane32_swap_b32_e32 v142, v158
	v_pk_add_f32 v[138:139], v[138:139], v[152:153]
	v_pk_add_f32 v[142:143], v[142:143], v[158:159]
	v_add_f32_e32 v138, v138, v139
	v_mul_f32_e32 v148, 0x45800000, v147
	v_pk_fma_f32 v[142:143], v[142:143], s[36:37], v[166:167] op_sel_hi:[1,0,0]
	v_cndmask_b32_e32 v48, v48, v151, vcc
	v_cmp_gt_f32_e32 vcc, s75, v146
	s_waitcnt lgkmcnt(0)
	v_mov_b32_e32 v139, v138
	s_nop 1
	v_permlane16_swap_b32_e32 v138, v139
	v_add_f32_e32 v139, v138, v139
	v_cndmask_b32_e64 v148, v147, v148, s[38:39]
	v_mul_f32_e32 v147, 0x4b800000, v146
	s_waitcnt vmcnt(0)
	v_pk_add_f32 v[140:141], v[140:141], v[156:157]
	v_mul_f32_e32 v144, 0x4b800000, v143
	v_add_f32_e32 v138, v140, v141
	v_cmp_gt_f32_e64 s[38:39], s75, v143
	v_cndmask_b32_e32 v146, v146, v147, vcc
	v_rsq_f32_e32 v146, v146
	v_cndmask_b32_e64 v143, v143, v144, s[38:39]
	v_rsq_f32_e32 v143, v143
	s_waitcnt lgkmcnt(0)
	v_mov_b32_e32 v140, v138
	s_nop 1
	v_permlane16_swap_b32_e32 v138, v140
	v_add_f32_e32 v138, v138, v140
	v_mov_b32_e32 v153, v139
	v_mov_b32_e32 v152, v138
	s_nop 0
	v_permlane32_swap_b32_e32 v139, v153
	v_permlane32_swap_b32_e32 v138, v152
	v_pk_add_f32 v[138:139], v[138:139], v[152:153]
	v_mul_f32_e32 v147, 0x45800000, v146
	v_mul_f32_e32 v144, 0x45800000, v143
	v_pk_fma_f32 v[138:139], v[138:139], s[36:37], v[166:167] op_sel_hi:[1,0,0]
	v_cndmask_b32_e32 v146, v146, v147, vcc
	v_cmp_gt_f32_e32 vcc, s75, v142
	v_cndmask_b32_e64 v144, v143, v144, s[38:39]
	v_mul_f32_e32 v143, 0x4b800000, v142
	v_mul_f32_e32 v140, 0x4b800000, v139
	v_cmp_gt_f32_e64 s[38:39], s75, v139
	v_cndmask_b32_e32 v142, v142, v143, vcc
	v_rsq_f32_e32 v142, v142
	v_cndmask_b32_e64 v139, v139, v140, s[38:39]
	v_rsq_f32_e32 v139, v139
	v_pk_mul_f32 v[126:127], v[126:127], v[150:151] op_sel_hi:[1,0]
	v_mul_f32_e32 v143, 0x45800000, v142
	v_cndmask_b32_e32 v142, v142, v143, vcc
	v_mul_f32_e32 v140, 0x45800000, v139
	v_cmp_gt_f32_e32 vcc, s75, v138
	v_cndmask_b32_e64 v140, v139, v140, s[38:39]
	v_mul_f32_e32 v139, 0x4b800000, v138
	v_cndmask_b32_e32 v138, v138, v139, vcc
	v_rsq_f32_e32 v138, v138
	v_pk_mul_f32 v[122:123], v[122:123], v[150:151] op_sel_hi:[1,0]
	v_pk_mul_f32 v[124:125], v[124:125], v[150:151] op_sel_hi:[1,0]
	v_pk_mul_f32 v[122:123], v[126:127], v[122:123]
	v_mul_f32_e32 v139, 0x45800000, v138
	v_cndmask_b32_e32 v138, v138, v139, vcc
	v_mul_f32_e32 v139, 0xbfb8aa3b, v126
	v_mul_f32_e32 v126, 0xbfb8aa3b, v127
	v_exp_f32_e32 v126, v126
	v_exp_f32_e32 v139, v139
	v_pk_mul_f32 v[118:119], v[118:119], v[150:151] op_sel_hi:[1,0]
	v_pk_mul_f32 v[114:115], v[114:115], v[150:151] op_sel_hi:[1,0]
	v_add_f32_e32 v126, 1.0, v126
	v_rcp_f32_e32 v157, v126
	v_pk_mul_f32 v[126:127], v[128:129], v[150:151] op_sel_hi:[1,0]
	v_add_f32_e32 v139, 1.0, v139
	v_mul_f32_e32 v128, 0xbfb8aa3b, v126
	v_pk_mul_f32 v[124:125], v[126:127], v[124:125]
	v_mul_f32_e32 v126, 0xbfb8aa3b, v127
	v_exp_f32_e32 v128, v128
	v_exp_f32_e32 v126, v126
	v_rcp_f32_e32 v156, v139
	v_pk_mul_f32 v[114:115], v[118:119], v[114:115]
	v_add_f32_e32 v128, 1.0, v128
	v_add_f32_e32 v126, 1.0, v126
	v_rcp_f32_e32 v128, v128
	v_rcp_f32_e32 v129, v126
	v_pk_mul_f32 v[122:123], v[122:123], v[156:157]
	v_pk_mul_f32 v[116:117], v[116:117], v[150:151] op_sel_hi:[1,0]
	v_cvt_pk_bf16_f32 v122, v122, v123
	v_pk_mul_f32 v[124:125], v[124:125], v[128:129]
	v_lshl_or_b32 v152, s18, 7, v175
	v_cvt_pk_bf16_f32 v123, v124, v125
	v_mul_f32_e32 v124, 0xbfb8aa3b, v118
	v_mul_f32_e32 v118, 0xbfb8aa3b, v119
	v_exp_f32_e32 v118, v118
	v_exp_f32_e32 v124, v124
	s_movk_i32 s6, 0xb00
	v_pk_mul_f32 v[110:111], v[110:111], v[48:49] op_sel_hi:[1,0]
	v_add_f32_e32 v118, 1.0, v118
	v_rcp_f32_e32 v125, v118
	v_pk_mul_f32 v[118:119], v[120:121], v[150:151] op_sel_hi:[1,0]
	v_add_f32_e32 v124, 1.0, v124
	v_mul_f32_e32 v120, 0xbfb8aa3b, v118
	v_pk_mul_f32 v[116:117], v[118:119], v[116:117]
	v_mul_f32_e32 v118, 0xbfb8aa3b, v119
	v_exp_f32_e32 v120, v120
	v_exp_f32_e32 v118, v118
	v_rcp_f32_e32 v124, v124
	v_pk_mul_f32 v[106:107], v[106:107], v[48:49] op_sel_hi:[1,0]
	v_add_f32_e32 v120, 1.0, v120
	v_add_f32_e32 v118, 1.0, v118
	v_rcp_f32_e32 v120, v120
	v_rcp_f32_e32 v121, v118
	v_pk_mul_f32 v[114:115], v[114:115], v[124:125]
	v_pk_mul_f32 v[106:107], v[110:111], v[106:107]
	v_cvt_pk_bf16_f32 v124, v114, v115
	v_mad_u64_u32 v[114:115], s[20:21], v177, s6, v[152:153]
	v_pk_mul_f32 v[116:117], v[116:117], v[120:121]
	v_mov_b32_e32 v115, v49
	v_cvt_pk_bf16_f32 v125, v116, v117
	v_lshl_add_u64 v[116:117], v[114:115], 1, s[12:13]
	v_mul_f32_e32 v115, 0xbfb8aa3b, v110
	v_mul_f32_e32 v110, 0xbfb8aa3b, v111
	v_exp_f32_e32 v110, v110
	global_store_dwordx4 v[116:117], v[122:125], off
	s_nop 1
	v_pk_mul_f32 v[108:109], v[108:109], v[48:49] op_sel_hi:[1,0]
	v_exp_f32_e32 v115, v115
	v_add_f32_e32 v110, 1.0, v110
	v_rcp_f32_e32 v117, v110
	v_pk_mul_f32 v[110:111], v[112:113], v[48:49] op_sel_hi:[1,0]
	v_add_f32_e32 v115, 1.0, v115
	v_mul_f32_e32 v112, 0xbfb8aa3b, v110
	v_pk_mul_f32 v[108:109], v[110:111], v[108:109]
	v_mul_f32_e32 v110, 0xbfb8aa3b, v111
	v_exp_f32_e32 v112, v112
	v_exp_f32_e32 v110, v110
	v_rcp_f32_e32 v116, v115
	v_pk_mul_f32 v[102:103], v[102:103], v[48:49] op_sel_hi:[1,0]
	v_add_f32_e32 v112, 1.0, v112
	v_add_f32_e32 v110, 1.0, v110
	v_rcp_f32_e32 v112, v112
	v_rcp_f32_e32 v113, v110
	v_pk_mul_f32 v[106:107], v[106:107], v[116:117]
	v_pk_mul_f32 v[98:99], v[98:99], v[48:49] op_sel_hi:[1,0]
	v_cvt_pk_bf16_f32 v106, v106, v107
	v_pk_mul_f32 v[108:109], v[108:109], v[112:113]
	v_pk_mul_f32 v[98:99], v[102:103], v[98:99]
	v_cvt_pk_bf16_f32 v107, v108, v109
	v_mul_f32_e32 v108, 0xbfb8aa3b, v102
	v_mul_f32_e32 v102, 0xbfb8aa3b, v103
	v_exp_f32_e32 v102, v102
	v_exp_f32_e32 v108, v108
	v_pk_mul_f32 v[100:101], v[100:101], v[48:49] op_sel_hi:[1,0]
	v_pk_mul_f32 v[94:95], v[94:95], v[148:149] op_sel_hi:[1,0]
	v_add_f32_e32 v102, 1.0, v102
	v_rcp_f32_e32 v109, v102
	v_pk_mul_f32 v[102:103], v[104:105], v[48:49] op_sel_hi:[1,0]
	v_add_f32_e32 v108, 1.0, v108
	v_mul_f32_e32 v48, 0xbfb8aa3b, v103
	v_exp_f32_e32 v48, v48
	v_rcp_f32_e32 v108, v108
	v_mul_f32_e32 v104, 0xbfb8aa3b, v102
	v_exp_f32_e32 v104, v104
	v_add_f32_e32 v48, 1.0, v48
	v_pk_mul_f32 v[98:99], v[98:99], v[108:109]
	v_rcp_f32_e32 v105, v48
	v_add_u32_e32 v48, 0xb000, v114
	v_add_f32_e32 v104, 1.0, v104
	v_cvt_pk_bf16_f32 v108, v98, v99
	v_lshl_add_u64 v[98:99], v[48:49], 1, s[12:13]
	v_mul_f32_e32 v48, 0xbfb8aa3b, v94
	v_rcp_f32_e32 v104, v104
	v_exp_f32_e32 v48, v48
	v_pk_mul_f32 v[100:101], v[102:103], v[100:101]
	v_pk_mul_f32 v[90:91], v[90:91], v[148:149] op_sel_hi:[1,0]
	v_pk_mul_f32 v[100:101], v[100:101], v[104:105]
	v_add_f32_e32 v48, 1.0, v48
	v_cvt_pk_bf16_f32 v109, v100, v101
	global_store_dwordx4 v[98:99], v[106:109], off
	s_nop 1
	v_rcp_f32_e32 v98, v48
	v_mul_f32_e32 v48, 0xbfb8aa3b, v95
	v_exp_f32_e32 v48, v48
	v_pk_mul_f32 v[90:91], v[94:95], v[90:91]
	v_pk_mul_f32 v[94:95], v[96:97], v[148:149] op_sel_hi:[1,0]
	v_pk_mul_f32 v[86:87], v[86:87], v[148:149] op_sel_hi:[1,0]
	v_add_f32_e32 v48, 1.0, v48
	v_rcp_f32_e32 v99, v48
	v_mul_f32_e32 v48, 0xbfb8aa3b, v94
	v_exp_f32_e32 v48, v48
	v_pk_mul_f32 v[92:93], v[92:93], v[148:149] op_sel_hi:[1,0]
	v_pk_mul_f32 v[90:91], v[90:91], v[98:99]
	v_pk_mul_f32 v[92:93], v[94:95], v[92:93]
	v_add_f32_e32 v48, 1.0, v48
	v_rcp_f32_e32 v96, v48
	v_mul_f32_e32 v48, 0xbfb8aa3b, v95
	v_exp_f32_e32 v48, v48
	v_cvt_pk_bf16_f32 v90, v90, v91
	v_pk_mul_f32 v[82:83], v[82:83], v[148:149] op_sel_hi:[1,0]
	v_pk_mul_f32 v[78:79], v[78:79], v[146:147] op_sel_hi:[1,0]
	v_add_f32_e32 v48, 1.0, v48
	v_rcp_f32_e32 v97, v48
	v_mul_f32_e32 v48, 0xbfb8aa3b, v86
	v_exp_f32_e32 v48, v48
	v_pk_mul_f32 v[82:83], v[86:87], v[82:83]
	v_pk_mul_f32 v[92:93], v[92:93], v[96:97]
	v_pk_mul_f32 v[84:85], v[84:85], v[148:149] op_sel_hi:[1,0]
	v_add_f32_e32 v48, 1.0, v48
	v_cvt_pk_bf16_f32 v91, v92, v93
	v_rcp_f32_e32 v92, v48
	v_mul_f32_e32 v48, 0xbfb8aa3b, v87
	v_exp_f32_e32 v48, v48
	v_pk_mul_f32 v[86:87], v[88:89], v[148:149] op_sel_hi:[1,0]
	v_pk_mul_f32 v[74:75], v[74:75], v[146:147] op_sel_hi:[1,0]
	v_pk_mul_f32 v[84:85], v[86:87], v[84:85]
	v_add_f32_e32 v48, 1.0, v48
	v_rcp_f32_e32 v93, v48
	v_mul_f32_e32 v48, 0xbfb8aa3b, v86
	v_exp_f32_e32 v48, v48
	v_pk_mul_f32 v[74:75], v[78:79], v[74:75]
	v_pk_mul_f32 v[82:83], v[82:83], v[92:93]
	v_pk_mul_f32 v[70:71], v[70:71], v[146:147] op_sel_hi:[1,0]
	v_add_f32_e32 v48, 1.0, v48
	v_rcp_f32_e32 v88, v48
	v_mul_f32_e32 v48, 0xbfb8aa3b, v87
	v_exp_f32_e32 v48, v48
	v_cvt_pk_bf16_f32 v92, v82, v83
	v_pk_mul_f32 v[76:77], v[76:77], v[146:147] op_sel_hi:[1,0]
	v_pk_mul_f32 v[66:67], v[66:67], v[146:147] op_sel_hi:[1,0]
	v_add_f32_e32 v48, 1.0, v48
	v_rcp_f32_e32 v89, v48
	v_add_u32_e32 v48, 0x16000, v114
	v_lshl_add_u64 v[82:83], v[48:49], 1, s[12:13]
	v_mul_f32_e32 v48, 0xbfb8aa3b, v78
	v_exp_f32_e32 v48, v48
	v_pk_mul_f32 v[84:85], v[84:85], v[88:89]
	v_pk_mul_f32 v[66:67], v[70:71], v[66:67]
	v_cvt_pk_bf16_f32 v93, v84, v85
	v_add_f32_e32 v48, 1.0, v48
	global_store_dwordx4 v[82:83], v[90:93], off
	s_nop 1
	v_rcp_f32_e32 v82, v48
	v_mul_f32_e32 v48, 0xbfb8aa3b, v79
	v_exp_f32_e32 v48, v48
	v_pk_mul_f32 v[78:79], v[80:81], v[146:147] op_sel_hi:[1,0]
	v_pk_mul_f32 v[62:63], v[62:63], v[144:145] op_sel_hi:[1,0]
	v_pk_mul_f32 v[76:77], v[78:79], v[76:77]
	v_add_f32_e32 v48, 1.0, v48
	v_rcp_f32_e32 v83, v48
	v_mul_f32_e32 v48, 0xbfb8aa3b, v78
	v_exp_f32_e32 v48, v48
	v_pk_mul_f32 v[68:69], v[68:69], v[146:147] op_sel_hi:[1,0]
	v_pk_mul_f32 v[74:75], v[74:75], v[82:83]
	v_pk_mul_f32 v[58:59], v[58:59], v[144:145] op_sel_hi:[1,0]
	v_add_f32_e32 v48, 1.0, v48
	v_rcp_f32_e32 v80, v48
	v_mul_f32_e32 v48, 0xbfb8aa3b, v79
	v_exp_f32_e32 v48, v48
	v_cvt_pk_bf16_f32 v74, v74, v75
	v_pk_mul_f32 v[58:59], v[62:63], v[58:59]
	v_pk_mul_f32 v[54:55], v[54:55], v[144:145] op_sel_hi:[1,0]
	v_add_f32_e32 v48, 1.0, v48
	v_rcp_f32_e32 v81, v48
	v_mul_f32_e32 v48, 0xbfb8aa3b, v70
	v_exp_f32_e32 v48, v48
	v_pk_mul_f32 v[60:61], v[60:61], v[144:145] op_sel_hi:[1,0]
	v_pk_mul_f32 v[76:77], v[76:77], v[80:81]
	v_pk_mul_f32 v[50:51], v[50:51], v[144:145] op_sel_hi:[1,0]
	v_add_f32_e32 v48, 1.0, v48
	v_cvt_pk_bf16_f32 v75, v76, v77
	v_rcp_f32_e32 v76, v48
	v_mul_f32_e32 v48, 0xbfb8aa3b, v71
	v_exp_f32_e32 v48, v48
	v_pk_mul_f32 v[70:71], v[72:73], v[146:147] op_sel_hi:[1,0]
	v_pk_mul_f32 v[50:51], v[54:55], v[50:51]
	v_pk_mul_f32 v[68:69], v[70:71], v[68:69]
	v_add_f32_e32 v48, 1.0, v48
	v_rcp_f32_e32 v77, v48
	v_mul_f32_e32 v48, 0xbfb8aa3b, v70
	v_exp_f32_e32 v48, v48
	v_pk_mul_f32 v[44:45], v[44:45], v[142:143] op_sel_hi:[1,0]
	v_pk_mul_f32 v[66:67], v[66:67], v[76:77]
	v_pk_mul_f32 v[40:41], v[40:41], v[142:143] op_sel_hi:[1,0]
	v_add_f32_e32 v48, 1.0, v48
	v_rcp_f32_e32 v72, v48
	v_mul_f32_e32 v48, 0xbfb8aa3b, v71
	v_exp_f32_e32 v48, v48
	v_cvt_pk_bf16_f32 v76, v66, v67
	v_pk_mul_f32 v[40:41], v[44:45], v[40:41]
	v_pk_mul_f32 v[52:53], v[52:53], v[144:145] op_sel_hi:[1,0]
	v_add_f32_e32 v48, 1.0, v48
	v_rcp_f32_e32 v73, v48
	v_add_u32_e32 v48, 0x21000, v114
	v_lshl_add_u64 v[66:67], v[48:49], 1, s[12:13]
	v_mul_f32_e32 v48, 0xbfb8aa3b, v62
	v_exp_f32_e32 v48, v48
	v_pk_mul_f32 v[68:69], v[68:69], v[72:73]
	v_pk_mul_f32 v[42:43], v[42:43], v[142:143] op_sel_hi:[1,0]
	v_cvt_pk_bf16_f32 v77, v68, v69
	v_add_f32_e32 v48, 1.0, v48
	global_store_dwordx4 v[66:67], v[74:77], off
	s_nop 1
	v_rcp_f32_e32 v66, v48
	v_mul_f32_e32 v48, 0xbfb8aa3b, v63
	v_exp_f32_e32 v48, v48
	v_pk_mul_f32 v[62:63], v[64:65], v[144:145] op_sel_hi:[1,0]
	v_pk_mul_f32 v[36:37], v[36:37], v[142:143] op_sel_hi:[1,0]
	v_pk_mul_f32 v[60:61], v[62:63], v[60:61]
	v_add_f32_e32 v48, 1.0, v48
	v_rcp_f32_e32 v67, v48
	v_mul_f32_e32 v48, 0xbfb8aa3b, v62
	v_exp_f32_e32 v48, v48
	v_pk_mul_f32 v[32:33], v[32:33], v[142:143] op_sel_hi:[1,0]
	v_pk_mul_f32 v[58:59], v[58:59], v[66:67]
	v_pk_mul_f32 v[32:33], v[36:37], v[32:33]
	v_add_f32_e32 v48, 1.0, v48
	v_rcp_f32_e32 v64, v48
	v_mul_f32_e32 v48, 0xbfb8aa3b, v63
	v_exp_f32_e32 v48, v48
	v_cvt_pk_bf16_f32 v58, v58, v59
	v_pk_mul_f32 v[34:35], v[34:35], v[142:143] op_sel_hi:[1,0]
	v_pk_mul_f32 v[28:29], v[28:29], v[140:141] op_sel_hi:[1,0]
	v_add_f32_e32 v48, 1.0, v48
	v_rcp_f32_e32 v65, v48
	v_mul_f32_e32 v48, 0xbfb8aa3b, v54
	v_exp_f32_e32 v48, v48
	v_pk_mul_f32 v[24:25], v[24:25], v[140:141] op_sel_hi:[1,0]
	v_pk_mul_f32 v[60:61], v[60:61], v[64:65]
	v_pk_mul_f32 v[24:25], v[28:29], v[24:25]
	v_add_f32_e32 v48, 1.0, v48
	v_cvt_pk_bf16_f32 v59, v60, v61
	v_rcp_f32_e32 v60, v48
	v_mul_f32_e32 v48, 0xbfb8aa3b, v55
	v_exp_f32_e32 v48, v48
	v_pk_mul_f32 v[54:55], v[56:57], v[144:145] op_sel_hi:[1,0]
	v_pk_mul_f32 v[26:27], v[26:27], v[140:141] op_sel_hi:[1,0]
	v_pk_mul_f32 v[52:53], v[54:55], v[52:53]
	v_add_f32_e32 v48, 1.0, v48
	v_rcp_f32_e32 v61, v48
	v_mul_f32_e32 v48, 0xbfb8aa3b, v54
	v_exp_f32_e32 v48, v48
	v_pk_mul_f32 v[20:21], v[20:21], v[140:141] op_sel_hi:[1,0]
	v_pk_mul_f32 v[50:51], v[50:51], v[60:61]
	v_pk_mul_f32 v[16:17], v[16:17], v[140:141] op_sel_hi:[1,0]
	v_add_f32_e32 v48, 1.0, v48
	v_rcp_f32_e32 v56, v48
	v_mul_f32_e32 v48, 0xbfb8aa3b, v55
	v_exp_f32_e32 v48, v48
	v_cvt_pk_bf16_f32 v60, v50, v51
	v_pk_mul_f32 v[16:17], v[20:21], v[16:17]
	v_pk_mul_f32 v[18:19], v[18:19], v[140:141] op_sel_hi:[1,0]
	v_add_f32_e32 v48, 1.0, v48
	v_rcp_f32_e32 v57, v48
	v_add_u32_e32 v48, 0x58000, v114
	v_lshl_add_u64 v[50:51], v[48:49], 1, s[12:13]
	v_mul_f32_e32 v48, 0xbfb8aa3b, v44
	v_mul_f32_e32 v44, 0xbfb8aa3b, v45
	v_exp_f32_e32 v44, v44
	v_pk_mul_f32 v[52:53], v[52:53], v[56:57]
	v_exp_f32_e32 v48, v48
	v_cvt_pk_bf16_f32 v61, v52, v53
	v_add_f32_e32 v44, 1.0, v44
	global_store_dwordx4 v[50:51], v[58:61], off
	s_nop 1
	v_rcp_f32_e32 v51, v44
	v_pk_mul_f32 v[44:45], v[46:47], v[142:143] op_sel_hi:[1,0]
	v_add_f32_e32 v48, 1.0, v48
	v_mul_f32_e32 v46, 0xbfb8aa3b, v44
	v_pk_mul_f32 v[42:43], v[44:45], v[42:43]
	v_mul_f32_e32 v44, 0xbfb8aa3b, v45
	v_exp_f32_e32 v46, v46
	v_exp_f32_e32 v44, v44
	v_rcp_f32_e32 v50, v48
	v_add_u32_e32 v48, 0x63000, v114
	v_add_f32_e32 v46, 1.0, v46
	v_add_f32_e32 v44, 1.0, v44
	v_rcp_f32_e32 v46, v46
	v_rcp_f32_e32 v47, v44
	v_pk_mul_f32 v[40:41], v[40:41], v[50:51]
	v_pk_mul_f32 v[12:13], v[12:13], v[138:139] op_sel_hi:[1,0]
	v_cvt_pk_bf16_f32 v40, v40, v41
	v_pk_mul_f32 v[42:43], v[42:43], v[46:47]
	v_pk_mul_f32 v[8:9], v[8:9], v[138:139] op_sel_hi:[1,0]
	v_cvt_pk_bf16_f32 v41, v42, v43
	v_mul_f32_e32 v42, 0xbfb8aa3b, v36
	v_mul_f32_e32 v36, 0xbfb8aa3b, v37
	v_exp_f32_e32 v36, v36
	v_exp_f32_e32 v42, v42
	v_pk_mul_f32 v[8:9], v[12:13], v[8:9]
	v_pk_mul_f32 v[10:11], v[10:11], v[138:139] op_sel_hi:[1,0]
	v_add_f32_e32 v36, 1.0, v36
	v_rcp_f32_e32 v43, v36
	v_pk_mul_f32 v[36:37], v[38:39], v[142:143] op_sel_hi:[1,0]
	v_add_f32_e32 v42, 1.0, v42
	v_mul_f32_e32 v38, 0xbfb8aa3b, v36
	v_pk_mul_f32 v[34:35], v[36:37], v[34:35]
	v_mul_f32_e32 v36, 0xbfb8aa3b, v37
	v_exp_f32_e32 v38, v38
	v_exp_f32_e32 v36, v36
	v_rcp_f32_e32 v42, v42
	v_pk_mul_f32 v[4:5], v[4:5], v[138:139] op_sel_hi:[1,0]
	v_add_f32_e32 v38, 1.0, v38
	v_add_f32_e32 v36, 1.0, v36
	v_rcp_f32_e32 v38, v38
	v_rcp_f32_e32 v39, v36
	v_pk_mul_f32 v[32:33], v[32:33], v[42:43]
	v_pk_mul_f32 v[0:1], v[0:1], v[138:139] op_sel_hi:[1,0]
	v_cvt_pk_bf16_f32 v42, v32, v33
	v_pk_mul_f32 v[34:35], v[34:35], v[38:39]
	v_lshl_add_u64 v[32:33], v[48:49], 1, s[12:13]
	v_cvt_pk_bf16_f32 v43, v34, v35
	global_store_dwordx4 v[32:33], v[40:43], off
	s_nop 1
	v_mul_f32_e32 v32, 0xbfb8aa3b, v28
	v_mul_f32_e32 v28, 0xbfb8aa3b, v29
	v_exp_f32_e32 v28, v28
	v_exp_f32_e32 v32, v32
	v_add_u32_e32 v48, 0x6e000, v114
	v_pk_mul_f32 v[0:1], v[4:5], v[0:1]
	v_add_f32_e32 v28, 1.0, v28
	v_rcp_f32_e32 v33, v28
	v_pk_mul_f32 v[28:29], v[30:31], v[140:141] op_sel_hi:[1,0]
	v_add_f32_e32 v32, 1.0, v32
	v_mul_f32_e32 v30, 0xbfb8aa3b, v28
	v_pk_mul_f32 v[26:27], v[28:29], v[26:27]
	v_mul_f32_e32 v28, 0xbfb8aa3b, v29
	v_exp_f32_e32 v30, v30
	v_exp_f32_e32 v28, v28
	v_rcp_f32_e32 v32, v32
	v_pk_mul_f32 v[2:3], v[2:3], v[138:139] op_sel_hi:[1,0]
	v_add_f32_e32 v30, 1.0, v30
	v_add_f32_e32 v28, 1.0, v28
	v_rcp_f32_e32 v30, v30
	v_rcp_f32_e32 v31, v28
	v_pk_mul_f32 v[24:25], v[24:25], v[32:33]
	s_mov_b64 s[38:39], -1
	v_cvt_pk_bf16_f32 v24, v24, v25
	v_pk_mul_f32 v[26:27], v[26:27], v[30:31]
	s_andn2_b64 vcc, exec, s[48:49]
	v_cvt_pk_bf16_f32 v25, v26, v27
	v_mul_f32_e32 v26, 0xbfb8aa3b, v20
	v_mul_f32_e32 v20, 0xbfb8aa3b, v21
	v_exp_f32_e32 v20, v20
	v_exp_f32_e32 v26, v26
	v_add_f32_e32 v20, 1.0, v20
	v_rcp_f32_e32 v27, v20
	v_pk_mul_f32 v[20:21], v[22:23], v[140:141] op_sel_hi:[1,0]
	v_add_f32_e32 v26, 1.0, v26
	v_mul_f32_e32 v22, 0xbfb8aa3b, v20
	v_pk_mul_f32 v[18:19], v[20:21], v[18:19]
	v_mul_f32_e32 v20, 0xbfb8aa3b, v21
	v_exp_f32_e32 v22, v22
	v_exp_f32_e32 v20, v20
	v_rcp_f32_e32 v26, v26
	v_add_f32_e32 v22, 1.0, v22
	v_add_f32_e32 v20, 1.0, v20
	v_rcp_f32_e32 v22, v22
	v_rcp_f32_e32 v23, v20
	v_pk_mul_f32 v[16:17], v[16:17], v[26:27]
	v_pk_mul_f32 v[18:19], v[18:19], v[22:23]
	v_cvt_pk_bf16_f32 v26, v16, v17
	v_lshl_add_u64 v[16:17], v[48:49], 1, s[12:13]
	v_cvt_pk_bf16_f32 v27, v18, v19
	global_store_dwordx4 v[16:17], v[24:27], off
	s_nop 1
	v_mul_f32_e32 v16, 0xbfb8aa3b, v12
	v_mul_f32_e32 v12, 0xbfb8aa3b, v13
	v_exp_f32_e32 v12, v12
	v_exp_f32_e32 v16, v16
	v_add_u32_e32 v48, 0x79000, v114
	v_add_f32_e32 v12, 1.0, v12
	v_rcp_f32_e32 v17, v12
	v_pk_mul_f32 v[12:13], v[14:15], v[138:139] op_sel_hi:[1,0]
	v_add_f32_e32 v16, 1.0, v16
	v_mul_f32_e32 v14, 0xbfb8aa3b, v12
	v_pk_mul_f32 v[10:11], v[12:13], v[10:11]
	v_mul_f32_e32 v12, 0xbfb8aa3b, v13
	v_exp_f32_e32 v14, v14
	v_exp_f32_e32 v12, v12
	v_rcp_f32_e32 v16, v16
	v_add_f32_e32 v14, 1.0, v14
	v_add_f32_e32 v12, 1.0, v12
	v_rcp_f32_e32 v14, v14
	v_rcp_f32_e32 v15, v12
	v_pk_mul_f32 v[8:9], v[8:9], v[16:17]
	v_pk_mul_f32 v[10:11], v[10:11], v[14:15]
	v_cvt_pk_bf16_f32 v8, v8, v9
	v_cvt_pk_bf16_f32 v9, v10, v11
	v_mul_f32_e32 v10, 0xbfb8aa3b, v4
	v_mul_f32_e32 v4, 0xbfb8aa3b, v5
	v_exp_f32_e32 v4, v4
	v_exp_f32_e32 v10, v10
	v_add_f32_e32 v4, 1.0, v4
	v_rcp_f32_e32 v11, v4
	v_pk_mul_f32 v[4:5], v[6:7], v[138:139] op_sel_hi:[1,0]
	v_add_f32_e32 v10, 1.0, v10
	v_mul_f32_e32 v6, 0xbfb8aa3b, v4
	v_pk_mul_f32 v[2:3], v[4:5], v[2:3]
	v_mul_f32_e32 v4, 0xbfb8aa3b, v5
	v_exp_f32_e32 v6, v6
	v_exp_f32_e32 v4, v4
	v_rcp_f32_e32 v10, v10
	v_add_f32_e32 v6, 1.0, v6
	v_add_f32_e32 v4, 1.0, v4
	v_rcp_f32_e32 v6, v6
	v_rcp_f32_e32 v7, v4
	v_pk_mul_f32 v[0:1], v[0:1], v[10:11]
	v_pk_mul_f32 v[2:3], v[2:3], v[6:7]
	v_cvt_pk_bf16_f32 v10, v0, v1
	v_cvt_pk_bf16_f32 v11, v2, v3
	v_lshl_add_u64 v[0:1], v[48:49], 1, s[12:13]
	global_store_dwordx4 v[0:1], v[8:11], off
	s_nop 1
	s_cbranch_vccnz .LBB0_244
	s_andn2_b64 vcc, exec, s[40:41]
	s_cbranch_vccnz .LBB0_243
	s_barrier
	s_branch .LBB0_243

.LBB0_588:
	v_lshl_add_u32 v179, s42, 8, v174
	v_add_u32_e32 v48, v179, v176
	v_add_u32_e32 v144, 0x4000, v48
	v_mov_b32_e32 v145, v49
	v_add_u32_e32 v146, 0x8000, v48
	v_mov_b32_e32 v147, v49
	v_add_u32_e32 v150, 0x4020, v48
	v_mov_b32_e32 v151, v49
	v_add_u32_e32 v158, 0x4030, v48
	v_mov_b32_e32 v159, v49
	v_lshl_add_u64 v[142:143], v[48:49], 2, s[22:23]
	v_lshl_add_u64 v[144:145], v[144:145], 2, s[22:23]
	v_lshl_add_u64 v[146:147], v[146:147], 2, s[22:23]
	v_lshl_add_u64 v[150:151], v[150:151], 2, s[22:23]
	v_lshl_add_u64 v[158:159], v[158:159], 2, s[22:23]
	global_load_dword v142, v[142:143], off
	s_movk_i32 s6, 0x600
	global_load_dword v144, v[144:145], off
	s_cmp_lt_i32 s44, 1
	global_load_dword v152, v[150:151], off
	global_load_dword v143, v[146:147], off
	global_load_dword v160, v[158:159], off
	v_add_u32_e32 v146, 0xc000, v48
	v_mov_b32_e32 v147, v49
	v_lshl_add_u64 v[146:147], v[146:147], 2, s[22:23]
	global_load_dword v145, v[146:147], off
	v_or_b32_e32 v146, 16, v48
	v_mov_b32_e32 v147, v49
	v_lshl_add_u64 v[146:147], v[146:147], 2, s[22:23]
	global_load_dword v148, v[146:147], off
	v_add_u32_e32 v146, 0x4010, v48
	v_mov_b32_e32 v147, v49
	v_lshl_add_u64 v[146:147], v[146:147], 2, s[22:23]
	global_load_dword v156, v[146:147], off
	v_add_u32_e32 v146, 0x8010, v48
	v_mov_b32_e32 v147, v49
	v_lshl_add_u64 v[146:147], v[146:147], 2, s[22:23]
	global_load_dword v149, v[146:147], off
	v_add_u32_e32 v146, 0xc010, v48
	v_mov_b32_e32 v147, v49
	v_lshl_add_u64 v[146:147], v[146:147], 2, s[22:23]
	global_load_dword v157, v[146:147], off
	v_or_b32_e32 v146, 32, v48
	v_mov_b32_e32 v147, v49
	v_add_u32_e32 v150, 0x8020, v48
	v_mov_b32_e32 v151, v49
	v_lshl_add_u64 v[146:147], v[146:147], 2, s[22:23]
	v_lshl_add_u64 v[150:151], v[150:151], 2, s[22:23]
	global_load_dword v146, v[146:147], off
	v_add_u32_e32 v158, 0x8030, v48
	global_load_dword v147, v[150:151], off
	v_add_u32_e32 v150, 0xc020, v48
	v_mov_b32_e32 v151, v49
	v_lshl_add_u64 v[150:151], v[150:151], 2, s[22:23]
	global_load_dword v153, v[150:151], off
	v_or_b32_e32 v150, 48, v48
	v_mov_b32_e32 v151, v49
	v_mov_b32_e32 v159, v49
	v_lshl_add_u64 v[150:151], v[150:151], 2, s[22:23]
	v_lshl_add_u64 v[158:159], v[158:159], 2, s[22:23]
	global_load_dword v150, v[150:151], off
	s_waitcnt vmcnt(0)
	v_pk_add_f32 v[142:143], v[142:143], v[144:145]
	global_load_dword v151, v[158:159], off
	v_add_u32_e32 v158, 0xc030, v48
	v_mov_b32_e32 v159, v49
	v_lshl_add_u64 v[158:159], v[158:159], 2, s[22:23]
	global_load_dword v161, v[158:159], off
	v_add_u32_e32 v158, 0x80, v48
	v_mov_b32_e32 v159, v49
	v_lshl_add_u64 v[158:159], v[158:159], 2, s[22:23]
	global_load_dword v162, v[158:159], off
	v_add_u32_e32 v158, 0x4080, v48
	v_mov_b32_e32 v159, v49
	v_lshl_add_u64 v[158:159], v[158:159], 2, s[22:23]
	global_load_dword v166, v[158:159], off
	v_add_u32_e32 v158, 0x8080, v48
	v_mov_b32_e32 v159, v49
	v_lshl_add_u64 v[158:159], v[158:159], 2, s[22:23]
	global_load_dword v163, v[158:159], off
	v_add_u32_e32 v158, 0xc080, v48
	v_mov_b32_e32 v159, v49
	v_lshl_add_u64 v[158:159], v[158:159], 2, s[22:23]
	global_load_dword v167, v[158:159], off
	v_add_u32_e32 v158, 0x90, v48
	v_mov_b32_e32 v159, v49
	v_lshl_add_u64 v[158:159], v[158:159], 2, s[22:23]
	global_load_dword v164, v[158:159], off
	v_add_u32_e32 v158, 0x4090, v48
	v_mov_b32_e32 v159, v49
	v_lshl_add_u64 v[158:159], v[158:159], 2, s[22:23]
	global_load_dword v168, v[158:159], off
	v_add_u32_e32 v158, 0x8090, v48
	v_mov_b32_e32 v159, v49
	v_lshl_add_u64 v[158:159], v[158:159], 2, s[22:23]
	global_load_dword v165, v[158:159], off
	v_add_u32_e32 v158, 0xc090, v48
	v_mov_b32_e32 v159, v49
	v_lshl_add_u64 v[158:159], v[158:159], 2, s[22:23]
	global_load_dword v169, v[158:159], off
	v_add_u32_e32 v158, 0xa0, v48
	v_mov_b32_e32 v159, v49
	v_lshl_add_u64 v[158:159], v[158:159], 2, s[22:23]
	global_load_dword v170, v[158:159], off
	v_add_u32_e32 v158, 0x40a0, v48
	v_mov_b32_e32 v159, v49
	v_lshl_add_u64 v[158:159], v[158:159], 2, s[22:23]
	global_load_dword v172, v[158:159], off
	v_add_u32_e32 v158, 0x80a0, v48
	v_mov_b32_e32 v159, v49
	v_lshl_add_u64 v[158:159], v[158:159], 2, s[22:23]
	global_load_dword v171, v[158:159], off
	v_add_u32_e32 v158, 0xc0a0, v48
	v_mov_b32_e32 v159, v49
	v_lshl_add_u64 v[158:159], v[158:159], 2, s[22:23]
	global_load_dword v173, v[158:159], off
	v_add_u32_e32 v158, 0xb0, v48
	v_mov_b32_e32 v159, v49
	v_lshl_add_u64 v[158:159], v[158:159], 2, s[22:23]
	global_load_dword v182, v[158:159], off
	v_add_u32_e32 v158, 0x40b0, v48
	v_mov_b32_e32 v159, v49
	v_lshl_add_u64 v[158:159], v[158:159], 2, s[22:23]
	global_load_dword v184, v[158:159], off
	v_add_u32_e32 v158, 0x80b0, v48
	v_mov_b32_e32 v159, v49
	v_lshl_add_u64 v[158:159], v[158:159], 2, s[22:23]
	v_add_u32_e32 v48, 0xc0b0, v48
	global_load_dword v183, v[158:159], off
	v_lshl_add_u64 v[158:159], v[48:49], 2, s[22:23]
	global_load_dword v185, v[158:159], off
	v_and_b32_e32 v158, 64, v205
	v_xor_b32_e32 v48, 16, v205
	v_add_u32_e32 v158, 64, v158
	v_cmp_lt_i32_e32 vcc, v48, v158
	v_pk_add_f32 v[148:149], v[148:149], v[156:157]
	s_nop 0
	v_cndmask_b32_e32 v48, v205, v48, vcc
	v_lshlrev_b32_e32 v180, 2, v48
	v_add_f32_e32 v48, v142, v143
	s_waitcnt lgkmcnt(0)
	v_mov_b32_e32 v142, v48
	s_nop 1
	v_permlane16_swap_b32_e32 v48, v142
	v_add_f32_e32 v143, v48, v142
	v_add_f32_e32 v48, v148, v149
	v_mov_b32_e32 v145, v143
	s_nop 1
	v_permlane32_swap_b32_e32 v143, v145
	s_waitcnt lgkmcnt(0)
	v_mov_b32_e32 v142, v48
	s_nop 1
	v_permlane16_swap_b32_e32 v48, v142
	v_add_f32_e32 v142, v48, v142
	v_mov_b32_e32 v144, v142
	s_nop 1
	v_permlane32_swap_b32_e32 v142, v144
	v_pk_add_f32 v[142:143], v[142:143], v[144:145]
	s_nop 0
	v_pk_fma_f32 v[158:159], v[142:143], s[36:37], v[154:155] op_sel_hi:[1,0,0]
	s_nop 0
	v_mul_f32_e32 v48, 0x4b800000, v159
	v_cmp_gt_f32_e32 vcc, s75, v159
	v_cmp_gt_f32_e64 s[42:43], s75, v158
	s_nop 0
	v_cndmask_b32_e32 v48, v159, v48, vcc
	v_rsq_f32_e32 v48, v48
	s_nop 0
	v_mul_f32_e32 v142, 0x45800000, v48
	v_cndmask_b32_e32 v48, v48, v142, vcc
	v_pk_add_f32 v[142:143], v[146:147], v[152:153]
	v_pk_mul_f32 v[126:127], v[126:127], v[48:49] op_sel_hi:[1,0]
	v_add_f32_e32 v142, v142, v143
	v_pk_mul_f32 v[122:123], v[122:123], v[48:49] op_sel_hi:[1,0]
	v_pk_mul_f32 v[128:129], v[128:129], v[48:49] op_sel_hi:[1,0]
	v_pk_mul_f32 v[124:125], v[124:125], v[48:49] op_sel_hi:[1,0]
	v_pk_mul_f32 v[120:121], v[120:121], v[48:49] op_sel_hi:[1,0]
	s_waitcnt lgkmcnt(0)
	v_mov_b32_e32 v143, v142
	s_nop 1
	v_permlane16_swap_b32_e32 v142, v143
	v_add_f32_e32 v153, v142, v143
	s_waitcnt vmcnt(16)
	v_pk_add_f32 v[142:143], v[150:151], v[160:161]
	v_pk_mul_f32 v[118:119], v[118:119], v[48:49] op_sel_hi:[1,0]
	v_add_f32_e32 v142, v142, v143
	v_pk_mul_f32 v[116:117], v[116:117], v[48:49] op_sel_hi:[1,0]
	v_pk_mul_f32 v[114:115], v[114:115], v[48:49] op_sel_hi:[1,0]
	v_mul_f32_e32 v48, v127, v127
	v_cvt_pk_bf16_f32 v160, v126, v127
	s_waitcnt lgkmcnt(0)
	v_mov_b32_e32 v143, v142
	s_nop 1
	v_permlane16_swap_b32_e32 v142, v143
	v_add_f32_e32 v152, v142, v143
	s_waitcnt vmcnt(12)
	v_pk_add_f32 v[142:143], v[162:163], v[166:167]
	v_cvt_pk_bf16_f32 v162, v122, v123
	v_add_f32_e32 v142, v142, v143
	v_mul_f32_e32 v123, v123, v123
	v_cvt_pk_bf16_f32 v161, v128, v129
	v_cvt_pk_bf16_f32 v163, v124, v125
	v_fmac_f32_e32 v48, v126, v126
	s_waitcnt lgkmcnt(0)
	v_mov_b32_e32 v143, v142
	s_nop 1
	v_permlane16_swap_b32_e32 v142, v143
	v_add_f32_e32 v149, v142, v143
	s_waitcnt vmcnt(8)
	v_pk_add_f32 v[142:143], v[164:165], v[168:169]
	v_mul_f32_e32 v126, v129, v129
	v_add_f32_e32 v142, v142, v143
	v_fmac_f32_e32 v123, v122, v122
	v_mul_f32_e32 v122, v125, v125
	v_fmac_f32_e32 v126, v128, v128
	v_fmac_f32_e32 v122, v124, v124
	s_waitcnt lgkmcnt(0)
	v_mov_b32_e32 v143, v142
	s_nop 1
	v_permlane16_swap_b32_e32 v142, v143
	v_add_f32_e32 v148, v142, v143
	s_waitcnt vmcnt(4)
	v_pk_add_f32 v[142:143], v[170:171], v[172:173]
	v_mov_b32_e32 v157, v153
	v_add_f32_e32 v142, v142, v143
	v_mov_b32_e32 v156, v152
	v_mov_b32_e32 v151, v149
	v_mov_b32_e32 v150, v148
	v_add_f32_e32 v48, v48, v126
	s_waitcnt lgkmcnt(0)
	v_mov_b32_e32 v143, v142
	s_nop 1
	v_permlane16_swap_b32_e32 v142, v143
	v_add_f32_e32 v145, v142, v143
	s_waitcnt vmcnt(0)
	v_pk_add_f32 v[142:143], v[182:183], v[184:185]
	v_mov_b32_e32 v147, v145
	v_add_f32_e32 v142, v142, v143
	v_add_f32_e32 v122, v123, v122
	v_permlane32_swap_b32_e32 v153, v157
	v_permlane32_swap_b32_e32 v152, v156
	s_waitcnt lgkmcnt(0)
	v_mov_b32_e32 v143, v142
	s_nop 1
	v_permlane16_swap_b32_e32 v142, v143
	v_add_f32_e32 v144, v142, v143
	v_lshl_or_b32 v142, s44, 8, v177
	v_mad_u64_u32 v[142:143], s[20:21], v179, s6, v[142:143]
	v_mov_b32_e32 v143, v49
	v_lshl_add_u64 v[164:165], v[142:143], 1, s[12:13]
	global_store_dwordx4 v[164:165], v[160:163], off
	s_nop 1
	v_cvt_pk_bf16_f32 v160, v118, v119
	v_cvt_pk_bf16_f32 v161, v120, v121
	v_cvt_pk_bf16_f32 v162, v114, v115
	v_cvt_pk_bf16_f32 v163, v116, v117
	v_lshl_add_u64 v[164:165], v[164:165], 0, s[34:35]
	global_store_dwordx4 v[164:165], v[160:163], off
	s_nop 1
	v_mov_b32_e32 v146, v144
	v_permlane32_swap_b32_e32 v149, v151
	v_permlane32_swap_b32_e32 v148, v150
	v_permlane32_swap_b32_e32 v145, v147
	v_permlane32_swap_b32_e32 v144, v146
	v_add_f32_e32 v48, v48, v122
	s_cbranch_scc1 .LBB0_591
	s_mov_b64 s[62:63], 0
	s_cmp_eq_u32 s44, 1
	s_mov_b64 s[60:61], 0
	s_cbranch_scc0 .LBB0_592
	ds_bpermute_b32 v122, v180, v48
	s_and_b64 s[60:61], s[40:41], exec
	s_waitcnt lgkmcnt(0)
	v_add_f32_e32 v122, v48, v122
	v_mov_b32_e32 v123, v122
	s_nop 1
	v_permlane32_swap_b32_e32 v122, v123
	s_branch .LBB0_592

.LBB0_693:
	v_lshl_add_u32 v181, s40, 8, v176
	v_add_u32_e32 v48, v181, v178
	v_add_u32_e32 v144, 0x40a0, v48
	v_mov_b32_e32 v145, v49
	v_lshl_add_u64 v[142:143], v[48:49], 2, s[22:23]
	v_lshl_add_u64 v[144:145], v[144:145], 2, s[22:23]
	global_load_dword v172, v[142:143], off
	global_load_dword v148, v[144:145], off
	v_add_u32_e32 v142, 0x4000, v48
	v_mov_b32_e32 v143, v49
	v_add_u32_e32 v150, 0x40b0, v48
	v_mov_b32_e32 v151, v49
	v_lshl_add_u64 v[142:143], v[142:143], 2, s[22:23]
	v_lshl_add_u64 v[150:151], v[150:151], 2, s[22:23]
	global_load_dword v174, v[142:143], off
	v_add_u32_e32 v144, 0x80a0, v48
	global_load_dword v150, v[150:151], off
	v_add_u32_e32 v142, 0x8000, v48
	v_mov_b32_e32 v143, v49
	v_lshl_add_u64 v[142:143], v[142:143], 2, s[22:23]
	global_load_dword v173, v[142:143], off
	v_add_u32_e32 v142, 0xc000, v48
	v_mov_b32_e32 v143, v49
	v_lshl_add_u64 v[142:143], v[142:143], 2, s[22:23]
	global_load_dword v175, v[142:143], off
	v_or_b32_e32 v142, 16, v48
	v_mov_b32_e32 v143, v49
	v_lshl_add_u64 v[142:143], v[142:143], 2, s[22:23]
	global_load_dword v146, v[142:143], off
	v_add_u32_e32 v142, 0x4010, v48
	v_mov_b32_e32 v143, v49
	v_lshl_add_u64 v[142:143], v[142:143], 2, s[22:23]
	global_load_dword v170, v[142:143], off
	v_add_u32_e32 v142, 0x8010, v48
	v_mov_b32_e32 v143, v49
	v_lshl_add_u64 v[142:143], v[142:143], 2, s[22:23]
	global_load_dword v147, v[142:143], off
	v_add_u32_e32 v142, 0xc010, v48
	v_mov_b32_e32 v143, v49
	v_lshl_add_u64 v[142:143], v[142:143], 2, s[22:23]
	global_load_dword v171, v[142:143], off
	v_or_b32_e32 v142, 32, v48
	v_mov_b32_e32 v143, v49
	v_lshl_add_u64 v[142:143], v[142:143], 2, s[22:23]
	global_load_dword v160, v[142:143], off
	v_add_u32_e32 v142, 0x4020, v48
	v_mov_b32_e32 v143, v49
	v_lshl_add_u64 v[142:143], v[142:143], 2, s[22:23]
	global_load_dword v166, v[142:143], off
	v_add_u32_e32 v142, 0x8020, v48
	v_mov_b32_e32 v143, v49
	v_lshl_add_u64 v[142:143], v[142:143], 2, s[22:23]
	global_load_dword v161, v[142:143], off
	v_add_u32_e32 v142, 0xc020, v48
	v_mov_b32_e32 v143, v49
	v_lshl_add_u64 v[142:143], v[142:143], 2, s[22:23]
	global_load_dword v167, v[142:143], off
	v_or_b32_e32 v142, 48, v48
	v_mov_b32_e32 v143, v49
	v_lshl_add_u64 v[142:143], v[142:143], 2, s[22:23]
	global_load_dword v164, v[142:143], off
	v_add_u32_e32 v142, 0x4030, v48
	v_mov_b32_e32 v143, v49
	v_lshl_add_u64 v[142:143], v[142:143], 2, s[22:23]
	global_load_dword v168, v[142:143], off
	v_add_u32_e32 v142, 0x8030, v48
	v_mov_b32_e32 v143, v49
	v_lshl_add_u64 v[142:143], v[142:143], 2, s[22:23]
	global_load_dword v165, v[142:143], off
	v_add_u32_e32 v142, 0xc030, v48
	v_mov_b32_e32 v143, v49
	v_lshl_add_u64 v[142:143], v[142:143], 2, s[22:23]
	global_load_dword v169, v[142:143], off
	v_add_u32_e32 v142, 0x80, v48
	v_mov_b32_e32 v143, v49
	v_lshl_add_u64 v[142:143], v[142:143], 2, s[22:23]
	global_load_dword v152, v[142:143], off
	v_add_u32_e32 v142, 0x4080, v48
	v_mov_b32_e32 v143, v49
	v_lshl_add_u64 v[142:143], v[142:143], 2, s[22:23]
	global_load_dword v158, v[142:143], off
	v_add_u32_e32 v142, 0x8080, v48
	v_mov_b32_e32 v143, v49
	v_lshl_add_u64 v[142:143], v[142:143], 2, s[22:23]
	global_load_dword v153, v[142:143], off
	v_add_u32_e32 v142, 0xc080, v48
	v_mov_b32_e32 v143, v49
	v_lshl_add_u64 v[142:143], v[142:143], 2, s[22:23]
	global_load_dword v159, v[142:143], off
	v_add_u32_e32 v142, 0x90, v48
	v_mov_b32_e32 v143, v49
	v_lshl_add_u64 v[142:143], v[142:143], 2, s[22:23]
	global_load_dword v156, v[142:143], off
	v_add_u32_e32 v142, 0x4090, v48
	v_mov_b32_e32 v143, v49
	v_lshl_add_u64 v[142:143], v[142:143], 2, s[22:23]
	global_load_dword v162, v[142:143], off
	v_add_u32_e32 v142, 0x8090, v48
	v_mov_b32_e32 v143, v49
	v_lshl_add_u64 v[142:143], v[142:143], 2, s[22:23]
	global_load_dword v157, v[142:143], off
	v_add_u32_e32 v142, 0xc090, v48
	v_mov_b32_e32 v143, v49
	v_lshl_add_u64 v[142:143], v[142:143], 2, s[22:23]
	global_load_dword v163, v[142:143], off
	v_add_u32_e32 v142, 0xa0, v48
	v_mov_b32_e32 v143, v49
	v_mov_b32_e32 v145, v49
	v_lshl_add_u64 v[142:143], v[142:143], 2, s[22:23]
	v_lshl_add_u64 v[144:145], v[144:145], 2, s[22:23]
	global_load_dword v142, v[142:143], off
	v_add_u32_e32 v182, 0x80b0, v48
	global_load_dword v143, v[144:145], off
	v_add_u32_e32 v144, 0xc0a0, v48
	v_mov_b32_e32 v145, v49
	v_lshl_add_u64 v[144:145], v[144:145], 2, s[22:23]
	global_load_dword v149, v[144:145], off
	v_add_u32_e32 v144, 0xb0, v48
	v_mov_b32_e32 v145, v49
	v_mov_b32_e32 v183, v49
	v_lshl_add_u64 v[144:145], v[144:145], 2, s[22:23]
	v_lshl_add_u64 v[182:183], v[182:183], 2, s[22:23]
	v_add_u32_e32 v48, 0xc0b0, v48
	global_load_dword v144, v[144:145], off
	s_waitcnt vmcnt(0)
	v_pk_add_f32 v[172:173], v[172:173], v[174:175]
	global_load_dword v145, v[182:183], off
	v_lshl_add_u64 v[182:183], v[48:49], 2, s[22:23]
	global_load_dword v151, v[182:183], off
	v_and_b32_e32 v182, 64, v205
	v_xor_b32_e32 v48, 16, v205
	v_add_u32_e32 v182, 64, v182
	v_cmp_lt_i32_e32 vcc, v48, v182
	v_pk_add_f32 v[146:147], v[146:147], v[170:171]
	s_mov_b32 s6, 0x358637bd
	v_cndmask_b32_e32 v48, v205, v48, vcc
	v_lshlrev_b32_e32 v182, 2, v48
	v_add_f32_e32 v48, v172, v173
	v_mov_b64_e32 v[170:171], s[6:7]
	v_pk_add_f32 v[160:161], v[160:161], v[166:167]
	s_movk_i32 s6, 0xb00
	s_waitcnt lgkmcnt(0)
	v_mov_b32_e32 v172, v48
	s_nop 1
	v_permlane16_swap_b32_e32 v48, v172
	v_add_f32_e32 v173, v48, v172
	v_add_f32_e32 v48, v146, v147
	v_mov_b32_e32 v175, v173
	s_nop 1
	v_permlane32_swap_b32_e32 v173, v175
	s_waitcnt lgkmcnt(0)
	v_mov_b32_e32 v146, v48
	s_nop 1
	v_permlane16_swap_b32_e32 v48, v146
	v_add_f32_e32 v172, v48, v146
	v_mov_b32_e32 v174, v172
	s_nop 1
	v_permlane32_swap_b32_e32 v172, v174
	v_pk_add_f32 v[146:147], v[172:173], v[174:175]
	v_pk_add_f32 v[164:165], v[164:165], v[168:169]
	v_pk_fma_f32 v[146:147], v[146:147], s[36:37], v[170:171] op_sel_hi:[1,0,0]
	v_pk_add_f32 v[152:153], v[152:153], v[158:159]
	v_mul_f32_e32 v48, 0x4b800000, v147
	v_cmp_gt_f32_e64 s[40:41], s75, v147
	v_cmp_gt_f32_e32 vcc, s75, v146
	v_pk_add_f32 v[156:157], v[156:157], v[162:163]
	v_cndmask_b32_e64 v48, v147, v48, s[40:41]
	v_rsq_f32_e32 v48, v48
	v_pk_add_f32 v[142:143], v[142:143], v[148:149]
	v_mul_f32_e32 v147, 0x45800000, v48
	v_cndmask_b32_e64 v48, v48, v147, s[40:41]
	v_mul_f32_e32 v147, 0x4b800000, v146
	v_cndmask_b32_e32 v146, v146, v147, vcc
	v_rsq_f32_e32 v146, v146
	v_add_f32_e32 v142, v142, v143
	ds_bpermute_b32 v143, v182, v142
	v_pk_mul_f32 v[128:129], v[128:129], v[48:49] op_sel_hi:[1,0]
	v_mul_f32_e32 v147, 0x45800000, v146
	v_cndmask_b32_e32 v146, v146, v147, vcc
	v_add_f32_e32 v147, v160, v161
	ds_bpermute_b32 v160, v182, v147
	s_waitcnt vmcnt(0)
	v_pk_add_f32 v[144:145], v[144:145], v[150:151]
	s_waitcnt lgkmcnt(1)
	v_add_f32_e32 v143, v142, v143
	v_add_f32_e32 v142, v144, v145
	ds_bpermute_b32 v144, v182, v142
	s_waitcnt lgkmcnt(1)
	v_add_f32_e32 v161, v147, v160
	v_add_f32_e32 v147, v164, v165
	ds_bpermute_b32 v160, v182, v147
	v_mov_b32_e32 v167, v161
	s_nop 1
	v_permlane32_swap_b32_e32 v161, v167
	s_waitcnt lgkmcnt(1)
	v_add_f32_e32 v142, v142, v144
	s_waitcnt lgkmcnt(0)
	v_add_f32_e32 v160, v147, v160
	v_mov_b32_e32 v166, v160
	s_nop 1
	v_permlane32_swap_b32_e32 v160, v166
	v_pk_add_f32 v[160:161], v[160:161], v[166:167]
	v_mov_b32_e32 v149, v143
	v_pk_fma_f32 v[160:161], v[160:161], s[36:37], v[170:171] op_sel_hi:[1,0,0]
	v_mov_b32_e32 v148, v142
	v_mul_f32_e32 v147, 0x4b800000, v161
	v_cmp_gt_f32_e64 s[40:41], s75, v161
	v_cmp_gt_f32_e32 vcc, s75, v160
	v_permlane32_swap_b32_e32 v143, v149
	v_cndmask_b32_e64 v147, v161, v147, s[40:41]
	v_rsq_f32_e32 v147, v147
	v_permlane32_swap_b32_e32 v142, v148
	v_pk_add_f32 v[142:143], v[142:143], v[148:149]
	v_mul_f32_e32 v161, 0x45800000, v147
	v_cndmask_b32_e64 v164, v147, v161, s[40:41]
	v_mul_f32_e32 v147, 0x4b800000, v160
	v_cndmask_b32_e32 v147, v160, v147, vcc
	v_rsq_f32_e32 v147, v147
	v_pk_fma_f32 v[142:143], v[142:143], s[36:37], v[170:171] op_sel_hi:[1,0,0]
	v_pk_mul_f32 v[126:127], v[126:127], v[48:49] op_sel_hi:[1,0]
	v_mul_f32_e32 v144, 0x4b800000, v143
	v_mul_f32_e32 v160, 0x45800000, v147
	v_cndmask_b32_e32 v160, v147, v160, vcc
	v_add_f32_e32 v147, v152, v153
	v_pk_mul_f32 v[150:151], v[124:125], v[48:49] op_sel_hi:[1,0]
	v_pk_mul_f32 v[124:125], v[122:123], v[48:49] op_sel_hi:[1,0]
	v_cvt_pk_bf16_f32 v122, v126, v127
	v_cvt_pk_bf16_f32 v123, v128, v129
	s_waitcnt lgkmcnt(0)
	v_mov_b32_e32 v152, v147
	s_nop 1
	v_permlane16_swap_b32_e32 v147, v152
	v_add_f32_e32 v153, v147, v152
	v_add_f32_e32 v147, v156, v157
	v_mov_b32_e32 v159, v153
	s_nop 1
	v_permlane32_swap_b32_e32 v153, v159
	v_cvt_pk_bf16_f32 v124, v124, v125
	s_waitcnt lgkmcnt(0)
	v_mov_b32_e32 v152, v147
	s_nop 1
	v_permlane16_swap_b32_e32 v147, v152
	v_add_f32_e32 v152, v147, v152
	v_mov_b32_e32 v158, v152
	s_nop 1
	v_permlane32_swap_b32_e32 v152, v158
	v_pk_add_f32 v[152:153], v[152:153], v[158:159]
	v_cvt_pk_bf16_f32 v125, v150, v151
	v_pk_fma_f32 v[152:153], v[152:153], s[36:37], v[170:171] op_sel_hi:[1,0,0]
	v_pk_mul_f32 v[116:117], v[116:117], v[48:49] op_sel_hi:[1,0]
	v_mul_f32_e32 v147, 0x4b800000, v153
	v_cmp_gt_f32_e64 s[40:41], s75, v153
	v_cmp_gt_f32_e32 vcc, s75, v152
	v_pk_mul_f32 v[114:115], v[114:115], v[48:49] op_sel_hi:[1,0]
	v_cndmask_b32_e64 v147, v153, v147, s[40:41]
	v_rsq_f32_e32 v147, v147
	v_pk_mul_f32 v[96:97], v[96:97], v[164:165] op_sel_hi:[1,0]
	v_pk_mul_f32 v[94:95], v[94:95], v[164:165] op_sel_hi:[1,0]
	v_pk_mul_f32 v[84:85], v[84:85], v[164:165] op_sel_hi:[1,0]
	v_mul_f32_e32 v153, 0x45800000, v147
	v_cndmask_b32_e64 v156, v147, v153, s[40:41]
	v_mul_f32_e32 v147, 0x4b800000, v152
	v_cmp_gt_f32_e64 s[40:41], s75, v143
	v_cndmask_b32_e32 v147, v152, v147, vcc
	v_rsq_f32_e32 v147, v147
	v_cndmask_b32_e64 v143, v143, v144, s[40:41]
	v_rsq_f32_e32 v143, v143
	v_pk_mul_f32 v[82:83], v[82:83], v[164:165] op_sel_hi:[1,0]
	v_mul_f32_e32 v152, 0x45800000, v147
	v_cndmask_b32_e32 v152, v147, v152, vcc
	v_mul_f32_e32 v144, 0x45800000, v143
	v_cmp_gt_f32_e32 vcc, s75, v142
	v_cndmask_b32_e64 v148, v143, v144, s[40:41]
	v_mul_f32_e32 v143, 0x4b800000, v142
	v_cndmask_b32_e32 v142, v142, v143, vcc
	v_rsq_f32_e32 v142, v142
	v_pk_mul_f32 v[112:113], v[112:113], v[146:147] op_sel_hi:[1,0]
	v_pk_mul_f32 v[110:111], v[110:111], v[146:147] op_sel_hi:[1,0]
	v_pk_mul_f32 v[100:101], v[100:101], v[146:147] op_sel_hi:[1,0]
	v_mul_f32_e32 v143, 0x45800000, v142
	v_cndmask_b32_e32 v144, v142, v143, vcc
	v_lshl_or_b32 v142, s67, 8, v179
	v_mad_u64_u32 v[142:143], s[20:21], v181, s6, v[142:143]
	v_mov_b32_e32 v143, v49
	v_lshl_add_u64 v[126:127], v[142:143], 1, s[12:13]
	global_store_dwordx4 v[126:127], v[122:125], off
	s_nop 1
	v_pk_mul_f32 v[122:123], v[108:109], v[48:49] op_sel_hi:[1,0]
	v_pk_mul_f32 v[108:109], v[106:107], v[48:49] op_sel_hi:[1,0]
	v_cvt_pk_bf16_f32 v106, v114, v115
	v_cvt_pk_bf16_f32 v107, v116, v117
	v_cvt_pk_bf16_f32 v108, v108, v109
	v_cvt_pk_bf16_f32 v109, v122, v123
	v_lshl_add_u64 v[114:115], v[126:127], 0, s[34:35]
	global_store_dwordx4 v[114:115], v[106:109], off
	s_nop 1
	v_pk_mul_f32 v[108:109], v[120:121], v[146:147] op_sel_hi:[1,0]
	v_pk_mul_f32 v[106:107], v[118:119], v[146:147] op_sel_hi:[1,0]
	v_add_u32_e32 v48, 0xb000, v142
	v_cvt_pk_bf16_f32 v106, v106, v107
	v_cvt_pk_bf16_f32 v107, v108, v109
	v_cvt_pk_bf16_f32 v108, v110, v111
	v_cvt_pk_bf16_f32 v109, v112, v113
	v_lshl_add_u64 v[110:111], v[48:49], 1, s[12:13]
	global_store_dwordx4 v[110:111], v[106:109], off
	s_nop 1
	v_pk_mul_f32 v[98:99], v[98:99], v[146:147] op_sel_hi:[1,0]
	v_pk_mul_f32 v[106:107], v[92:93], v[146:147] op_sel_hi:[1,0]
	v_pk_mul_f32 v[92:93], v[90:91], v[146:147] op_sel_hi:[1,0]
	v_cvt_pk_bf16_f32 v90, v98, v99
	v_cvt_pk_bf16_f32 v91, v100, v101
	v_cvt_pk_bf16_f32 v92, v92, v93
	v_cvt_pk_bf16_f32 v93, v106, v107
	v_add_u32_e32 v48, 0xb080, v142
	v_lshl_add_u64 v[98:99], v[48:49], 1, s[12:13]
	global_store_dwordx4 v[98:99], v[90:93], off
	s_nop 1
	v_pk_mul_f32 v[92:93], v[104:105], v[164:165] op_sel_hi:[1,0]
	v_pk_mul_f32 v[90:91], v[102:103], v[164:165] op_sel_hi:[1,0]
	v_add_u32_e32 v48, 0x16000, v142
	v_cvt_pk_bf16_f32 v90, v90, v91
	v_cvt_pk_bf16_f32 v91, v92, v93
	v_cvt_pk_bf16_f32 v92, v94, v95
	v_cvt_pk_bf16_f32 v93, v96, v97
	v_lshl_add_u64 v[94:95], v[48:49], 1, s[12:13]
	global_store_dwordx4 v[94:95], v[90:93], off
	s_nop 1
	v_pk_mul_f32 v[90:91], v[76:77], v[164:165] op_sel_hi:[1,0]
	v_pk_mul_f32 v[76:77], v[74:75], v[164:165] op_sel_hi:[1,0]
	v_cvt_pk_bf16_f32 v74, v82, v83
	v_cvt_pk_bf16_f32 v75, v84, v85
	v_cvt_pk_bf16_f32 v76, v76, v77
	v_cvt_pk_bf16_f32 v77, v90, v91
	v_add_u32_e32 v48, 0x16080, v142
	v_lshl_add_u64 v[82:83], v[48:49], 1, s[12:13]
	global_store_dwordx4 v[82:83], v[74:77], off
	s_nop 1
	v_pk_mul_f32 v[76:77], v[88:89], v[160:161] op_sel_hi:[1,0]
	v_pk_mul_f32 v[74:75], v[86:87], v[160:161] op_sel_hi:[1,0]
	v_pk_mul_f32 v[80:81], v[80:81], v[160:161] op_sel_hi:[1,0]
	v_pk_mul_f32 v[78:79], v[78:79], v[160:161] op_sel_hi:[1,0]
	v_cvt_pk_bf16_f32 v74, v74, v75
	v_cvt_pk_bf16_f32 v75, v76, v77
	v_add_u32_e32 v48, 0x21000, v142
	v_pk_mul_f32 v[72:73], v[72:73], v[160:161] op_sel_hi:[1,0]
	v_pk_mul_f32 v[70:71], v[70:71], v[160:161] op_sel_hi:[1,0]
	v_cvt_pk_bf16_f32 v76, v78, v79
	v_cvt_pk_bf16_f32 v77, v80, v81
	v_lshl_add_u64 v[78:79], v[48:49], 1, s[12:13]
	global_store_dwordx4 v[78:79], v[74:77], off
	s_nop 1
	v_pk_mul_f32 v[74:75], v[68:69], v[160:161] op_sel_hi:[1,0]
	v_pk_mul_f32 v[68:69], v[66:67], v[160:161] op_sel_hi:[1,0]
	v_cvt_pk_bf16_f32 v66, v70, v71
	v_cvt_pk_bf16_f32 v67, v72, v73
	v_add_u32_e32 v48, 0x21080, v142
	v_pk_mul_f32 v[64:65], v[64:65], v[156:157] op_sel_hi:[1,0]
	v_pk_mul_f32 v[62:63], v[62:63], v[156:157] op_sel_hi:[1,0]
	v_cvt_pk_bf16_f32 v68, v68, v69
	v_cvt_pk_bf16_f32 v69, v74, v75
	v_lshl_add_u64 v[70:71], v[48:49], 1, s[12:13]
	global_store_dwordx4 v[70:71], v[66:69], off
	s_nop 1
	v_pk_mul_f32 v[66:67], v[60:61], v[156:157] op_sel_hi:[1,0]
	v_pk_mul_f32 v[60:61], v[58:59], v[156:157] op_sel_hi:[1,0]
	v_cvt_pk_bf16_f32 v58, v62, v63
	v_cvt_pk_bf16_f32 v59, v64, v65
	v_add_u32_e32 v48, 0x58000, v142
	v_cvt_pk_bf16_f32 v60, v60, v61
	v_cvt_pk_bf16_f32 v61, v66, v67
	v_lshl_add_u64 v[62:63], v[48:49], 1, s[12:13]
	global_store_dwordx4 v[62:63], v[58:61], off
	s_nop 1
	v_pk_mul_f32 v[52:53], v[52:53], v[156:157] op_sel_hi:[1,0]
	v_pk_mul_f32 v[50:51], v[50:51], v[156:157] op_sel_hi:[1,0]
	v_pk_mul_f32 v[58:59], v[42:43], v[156:157] op_sel_hi:[1,0]
	v_pk_mul_f32 v[42:43], v[40:41], v[156:157] op_sel_hi:[1,0]
	v_cvt_pk_bf16_f32 v40, v50, v51
	v_cvt_pk_bf16_f32 v41, v52, v53
	v_cvt_pk_bf16_f32 v42, v42, v43
	v_cvt_pk_bf16_f32 v43, v58, v59
	v_add_u32_e32 v48, 0x58080, v142
	v_lshl_add_u64 v[50:51], v[48:49], 1, s[12:13]
	global_store_dwordx4 v[50:51], v[40:43], off
	s_nop 1
	v_pk_mul_f32 v[42:43], v[56:57], v[152:153] op_sel_hi:[1,0]
	v_pk_mul_f32 v[40:41], v[54:55], v[152:153] op_sel_hi:[1,0]
	v_pk_mul_f32 v[46:47], v[46:47], v[152:153] op_sel_hi:[1,0]
	v_pk_mul_f32 v[44:45], v[44:45], v[152:153] op_sel_hi:[1,0]
	v_cvt_pk_bf16_f32 v40, v40, v41
	v_cvt_pk_bf16_f32 v41, v42, v43
	v_add_u32_e32 v48, 0x63000, v142
	v_cvt_pk_bf16_f32 v42, v44, v45
	v_cvt_pk_bf16_f32 v43, v46, v47
	v_lshl_add_u64 v[44:45], v[48:49], 1, s[12:13]
	global_store_dwordx4 v[44:45], v[40:43], off
	s_nop 1
	v_pk_mul_f32 v[34:35], v[34:35], v[152:153] op_sel_hi:[1,0]
	v_pk_mul_f32 v[32:33], v[32:33], v[152:153] op_sel_hi:[1,0]
	v_pk_mul_f32 v[40:41], v[26:27], v[152:153] op_sel_hi:[1,0]
	v_pk_mul_f32 v[26:27], v[24:25], v[152:153] op_sel_hi:[1,0]
	v_cvt_pk_bf16_f32 v24, v32, v33
	v_cvt_pk_bf16_f32 v25, v34, v35
	v_cvt_pk_bf16_f32 v26, v26, v27
	v_cvt_pk_bf16_f32 v27, v40, v41
	v_add_u32_e32 v48, 0x63080, v142
	v_lshl_add_u64 v[32:33], v[48:49], 1, s[12:13]
	global_store_dwordx4 v[32:33], v[24:27], off
	s_nop 1
	v_pk_mul_f32 v[26:27], v[38:39], v[148:149] op_sel_hi:[1,0]
	v_pk_mul_f32 v[24:25], v[36:37], v[148:149] op_sel_hi:[1,0]
	v_pk_mul_f32 v[30:31], v[30:31], v[148:149] op_sel_hi:[1,0]
	v_pk_mul_f32 v[28:29], v[28:29], v[148:149] op_sel_hi:[1,0]
	v_cvt_pk_bf16_f32 v24, v24, v25
	v_cvt_pk_bf16_f32 v25, v26, v27
	v_add_u32_e32 v48, 0x6e000, v142
	v_cvt_pk_bf16_f32 v26, v28, v29
	v_cvt_pk_bf16_f32 v27, v30, v31
	v_lshl_add_u64 v[28:29], v[48:49], 1, s[12:13]
	global_store_dwordx4 v[28:29], v[24:27], off
	s_nop 1
	v_pk_mul_f32 v[18:19], v[18:19], v[148:149] op_sel_hi:[1,0]
	v_pk_mul_f32 v[16:17], v[16:17], v[148:149] op_sel_hi:[1,0]
	v_pk_mul_f32 v[24:25], v[10:11], v[148:149] op_sel_hi:[1,0]
	v_pk_mul_f32 v[10:11], v[8:9], v[148:149] op_sel_hi:[1,0]
	v_cvt_pk_bf16_f32 v8, v16, v17
	v_cvt_pk_bf16_f32 v9, v18, v19
	v_cvt_pk_bf16_f32 v10, v10, v11
	v_cvt_pk_bf16_f32 v11, v24, v25
	v_add_u32_e32 v48, 0x6e080, v142
	v_lshl_add_u64 v[16:17], v[48:49], 1, s[12:13]
	global_store_dwordx4 v[16:17], v[8:11], off
	s_nop 1
	v_pk_mul_f32 v[10:11], v[22:23], v[144:145] op_sel_hi:[1,0]
	v_pk_mul_f32 v[8:9], v[20:21], v[144:145] op_sel_hi:[1,0]
	v_pk_mul_f32 v[14:15], v[14:15], v[144:145] op_sel_hi:[1,0]
	v_pk_mul_f32 v[12:13], v[12:13], v[144:145] op_sel_hi:[1,0]
	v_cvt_pk_bf16_f32 v8, v8, v9
	v_cvt_pk_bf16_f32 v9, v10, v11
	v_add_u32_e32 v48, 0x79000, v142
	v_cvt_pk_bf16_f32 v10, v12, v13
	v_cvt_pk_bf16_f32 v11, v14, v15
	v_lshl_add_u64 v[12:13], v[48:49], 1, s[12:13]
	global_store_dwordx4 v[12:13], v[8:11], off
	s_nop 1
	v_pk_mul_f32 v[6:7], v[6:7], v[144:145] op_sel_hi:[1,0]
	v_pk_mul_f32 v[4:5], v[4:5], v[144:145] op_sel_hi:[1,0]
	v_pk_mul_f32 v[8:9], v[2:3], v[144:145] op_sel_hi:[1,0]
	v_pk_mul_f32 v[2:3], v[0:1], v[144:145] op_sel_hi:[1,0]
	v_add_u32_e32 v48, 0x79080, v142
	v_cvt_pk_bf16_f32 v0, v4, v5
	v_cvt_pk_bf16_f32 v1, v6, v7
	v_cvt_pk_bf16_f32 v2, v2, v3
	v_cvt_pk_bf16_f32 v3, v8, v9
	v_lshl_add_u64 v[4:5], v[48:49], 1, s[12:13]
	global_store_dwordx4 v[4:5], v[0:3], off
	s_nop 1
	s_mov_b64 s[40:41], -1
	s_andn2_b64 vcc, exec, s[50:51]
	s_cbranch_vccnz .LBB0_686
	s_andn2_b64 vcc, exec, s[42:43]
	s_cbranch_vccnz .LBB0_685
	s_barrier
	s_branch .LBB0_685

.LBB0_792:
	v_and_b32_e32 v165, 64, v205
	v_xor_b32_e32 v164, 16, v205
	v_add_u32_e32 v165, 64, v165
	v_lshl_add_u32 v177, v156, 8, v168
	v_cmp_lt_i32_e64 s[42:43], v164, v165
	v_add_u32_e32 v48, v177, v171
	v_cmp_lt_i32_e32 vcc, 2, v166
	v_cndmask_b32_e64 v164, v205, v164, s[42:43]
	v_or_b32_e32 v162, 16, v48
	v_mov_b32_e32 v163, v49
	v_or_b32_e32 v160, 32, v48
	v_mov_b32_e32 v161, v49
	v_or_b32_e32 v158, 48, v48
	v_mov_b32_e32 v159, v49
	v_add_u32_e32 v156, 0x80, v48
	v_mov_b32_e32 v157, v49
	v_add_u32_e32 v152, 0x90, v48
	v_mov_b32_e32 v153, v49
	v_add_u32_e32 v150, 0xa0, v48
	v_mov_b32_e32 v151, v49
	v_add_u32_e32 v148, 0xb0, v48
	v_mov_b32_e32 v149, v49
	v_lshlrev_b32_e32 v167, 2, v164
	s_and_saveexec_b64 s[6:7], vcc
	s_xor_b64 s[44:45], exec, s[6:7]
	s_cbranch_execz .LBB0_797
	v_lshl_add_u64 v[164:165], v[48:49], 2, s[62:63]
	global_load_dword v48, v[164:165], off
	v_lshl_add_u64 v[162:163], v[162:163], 2, s[62:63]
	global_load_dword v162, v[162:163], off
	v_lshl_add_u64 v[160:161], v[160:161], 2, s[62:63]
	global_load_dword v160, v[160:161], off
	v_lshl_add_u64 v[158:159], v[158:159], 2, s[62:63]
	global_load_dword v158, v[158:159], off
	v_lshl_add_u64 v[156:157], v[156:157], 2, s[62:63]
	global_load_dword v157, v[156:157], off
	v_lshl_add_u64 v[152:153], v[152:153], 2, s[62:63]
	global_load_dword v159, v[152:153], off
	v_lshl_add_u64 v[150:151], v[150:151], 2, s[62:63]
	v_lshl_add_u64 v[148:149], v[148:149], 2, s[62:63]
	global_load_dword v164, v[150:151], off
	global_load_dword v178, v[148:149], off
	s_mov_b32 s6, 0x358637bd
	s_waitcnt vmcnt(0)
	s_waitcnt lgkmcnt(0)
	v_mov_b32_e32 v148, v48
	s_nop 1
	v_permlane16_swap_b32_e32 v48, v148
	v_add_f32_e32 v149, v48, v148
	v_mov_b32_e32 v151, v149
	s_nop 1
	v_permlane32_swap_b32_e32 v149, v151
	s_waitcnt lgkmcnt(0)
	v_mov_b32_e32 v48, v162
	s_nop 1
	v_permlane16_swap_b32_e32 v162, v48
	v_add_f32_e32 v148, v162, v48
	v_mov_b32_e32 v150, v148
	s_nop 1
	v_permlane32_swap_b32_e32 v148, v150
	v_pk_add_f32 v[148:149], v[148:149], v[150:151]
	v_mov_b64_e32 v[162:163], s[6:7]
	s_brev_b32 s6, 60
	v_pk_fma_f32 v[148:149], v[148:149], s[6:7], v[162:163] op_sel_hi:[1,0,0]
	s_nop 0
	v_mul_f32_e32 v48, 0x4b800000, v149
	v_cmp_gt_f32_e64 s[42:43], s75, v149
	v_cmp_gt_f32_e32 vcc, s75, v148
	s_nop 0
	v_cndmask_b32_e64 v48, v149, v48, s[42:43]
	v_rsq_f32_e32 v48, v48
	s_nop 0
	v_mul_f32_e32 v149, 0x45800000, v48
	v_cndmask_b32_e64 v156, v48, v149, s[42:43]
	v_mul_f32_e32 v48, 0x4b800000, v148
	v_cndmask_b32_e32 v48, v148, v48, vcc
	v_rsq_f32_e32 v48, v48
	v_pk_mul_f32 v[180:181], v[122:123], v[156:157] op_sel_hi:[1,0]
	v_pk_mul_f32 v[182:183], v[60:61], v[156:157] op_sel_hi:[1,0]
	v_cvt_pk_bf16_f32 v180, v180, v181
	v_mul_f32_e32 v148, 0x45800000, v48
	v_cndmask_b32_e32 v148, v48, v148, vcc
	s_waitcnt lgkmcnt(0)
	v_mov_b32_e32 v48, v160
	s_nop 1
	v_permlane16_swap_b32_e32 v160, v48
	v_add_f32_e32 v151, v160, v48
	v_mov_b32_e32 v153, v151
	s_nop 1
	v_permlane32_swap_b32_e32 v151, v153
	s_waitcnt lgkmcnt(0)
	v_mov_b32_e32 v48, v158
	s_nop 1
	v_permlane16_swap_b32_e32 v158, v48
	v_add_f32_e32 v150, v158, v48
	v_mov_b32_e32 v152, v150
	s_nop 1
	v_permlane32_swap_b32_e32 v150, v152
	v_pk_add_f32 v[150:151], v[150:151], v[152:153]
	s_nop 0
	v_pk_fma_f32 v[150:151], v[150:151], s[6:7], v[162:163] op_sel_hi:[1,0,0]
	s_nop 0
	v_mul_f32_e32 v48, 0x4b800000, v151
	v_cmp_gt_f32_e64 s[42:43], s75, v151
	v_cmp_gt_f32_e32 vcc, s75, v150
	s_nop 0
	v_cndmask_b32_e64 v48, v151, v48, s[42:43]
	v_rsq_f32_e32 v48, v48
	s_nop 0
	v_mul_f32_e32 v149, 0x45800000, v48
	v_cndmask_b32_e64 v158, v48, v149, s[42:43]
	v_mul_f32_e32 v48, 0x4b800000, v150
	v_cndmask_b32_e32 v48, v150, v48, vcc
	v_rsq_f32_e32 v48, v48
	s_nop 0
	v_mul_f32_e32 v149, 0x45800000, v48
	v_cndmask_b32_e32 v150, v48, v149, vcc
	ds_bpermute_b32 v48, v167, v157
	s_waitcnt lgkmcnt(0)
	v_add_f32_e32 v153, v157, v48
	ds_bpermute_b32 v48, v167, v159
	v_mov_b32_e32 v161, v153
	s_nop 1
	v_permlane32_swap_b32_e32 v153, v161
	s_waitcnt lgkmcnt(0)
	v_add_f32_e32 v152, v159, v48
	v_mov_b32_e32 v160, v152
	s_nop 1
	v_permlane32_swap_b32_e32 v152, v160
	v_pk_add_f32 v[152:153], v[152:153], v[160:161]
	s_nop 0
	v_pk_fma_f32 v[152:153], v[152:153], s[6:7], v[162:163] op_sel_hi:[1,0,0]
	s_nop 0
	v_mul_f32_e32 v48, 0x4b800000, v153
	v_cmp_gt_f32_e64 s[42:43], s75, v153
	v_cmp_gt_f32_e32 vcc, s75, v152
	s_nop 0
	v_cndmask_b32_e64 v48, v153, v48, s[42:43]
	v_rsq_f32_e32 v48, v48
	s_nop 0
	v_mul_f32_e32 v149, 0x45800000, v48
	v_cndmask_b32_e64 v160, v48, v149, s[42:43]
	v_mul_f32_e32 v48, 0x4b800000, v152
	v_cndmask_b32_e32 v48, v152, v48, vcc
	v_rsq_f32_e32 v48, v48
	s_nop 0
	v_mul_f32_e32 v149, 0x45800000, v48
	v_cndmask_b32_e32 v152, v48, v149, vcc
	s_waitcnt lgkmcnt(0)
	v_mov_b32_e32 v48, v164
	s_nop 1
	v_permlane16_swap_b32_e32 v164, v48
	v_add_f32_e32 v165, v164, v48
	v_mov_b32_e32 v179, v165
	s_nop 1
	v_permlane32_swap_b32_e32 v165, v179
	s_waitcnt lgkmcnt(0)
	v_mov_b32_e32 v48, v178
	s_nop 1
	v_permlane16_swap_b32_e32 v178, v48
	v_add_f32_e32 v164, v178, v48
	v_mov_b32_e32 v178, v164
	s_nop 1
	v_permlane32_swap_b32_e32 v164, v178
	v_pk_add_f32 v[164:165], v[164:165], v[178:179]
	v_pk_mul_f32 v[178:179], v[126:127], v[156:157] op_sel_hi:[1,0]
	v_pk_fma_f32 v[162:163], v[164:165], s[6:7], v[162:163] op_sel_hi:[1,0,0]
	v_cvt_pk_bf16_f32 v178, v178, v179
	v_mul_f32_e32 v48, 0x4b800000, v163
	v_cmp_gt_f32_e64 s[42:43], s75, v163
	v_cmp_gt_f32_e32 vcc, s75, v162
	s_nop 0
	v_cndmask_b32_e64 v48, v163, v48, s[42:43]
	v_rsq_f32_e32 v48, v48
	s_nop 0
	v_mul_f32_e32 v149, 0x45800000, v48
	v_cndmask_b32_e64 v164, v48, v149, s[42:43]
	v_mul_f32_e32 v48, 0x4b800000, v162
	v_cndmask_b32_e32 v48, v162, v48, vcc
	v_rsq_f32_e32 v48, v48
	s_nop 0
	v_mul_f32_e32 v149, 0x45800000, v48
	v_cndmask_b32_e32 v162, v48, v149, vcc
	v_lshlrev_b32_e32 v149, 8, v166
	v_pk_mul_f32 v[166:167], v[128:129], v[156:157] op_sel_hi:[1,0]
	v_lshlrev_b32_e32 v48, 10, v177
	v_cvt_pk_bf16_f32 v179, v166, v167
	v_pk_mul_f32 v[166:167], v[124:125], v[156:157] op_sel_hi:[1,0]
	v_add3_u32 v48, v173, v149, v48
	v_cvt_pk_bf16_f32 v181, v166, v167
	v_lshl_add_u64 v[166:167], v[48:49], 1, s[58:59]
	global_store_dwordx4 v[166:167], v[178:181], off
	s_nop 1
	v_pk_mul_f32 v[180:181], v[64:65], v[156:157] op_sel_hi:[1,0]
	v_pk_mul_f32 v[178:179], v[62:63], v[156:157] op_sel_hi:[1,0]
	v_pk_mul_f32 v[156:157], v[58:59], v[156:157] op_sel_hi:[1,0]
	v_cvt_pk_bf16_f32 v178, v178, v179
	v_cvt_pk_bf16_f32 v179, v180, v181
	v_cvt_pk_bf16_f32 v180, v156, v157
	v_lshl_add_u64 v[156:157], v[166:167], 0, s[34:35]
	v_cvt_pk_bf16_f32 v181, v182, v183
	global_store_dwordx4 v[156:157], v[178:181], off
	s_nop 1
	v_add_u32_e32 v156, 0x4000, v48
	v_pk_mul_f32 v[166:167], v[120:121], v[148:149] op_sel_hi:[1,0]
	v_pk_mul_f32 v[178:179], v[118:119], v[148:149] op_sel_hi:[1,0]
	v_mov_b32_e32 v157, v49
	v_cvt_pk_bf16_f32 v178, v178, v179
	v_cvt_pk_bf16_f32 v179, v166, v167
	v_pk_mul_f32 v[166:167], v[116:117], v[148:149] op_sel_hi:[1,0]
	v_pk_mul_f32 v[180:181], v[114:115], v[148:149] op_sel_hi:[1,0]
	v_lshl_add_u64 v[156:157], v[156:157], 1, s[58:59]
	v_cvt_pk_bf16_f32 v180, v180, v181
	v_cvt_pk_bf16_f32 v181, v166, v167
	global_store_dwordx4 v[156:157], v[178:181], off
	s_nop 1
	v_pk_mul_f32 v[156:157], v[56:57], v[148:149] op_sel_hi:[1,0]
	v_pk_mul_f32 v[166:167], v[54:55], v[148:149] op_sel_hi:[1,0]
	v_cvt_pk_bf16_f32 v179, v156, v157
	v_pk_mul_f32 v[156:157], v[52:53], v[148:149] op_sel_hi:[1,0]
	v_pk_mul_f32 v[148:149], v[50:51], v[148:149] op_sel_hi:[1,0]
	v_cvt_pk_bf16_f32 v178, v166, v167
	v_cvt_pk_bf16_f32 v180, v148, v149
	v_add_u32_e32 v148, 0x4080, v48
	v_mov_b32_e32 v149, v49
	v_lshl_add_u64 v[148:149], v[148:149], 1, s[58:59]
	v_cvt_pk_bf16_f32 v181, v156, v157
	global_store_dwordx4 v[148:149], v[178:181], off
	s_nop 1
	v_add_u32_e32 v148, 0x8000, v48
	v_pk_mul_f32 v[156:157], v[112:113], v[158:159] op_sel_hi:[1,0]
	v_pk_mul_f32 v[166:167], v[110:111], v[158:159] op_sel_hi:[1,0]
	v_mov_b32_e32 v149, v49
	v_cvt_pk_bf16_f32 v178, v166, v167
	v_cvt_pk_bf16_f32 v179, v156, v157
	v_pk_mul_f32 v[156:157], v[108:109], v[158:159] op_sel_hi:[1,0]
	v_pk_mul_f32 v[166:167], v[106:107], v[158:159] op_sel_hi:[1,0]
	v_lshl_add_u64 v[148:149], v[148:149], 1, s[58:59]
	v_cvt_pk_bf16_f32 v180, v166, v167
	v_cvt_pk_bf16_f32 v181, v156, v157
	global_store_dwordx4 v[148:149], v[178:181], off
	s_nop 1
	v_pk_mul_f32 v[148:149], v[46:47], v[158:159] op_sel_hi:[1,0]
	v_pk_mul_f32 v[156:157], v[44:45], v[158:159] op_sel_hi:[1,0]
	v_pk_mul_f32 v[166:167], v[100:101], v[150:151] op_sel_hi:[1,0]
	v_cvt_pk_bf16_f32 v156, v156, v157
	v_cvt_pk_bf16_f32 v157, v148, v149
	v_pk_mul_f32 v[148:149], v[42:43], v[158:159] op_sel_hi:[1,0]
	v_pk_mul_f32 v[158:159], v[40:41], v[158:159] op_sel_hi:[1,0]
	s_nop 0
	v_cvt_pk_bf16_f32 v158, v158, v159
	v_cvt_pk_bf16_f32 v159, v148, v149
	v_add_u32_e32 v148, 0x8080, v48
	v_mov_b32_e32 v149, v49
	v_lshl_add_u64 v[148:149], v[148:149], 1, s[58:59]
	global_store_dwordx4 v[148:149], v[156:159], off
	s_nop 1
	v_add_u32_e32 v148, 0xc000, v48
	v_pk_mul_f32 v[158:159], v[104:105], v[150:151] op_sel_hi:[1,0]
	v_pk_mul_f32 v[156:157], v[102:103], v[150:151] op_sel_hi:[1,0]
	v_mov_b32_e32 v149, v49
	v_cvt_pk_bf16_f32 v156, v156, v157
	v_cvt_pk_bf16_f32 v157, v158, v159
	v_pk_mul_f32 v[158:159], v[98:99], v[150:151] op_sel_hi:[1,0]
	v_lshl_add_u64 v[148:149], v[148:149], 1, s[58:59]
	v_cvt_pk_bf16_f32 v158, v158, v159
	v_cvt_pk_bf16_f32 v159, v166, v167
	global_store_dwordx4 v[148:149], v[156:159], off
	s_nop 1
	v_pk_mul_f32 v[156:157], v[38:39], v[150:151] op_sel_hi:[1,0]
	v_pk_mul_f32 v[148:149], v[36:37], v[150:151] op_sel_hi:[1,0]
	v_pk_mul_f32 v[158:159], v[92:93], v[160:161] op_sel_hi:[1,0]
	v_cvt_pk_bf16_f32 v148, v148, v149
	v_cvt_pk_bf16_f32 v149, v156, v157
	v_pk_mul_f32 v[156:157], v[34:35], v[150:151] op_sel_hi:[1,0]
	v_pk_mul_f32 v[150:151], v[32:33], v[150:151] op_sel_hi:[1,0]
	s_nop 0
	v_cvt_pk_bf16_f32 v150, v150, v151
	v_cvt_pk_bf16_f32 v151, v156, v157
	v_add_u32_e32 v156, 0xc080, v48
	v_mov_b32_e32 v157, v49
	v_lshl_add_u64 v[156:157], v[156:157], 1, s[58:59]
	global_store_dwordx4 v[156:157], v[148:151], off
	s_nop 1
	v_pk_mul_f32 v[150:151], v[96:97], v[160:161] op_sel_hi:[1,0]
	v_pk_mul_f32 v[148:149], v[94:95], v[160:161] op_sel_hi:[1,0]
	v_add_u32_e32 v156, 0x20000, v48
	v_cvt_pk_bf16_f32 v148, v148, v149
	v_cvt_pk_bf16_f32 v149, v150, v151
	v_pk_mul_f32 v[150:151], v[90:91], v[160:161] op_sel_hi:[1,0]
	v_mov_b32_e32 v157, v49
	v_cvt_pk_bf16_f32 v150, v150, v151
	v_cvt_pk_bf16_f32 v151, v158, v159
	v_lshl_add_u64 v[156:157], v[156:157], 1, s[58:59]
	global_store_dwordx4 v[156:157], v[148:151], off
	s_nop 1
	v_pk_mul_f32 v[150:151], v[30:31], v[160:161] op_sel_hi:[1,0]
	v_pk_mul_f32 v[148:149], v[28:29], v[160:161] op_sel_hi:[1,0]
	v_pk_mul_f32 v[156:157], v[26:27], v[160:161] op_sel_hi:[1,0]
	v_cvt_pk_bf16_f32 v148, v148, v149
	v_cvt_pk_bf16_f32 v149, v150, v151
	v_pk_mul_f32 v[150:151], v[24:25], v[160:161] op_sel_hi:[1,0]
	v_pk_mul_f32 v[158:159], v[84:85], v[152:153] op_sel_hi:[1,0]
	v_cvt_pk_bf16_f32 v150, v150, v151
	v_cvt_pk_bf16_f32 v151, v156, v157
	v_add_u32_e32 v156, 0x20080, v48
	v_mov_b32_e32 v157, v49
	v_lshl_add_u64 v[156:157], v[156:157], 1, s[58:59]
	global_store_dwordx4 v[156:157], v[148:151], off
	s_nop 1
	v_pk_mul_f32 v[150:151], v[88:89], v[152:153] op_sel_hi:[1,0]
	v_pk_mul_f32 v[148:149], v[86:87], v[152:153] op_sel_hi:[1,0]
	v_add_u32_e32 v156, 0x24000, v48
	v_cvt_pk_bf16_f32 v148, v148, v149
	v_cvt_pk_bf16_f32 v149, v150, v151
	v_pk_mul_f32 v[150:151], v[82:83], v[152:153] op_sel_hi:[1,0]
	v_mov_b32_e32 v157, v49
	v_cvt_pk_bf16_f32 v150, v150, v151
	v_cvt_pk_bf16_f32 v151, v158, v159
	v_lshl_add_u64 v[156:157], v[156:157], 1, s[58:59]
	global_store_dwordx4 v[156:157], v[148:151], off
	s_nop 1
	v_pk_mul_f32 v[150:151], v[22:23], v[152:153] op_sel_hi:[1,0]
	v_pk_mul_f32 v[148:149], v[20:21], v[152:153] op_sel_hi:[1,0]
	v_pk_mul_f32 v[156:157], v[18:19], v[152:153] op_sel_hi:[1,0]
	v_cvt_pk_bf16_f32 v148, v148, v149
	v_cvt_pk_bf16_f32 v149, v150, v151
	v_pk_mul_f32 v[150:151], v[16:17], v[152:153] op_sel_hi:[1,0]
	v_add_u32_e32 v152, 0x24080, v48
	v_cvt_pk_bf16_f32 v150, v150, v151
	v_cvt_pk_bf16_f32 v151, v156, v157
	v_mov_b32_e32 v153, v49
	v_lshl_add_u64 v[152:153], v[152:153], 1, s[58:59]
	global_store_dwordx4 v[152:153], v[148:151], off
	s_nop 1
	v_pk_mul_f32 v[150:151], v[80:81], v[164:165] op_sel_hi:[1,0]
	v_pk_mul_f32 v[148:149], v[78:79], v[164:165] op_sel_hi:[1,0]
	v_pk_mul_f32 v[156:157], v[76:77], v[164:165] op_sel_hi:[1,0]
	v_cvt_pk_bf16_f32 v148, v148, v149
	v_cvt_pk_bf16_f32 v149, v150, v151
	v_pk_mul_f32 v[150:151], v[74:75], v[164:165] op_sel_hi:[1,0]
	v_add_u32_e32 v152, 0x28000, v48
	v_cvt_pk_bf16_f32 v150, v150, v151
	v_cvt_pk_bf16_f32 v151, v156, v157
	v_mov_b32_e32 v153, v49
	v_lshl_add_u64 v[152:153], v[152:153], 1, s[58:59]
	global_store_dwordx4 v[152:153], v[148:151], off
	s_nop 1
	v_pk_mul_f32 v[150:151], v[14:15], v[164:165] op_sel_hi:[1,0]
	v_pk_mul_f32 v[148:149], v[12:13], v[164:165] op_sel_hi:[1,0]
	v_pk_mul_f32 v[152:153], v[10:11], v[164:165] op_sel_hi:[1,0]
	v_cvt_pk_bf16_f32 v148, v148, v149
	v_cvt_pk_bf16_f32 v149, v150, v151
	v_pk_mul_f32 v[150:151], v[8:9], v[164:165] op_sel_hi:[1,0]
	v_pk_mul_f32 v[156:157], v[68:69], v[162:163] op_sel_hi:[1,0]
	v_cvt_pk_bf16_f32 v150, v150, v151
	v_cvt_pk_bf16_f32 v151, v152, v153
	v_add_u32_e32 v152, 0x28080, v48
	v_mov_b32_e32 v153, v49
	v_lshl_add_u64 v[152:153], v[152:153], 1, s[58:59]
	global_store_dwordx4 v[152:153], v[148:151], off
	s_nop 1
	v_pk_mul_f32 v[150:151], v[72:73], v[162:163] op_sel_hi:[1,0]
	v_pk_mul_f32 v[148:149], v[70:71], v[162:163] op_sel_hi:[1,0]
	v_add_u32_e32 v152, 0x2c000, v48
	v_cvt_pk_bf16_f32 v148, v148, v149
	v_cvt_pk_bf16_f32 v149, v150, v151
	v_pk_mul_f32 v[150:151], v[66:67], v[162:163] op_sel_hi:[1,0]
	v_mov_b32_e32 v153, v49
	v_cvt_pk_bf16_f32 v150, v150, v151
	v_cvt_pk_bf16_f32 v151, v156, v157
	v_lshl_add_u64 v[152:153], v[152:153], 1, s[58:59]
	global_store_dwordx4 v[152:153], v[148:151], off
	s_nop 1
	v_pk_mul_f32 v[150:151], v[6:7], v[162:163] op_sel_hi:[1,0]
	v_pk_mul_f32 v[148:149], v[4:5], v[162:163] op_sel_hi:[1,0]
	v_pk_mul_f32 v[152:153], v[2:3], v[162:163] op_sel_hi:[1,0]
	v_cvt_pk_bf16_f32 v148, v148, v149
	v_cvt_pk_bf16_f32 v149, v150, v151
	v_pk_mul_f32 v[150:151], v[0:1], v[162:163] op_sel_hi:[1,0]
	v_add_u32_e32 v48, 0x2c080, v48
	v_cvt_pk_bf16_f32 v150, v150, v151
	v_cvt_pk_bf16_f32 v151, v152, v153
	v_lshl_add_u64 v[152:153], v[48:49], 1, s[58:59]
	global_store_dwordx4 v[152:153], v[148:151], off
	s_nop 1
	s_andn2_saveexec_b64 s[68:69], s[44:45]
	s_cbranch_execnz .LBB0_798

.LBB0_798:
	v_lshl_add_u64 v[164:165], v[48:49], 2, s[60:61]
	global_load_dword v48, v[164:165], off
	v_lshl_add_u64 v[162:163], v[162:163], 2, s[60:61]
	global_load_dword v162, v[162:163], off
	v_lshl_add_u64 v[160:161], v[160:161], 2, s[60:61]
	global_load_dword v160, v[160:161], off
	v_lshl_add_u64 v[158:159], v[158:159], 2, s[60:61]
	global_load_dword v158, v[158:159], off
	v_lshl_add_u64 v[156:157], v[156:157], 2, s[60:61]
	global_load_dword v156, v[156:157], off
	v_lshl_add_u64 v[152:153], v[152:153], 2, s[60:61]
	global_load_dword v152, v[152:153], off
	v_lshl_add_u64 v[150:151], v[150:151], 2, s[60:61]
	global_load_dword v153, v[150:151], off
	v_lshl_add_u64 v[148:149], v[148:149], 2, s[60:61]
	global_load_dword v178, v[148:149], off
	s_mov_b32 s6, 0x3b800000
	s_waitcnt vmcnt(0)
	s_waitcnt lgkmcnt(0)
	v_mov_b32_e32 v148, v48
	s_nop 1
	v_permlane16_swap_b32_e32 v48, v148
	v_add_f32_e32 v149, v48, v148
	v_mov_b32_e32 v151, v149
	s_nop 1
	v_permlane32_swap_b32_e32 v149, v151
	s_waitcnt lgkmcnt(0)
	v_mov_b32_e32 v48, v162
	s_nop 1
	v_permlane16_swap_b32_e32 v162, v48
	v_add_f32_e32 v148, v162, v48
	v_mov_b32_e32 v150, v148
	s_nop 1
	v_permlane32_swap_b32_e32 v148, v150
	v_pk_add_f32 v[148:149], v[148:149], v[150:151]
	s_nop 0
	v_pk_fma_f32 v[164:165], v[148:149], s[6:7], v[154:155] op_sel_hi:[1,0,0]
	s_mov_b32 s6, 0x55555556
	v_mul_f32_e32 v48, 0x4b800000, v165
	v_cmp_gt_f32_e32 vcc, s75, v165
	v_cmp_gt_f32_e64 s[42:43], s75, v164
	s_nop 0
	v_cndmask_b32_e32 v48, v165, v48, vcc
	v_rsq_f32_e32 v48, v48
	v_lshl_or_b32 v165, v166, 3, s88
	v_mul_f32_e32 v148, 0x45800000, v48
	v_cndmask_b32_e32 v48, v48, v148, vcc
	v_mul_f32_e32 v148, 0x3e16c740, v48
	s_waitcnt lgkmcnt(0)
	v_mov_b32_e32 v48, v160
	s_nop 1
	v_permlane16_swap_b32_e32 v160, v48
	v_add_f32_e32 v161, v160, v48
	v_mov_b32_e32 v163, v161
	s_nop 1
	v_permlane32_swap_b32_e32 v161, v163
	s_waitcnt lgkmcnt(0)
	v_mov_b32_e32 v48, v158
	s_nop 1
	v_permlane16_swap_b32_e32 v158, v48
	v_add_f32_e32 v160, v158, v48
	v_mov_b32_e32 v162, v160
	s_nop 1
	v_permlane32_swap_b32_e32 v160, v162
	s_waitcnt lgkmcnt(0)
	v_mov_b32_e32 v48, v156
	s_nop 1
	v_permlane16_swap_b32_e32 v156, v48
	v_add_f32_e32 v157, v156, v48
	v_mov_b32_e32 v159, v157
	s_nop 1
	v_permlane32_swap_b32_e32 v157, v159
	s_waitcnt lgkmcnt(0)
	v_mov_b32_e32 v48, v152
	s_nop 1
	v_permlane16_swap_b32_e32 v152, v48
	v_add_f32_e32 v156, v152, v48
	v_mov_b32_e32 v158, v156
	s_nop 1
	v_permlane32_swap_b32_e32 v156, v158
	s_waitcnt lgkmcnt(0)
	v_mov_b32_e32 v48, v153
	s_nop 1
	v_permlane16_swap_b32_e32 v153, v48
	v_add_f32_e32 v151, v153, v48
	ds_bpermute_b32 v48, v167, v178
	v_mov_b32_e32 v153, v151
	s_nop 1
	v_permlane32_swap_b32_e32 v151, v153
	s_waitcnt lgkmcnt(0)
	v_add_f32_e32 v150, v178, v48
	v_mul_hi_i32 v48, v165, s6
	v_lshrrev_b32_e32 v149, 31, v48
	v_add_u32_e32 v48, v48, v149
	v_lshl_add_u32 v48, v48, 1, v48
	v_sub_u32_e32 v48, v165, v48
	v_mov_b32_e32 v152, v150
	v_cmp_eq_u32_e32 vcc, 2, v48
	v_lshlrev_b32_e32 v48, 4, v177
	s_movk_i32 s6, 0x7cf0
	v_permlane32_swap_b32_e32 v150, v152
	v_pk_mul_f32 v[128:129], v[128:129], v[148:149] op_sel_hi:[1,0]
	v_pk_mul_f32 v[126:127], v[126:127], v[148:149] op_sel_hi:[1,0]
	v_pk_mul_f32 v[124:125], v[124:125], v[148:149] op_sel_hi:[1,0]
	v_pk_mul_f32 v[166:167], v[122:123], v[148:149] op_sel_hi:[1,0]
	v_and_or_b32 v123, v48, s6, v172
	s_and_saveexec_b64 s[44:45], vcc
	s_cbranch_execz .LBB0_800
	v_lshlrev_b32_e32 v48, 2, v123
	global_load_dwordx4 v[178:181], v48, s[48:49]
	global_load_dwordx4 v[182:185], v48, s[46:47]
	s_waitcnt vmcnt(1)
	v_pk_mul_f32 v[186:187], v[124:125], v[180:181]
	v_pk_mul_f32 v[188:189], v[166:167], v[178:179]
	v_pk_mul_f32 v[180:181], v[128:129], v[180:181]
	v_pk_mul_f32 v[178:179], v[126:127], v[178:179]
	s_waitcnt vmcnt(0)
	v_pk_fma_f32 v[128:129], v[128:129], v[184:185], v[186:187] neg_lo:[0,0,1] neg_hi:[0,0,1]
	v_pk_fma_f32 v[126:127], v[126:127], v[182:183], v[188:189] neg_lo:[0,0,1] neg_hi:[0,0,1]
	v_pk_fma_f32 v[124:125], v[124:125], v[184:185], v[180:181]
	v_pk_fma_f32 v[166:167], v[166:167], v[182:183], v[178:179]

.LBB0_910:
	s_or_b64 exec, exec, s[46:47]
	v_add_u32_e32 v72, v111, v226
	v_ashrrev_i32_e32 v73, 31, v72
	v_lshrrev_b32_e32 v73, 26, v73
	v_add_u32_e32 v72, v72, v73
	v_ashrrev_i32_e32 v72, 6, v72
	v_cvt_pk_bf16_f32 v86, v66, v67
	v_lshl_add_u32 v66, v72, 3, s52
	v_cvt_pk_bf16_f32 v80, v80, v81
	v_cvt_pk_bf16_f32 v84, v82, v83
	v_cvt_pk_bf16_f32 v81, v78, v79
	v_cvt_pk_bf16_f32 v82, v76, v77
	v_cvt_pk_bf16_f32 v83, v74, v75
	v_ashrrev_i32_e32 v67, 31, v66
	v_cvt_pk_bf16_f32 v85, v70, v71
	v_cvt_pk_bf16_f32 v87, v68, v69
	ds_write_b128 v221, v[80:83]
	ds_write_b128 v221, v[84:87] offset:16
	s_waitcnt lgkmcnt(0)
	s_barrier
	v_lshlrev_b64 v[126:127], 11, v[66:67]
	ds_read_b128 v[66:69], v224
	ds_read_b128 v[82:85], v224 offset:64
	s_waitcnt lgkmcnt(1)
	v_mfma_f32_16x16x32_bf16 v[70:73], v[44:47], v[66:69], 0
	v_add_u32_e32 v132, v218, v225
	v_ashrrev_i32_e32 v133, 31, v132
	s_mov_b64 s[6:7], 0x7800400
	v_mfma_f32_16x16x32_bf16 v[74:77], v[50:53], v[66:69], 0
	v_or_b32_e32 v128, v227, v218
	v_ashrrev_i32_e32 v129, 31, v128
	v_cmp_lt_i32_e32 vcc, 0, v128
	v_mfma_f32_16x16x32_bf16 v[78:81], v[54:57], v[66:69], 0
	s_nop 0
	v_cndmask_b32_e64 v201, 0, -1, vcc
	v_cndmask_b32_e32 v200, 0, v210, vcc
	v_mfma_f32_16x16x32_bf16 v[66:69], v[58:61], v[66:69], 0
	v_cndmask_b32_e64 v176, 0, 1.0, vcc
	s_waitcnt lgkmcnt(0)
	v_mfma_f32_16x16x32_bf16 v[70:73], v[32:35], v[82:85], v[70:73]
	v_mfma_f32_16x16x32_bf16 v[74:77], v[36:39], v[82:85], v[74:77]
	v_mfma_f32_16x16x32_bf16 v[78:81], v[40:43], v[82:85], v[78:81]
	v_mfma_f32_16x16x32_bf16 v[66:69], v[62:65], v[82:85], v[66:69]
	ds_read_b128 v[82:85], v222 offset:45056
	ds_read_b128 v[86:89], v222 offset:45072
	s_waitcnt lgkmcnt(1)
	s_nop 1
	v_add_f32_e32 v70, v70, v82
	v_add_f32_e32 v71, v71, v83
	v_mul_f32_e32 v70, 0xbfb8aa3b, v70
	v_mul_f32_e32 v71, 0xbfb8aa3b, v71
	v_exp_f32_e32 v70, v70
	v_exp_f32_e32 v71, v71
	v_add_f32_e32 v70, 1.0, v70
	v_add_f32_e32 v71, 1.0, v71
	v_rcp_f32_e32 v70, v70
	v_rcp_f32_e32 v71, v71
	s_nop 0
	v_pk_mul_f32 v[160:161], v[70:71], s[72:73] op_sel_hi:[1,0]
	v_add_f32_e32 v70, v72, v84
	v_add_f32_e32 v71, v73, v85
	v_mul_f32_e32 v70, 0xbfb8aa3b, v70
	v_mul_f32_e32 v71, 0xbfb8aa3b, v71
	v_exp_f32_e32 v70, v70
	v_exp_f32_e32 v71, v71
	ds_read_b128 v[82:85], v224 offset:192
	v_add_f32_e32 v70, 1.0, v70
	v_add_f32_e32 v71, 1.0, v71
	v_rcp_f32_e32 v70, v70
	v_rcp_f32_e32 v71, v71
	s_nop 0
	v_pk_mul_f32 v[162:163], v[70:71], s[72:73] op_sel_hi:[1,0]
	s_waitcnt lgkmcnt(1)
	v_add_f32_e32 v70, v74, v86
	v_add_f32_e32 v71, v75, v87
	v_mul_f32_e32 v70, 0xbfb8aa3b, v70
	v_mul_f32_e32 v71, 0xbfb8aa3b, v71
	v_exp_f32_e32 v70, v70
	v_exp_f32_e32 v71, v71
	v_add_f32_e32 v70, 1.0, v70
	v_add_f32_e32 v71, 1.0, v71
	v_rcp_f32_e32 v70, v70
	v_rcp_f32_e32 v71, v71
	s_nop 0
	v_pk_mul_f32 v[164:165], v[70:71], s[72:73] op_sel_hi:[1,0]
	v_add_f32_e32 v70, v76, v88
	v_add_f32_e32 v71, v77, v89
	v_mul_f32_e32 v70, 0xbfb8aa3b, v70
	v_mul_f32_e32 v71, 0xbfb8aa3b, v71
	v_exp_f32_e32 v70, v70
	v_exp_f32_e32 v71, v71
	global_load_dwordx4 v[86:89], v[112:113], off offset:64
	v_add_f32_e32 v70, 1.0, v70
	v_add_f32_e32 v71, 1.0, v71
	v_rcp_f32_e32 v70, v70
	v_rcp_f32_e32 v71, v71
	s_nop 0
	v_pk_mul_f32 v[166:167], v[70:71], s[72:73] op_sel_hi:[1,0]
	ds_read_b128 v[70:73], v222 offset:45184
	s_waitcnt lgkmcnt(0)
	v_add_f32_e32 v70, v78, v70
	v_add_f32_e32 v71, v79, v71
	v_mul_f32_e32 v70, 0xbfb8aa3b, v70
	v_mul_f32_e32 v71, 0xbfb8aa3b, v71
	v_exp_f32_e32 v70, v70
	v_exp_f32_e32 v71, v71
	v_add_f32_e32 v70, 1.0, v70
	v_add_f32_e32 v71, 1.0, v71
	v_rcp_f32_e32 v70, v70
	v_rcp_f32_e32 v71, v71
	s_nop 0
	v_pk_mul_f32 v[150:151], v[70:71], s[72:73] op_sel_hi:[1,0]
	v_add_f32_e32 v70, v80, v72
	v_add_f32_e32 v71, v81, v73
	v_mul_f32_e32 v70, 0xbfb8aa3b, v70
	v_mul_f32_e32 v71, 0xbfb8aa3b, v71
	v_exp_f32_e32 v70, v70
	v_exp_f32_e32 v71, v71
	v_add_f32_e32 v70, 1.0, v70
	v_add_f32_e32 v71, 1.0, v71
	v_rcp_f32_e32 v70, v70
	v_rcp_f32_e32 v71, v71
	s_nop 0
	v_pk_mul_f32 v[152:153], v[70:71], s[72:73] op_sel_hi:[1,0]
	ds_read_b128 v[70:73], v222 offset:45200
	s_waitcnt lgkmcnt(0)
	v_add_f32_e32 v66, v66, v70
	v_add_f32_e32 v67, v67, v71
	v_mul_f32_e32 v66, 0xbfb8aa3b, v66
	v_mul_f32_e32 v67, 0xbfb8aa3b, v67
	v_exp_f32_e32 v66, v66
	v_exp_f32_e32 v67, v67
	v_add_f32_e32 v66, 1.0, v66
	v_add_f32_e32 v67, 1.0, v67
	v_rcp_f32_e32 v66, v66
	v_rcp_f32_e32 v67, v67
	s_nop 0
	v_pk_mul_f32 v[156:157], v[66:67], s[72:73] op_sel_hi:[1,0]
	v_add_f32_e32 v66, v68, v72
	v_add_f32_e32 v67, v69, v73
	v_mul_f32_e32 v66, 0xbfb8aa3b, v66
	v_mul_f32_e32 v67, 0xbfb8aa3b, v67
	v_exp_f32_e32 v66, v66
	v_exp_f32_e32 v67, v67
	v_add_f32_e32 v66, 1.0, v66
	v_add_f32_e32 v67, 1.0, v67
	v_rcp_f32_e32 v66, v66
	v_rcp_f32_e32 v67, v67
	s_nop 0
	v_pk_mul_f32 v[158:159], v[66:67], s[72:73] op_sel_hi:[1,0]
	ds_read_b128 v[66:69], v224 offset:128
	s_waitcnt lgkmcnt(0)
	v_mfma_f32_16x16x32_bf16 v[70:73], v[0:3], v[66:69], 0
	v_mfma_f32_16x16x32_bf16 v[74:77], v[4:7], v[66:69], 0
	v_mfma_f32_16x16x32_bf16 v[78:81], v[8:11], v[66:69], 0
	v_mfma_f32_16x16x32_bf16 v[66:69], v[12:15], v[66:69], 0
	v_mfma_f32_16x16x32_bf16 v[70:73], v[16:19], v[82:85], v[70:73]
	v_mfma_f32_16x16x32_bf16 v[74:77], v[20:23], v[82:85], v[74:77]
	v_mfma_f32_16x16x32_bf16 v[78:81], v[24:27], v[82:85], v[78:81]
	v_mfma_f32_16x16x32_bf16 v[66:69], v[28:31], v[82:85], v[66:69]
	ds_read_b128 v[82:85], v222 offset:47104
	s_waitcnt lgkmcnt(0)
	s_nop 2
	v_add_f32_e32 v70, v70, v82
	v_mul_f32_e32 v70, 0xbfb8aa3b, v70
	v_exp_f32_e32 v70, v70
	s_nop 0
	v_add_f32_e32 v70, 1.0, v70
	v_rcp_f32_e32 v146, v70
	v_add_f32_e32 v70, v71, v83
	v_mul_f32_e32 v70, 0xbfb8aa3b, v70
	v_exp_f32_e32 v70, v70
	s_nop 0
	v_add_f32_e32 v70, 1.0, v70
	v_rcp_f32_e32 v147, v70
	v_add_f32_e32 v70, v72, v84
	v_mul_f32_e32 v70, 0xbfb8aa3b, v70
	v_exp_f32_e32 v70, v70
	s_nop 0
	v_add_f32_e32 v70, 1.0, v70
	v_rcp_f32_e32 v148, v70
	v_add_f32_e32 v70, v73, v85
	v_mul_f32_e32 v70, 0xbfb8aa3b, v70
	v_exp_f32_e32 v70, v70
	global_load_dwordx4 v[82:85], v[118:119], off
	v_add_f32_e32 v70, 1.0, v70
	v_rcp_f32_e32 v149, v70
	ds_read_b128 v[70:73], v222 offset:47120
	s_waitcnt lgkmcnt(0)
	v_add_f32_e32 v70, v74, v70
	v_mul_f32_e32 v70, 0xbfb8aa3b, v70
	v_exp_f32_e32 v70, v70
	s_nop 0
	v_add_f32_e32 v70, 1.0, v70
	v_rcp_f32_e32 v142, v70
	v_add_f32_e32 v70, v75, v71
	v_mul_f32_e32 v70, 0xbfb8aa3b, v70
	v_exp_f32_e32 v70, v70
	s_nop 0
	v_add_f32_e32 v70, 1.0, v70
	v_rcp_f32_e32 v143, v70
	v_add_f32_e32 v70, v76, v72
	v_mul_f32_e32 v70, 0xbfb8aa3b, v70
	v_exp_f32_e32 v70, v70
	s_nop 0
	v_add_f32_e32 v70, 1.0, v70
	v_rcp_f32_e32 v144, v70
	v_add_f32_e32 v70, v77, v73
	v_mul_f32_e32 v70, 0xbfb8aa3b, v70
	v_exp_f32_e32 v70, v70
	global_load_dwordx4 v[74:77], v[114:115], off
	v_add_f32_e32 v70, 1.0, v70
	v_rcp_f32_e32 v145, v70
	ds_read_b128 v[70:73], v222 offset:47232
	s_waitcnt lgkmcnt(0)
	v_add_f32_e32 v70, v78, v70
	v_mul_f32_e32 v70, 0xbfb8aa3b, v70
	v_exp_f32_e32 v70, v70
	s_nop 0
	v_add_f32_e32 v70, 1.0, v70
	v_rcp_f32_e32 v138, v70
	v_add_f32_e32 v70, v79, v71
	v_mul_f32_e32 v70, 0xbfb8aa3b, v70
	v_exp_f32_e32 v70, v70
	s_nop 0
	v_add_f32_e32 v70, 1.0, v70
	v_rcp_f32_e32 v139, v70
	v_add_f32_e32 v70, v80, v72
	v_mul_f32_e32 v70, 0xbfb8aa3b, v70
	v_exp_f32_e32 v70, v70
	s_nop 0
	v_add_f32_e32 v70, 1.0, v70
	v_rcp_f32_e32 v140, v70
	v_add_f32_e32 v70, v81, v73
	v_mul_f32_e32 v70, 0xbfb8aa3b, v70
	v_exp_f32_e32 v70, v70
	global_load_dwordx4 v[78:81], v[116:117], off
	v_add_f32_e32 v70, 1.0, v70
	v_rcp_f32_e32 v141, v70
	ds_read_b128 v[70:73], v222 offset:47248
	s_waitcnt lgkmcnt(0)
	v_add_f32_e32 v66, v66, v70
	v_mul_f32_e32 v66, 0xbfb8aa3b, v66
	v_exp_f32_e32 v66, v66
	s_nop 0
	v_add_f32_e32 v66, 1.0, v66
	v_rcp_f32_e32 v134, v66
	v_add_f32_e32 v66, v67, v71
	v_mul_f32_e32 v66, 0xbfb8aa3b, v66
	v_exp_f32_e32 v66, v66
	s_nop 0
	v_add_f32_e32 v66, 1.0, v66
	v_rcp_f32_e32 v135, v66
	v_add_f32_e32 v66, v68, v72
	v_mul_f32_e32 v66, 0xbfb8aa3b, v66
	v_exp_f32_e32 v66, v66
	s_nop 0
	v_add_f32_e32 v66, 1.0, v66
	v_rcp_f32_e32 v136, v66
	v_add_f32_e32 v66, v69, v73
	global_load_dwordx4 v[70:73], v[112:113], off
	v_mul_f32_e32 v66, 0xbfb8aa3b, v66
	v_exp_f32_e32 v66, v66
	s_nop 0
	v_add_f32_e32 v66, 1.0, v66
	v_rcp_f32_e32 v137, v66
	ds_read_b128 v[66:69], v224 offset:256
	s_waitcnt vmcnt(0) lgkmcnt(0)
	v_mfma_f32_16x16x32_bf16 v[70:73], v[70:73], v[66:69], 0
	v_mfma_f32_16x16x32_bf16 v[74:77], v[74:77], v[66:69], 0
	v_mfma_f32_16x16x32_bf16 v[78:81], v[78:81], v[66:69], 0
	v_mfma_f32_16x16x32_bf16 v[66:69], v[82:85], v[66:69], 0
	ds_read_b128 v[82:85], v224 offset:320
	s_waitcnt lgkmcnt(0)
	v_mfma_f32_16x16x32_bf16 v[70:73], v[86:89], v[82:85], v[70:73]
	global_load_dwordx4 v[86:89], v[114:115], off offset:64
	s_waitcnt vmcnt(0)
	v_mfma_f32_16x16x32_bf16 v[74:77], v[86:89], v[82:85], v[74:77]
	global_load_dwordx4 v[86:89], v[116:117], off offset:64
	s_waitcnt vmcnt(0)
	v_mfma_f32_16x16x32_bf16 v[78:81], v[86:89], v[82:85], v[78:81]
	global_load_dwordx4 v[86:89], v[118:119], off offset:64
	s_waitcnt vmcnt(0)
	v_mfma_f32_16x16x32_bf16 v[66:69], v[86:89], v[82:85], v[66:69]
	global_load_dwordx4 v[86:89], v[112:113], off offset:128
	ds_read_b128 v[82:85], v224 offset:384
	s_waitcnt vmcnt(0) lgkmcnt(0)
	v_mfma_f32_16x16x32_bf16 v[86:89], v[86:89], v[82:85], v[70:73]
	s_nop 2
	global_load_dwordx4 v[70:73], v[114:115], off offset:128
	s_waitcnt vmcnt(0)
	v_mfma_f32_16x16x32_bf16 v[90:93], v[70:73], v[82:85], v[74:77]
	global_load_dwordx4 v[70:73], v[116:117], off offset:128
	s_nop 1
	global_load_dwordx4 v[74:77], v[112:113], off offset:192
	s_waitcnt vmcnt(1)
	v_mfma_f32_16x16x32_bf16 v[168:171], v[70:73], v[82:85], v[78:81]
	global_load_dwordx4 v[70:73], v[118:119], off offset:128
	s_nop 1
	global_load_dwordx4 v[78:81], v[114:115], off offset:192
	s_waitcnt vmcnt(1)
	v_mfma_f32_16x16x32_bf16 v[66:69], v[70:73], v[82:85], v[66:69]
	ds_read_b128 v[70:73], v224 offset:448
	global_load_dwordx4 v[82:85], v[116:117], off offset:192
	s_waitcnt lgkmcnt(0)
	v_mfma_f32_16x16x32_bf16 v[74:77], v[74:77], v[70:73], v[86:89]
	s_nop 2
	global_load_dwordx4 v[86:89], v[118:119], off offset:192
	s_waitcnt vmcnt(2)
	v_mfma_f32_16x16x32_bf16 v[78:81], v[78:81], v[70:73], v[90:93]
	s_waitcnt vmcnt(1)
	v_mfma_f32_16x16x32_bf16 v[82:85], v[82:85], v[70:73], v[168:171]
	s_waitcnt vmcnt(0)
	v_mfma_f32_16x16x32_bf16 v[66:69], v[86:89], v[70:73], v[66:69]
	v_lshlrev_b64 v[70:71], 11, v[132:133]
	v_lshl_add_u64 v[70:71], s[2:3], 0, v[70:71]
	v_lshl_add_u64 v[70:71], s[56:57], 1, v[70:71]
	v_lshl_add_u64 v[86:87], v[70:71], 0, v[48:49]
	v_lshl_add_u64 v[88:89], v[86:87], 0, s[6:7]
	v_cvt_pk_bf16_f32 v72, v78, v79
	s_mov_b64 s[6:7], 0x7800440
	v_cvt_pk_bf16_f32 v70, v74, v75
	v_cvt_pk_bf16_f32 v71, v76, v77
	v_cvt_pk_bf16_f32 v73, v80, v81
	global_store_dwordx4 v[88:89], v[70:73], off
	s_nop 1
	v_cvt_pk_bf16_f32 v72, v66, v67
	v_lshl_add_u64 v[66:67], v[86:87], 0, s[6:7]
	v_cvt_pk_bf16_f32 v70, v82, v83
	v_cvt_pk_bf16_f32 v71, v84, v85
	v_cvt_pk_bf16_f32 v73, v68, v69
	global_store_dwordx4 v[66:67], v[70:73], off
	s_nop 1
	v_lshl_add_u64 v[66:67], v[126:127], 0, v[128:129]
	v_mov_b64_e32 v[68:69], s[54:55]
	v_mad_u64_u32 v[182:183], s[6:7], v66, s95, v[68:69]
	v_mad_i32_i24 v183, v67, s95, v183
	v_mov_b64_e32 v[66:67], s[12:13]
	v_mad_i64_i32 v[202:203], s[6:7], v132, s19, v[66:67]
	v_lshl_add_u64 v[78:79], v[120:121], 1, v[202:203]
	s_mov_b64 s[6:7], 0x800
	v_lshl_add_u64 v[74:75], v[78:79], 0, s[6:7]
	v_lshl_add_u64 v[82:83], v[78:79], 0, v[200:201]
	global_load_dwordx4 v[70:73], v[78:79], off offset:2048
	global_load_dwordx4 v[66:69], v[78:79], off offset:3072
	s_nop 0
	global_load_dwordx4 v[74:77], v[74:75], off offset:2048
	v_lshl_add_u64 v[86:87], v[82:83], 0, s[6:7]
	global_load_dwordx4 v[78:81], v[82:83], off offset:2048
	s_nop 0
	global_load_dwordx4 v[82:85], v[82:83], off offset:3072
	s_nop 0
	global_load_dwordx4 v[86:89], v[86:87], off offset:2048
	ds_read_b128 v[170:173], v223 offset:32768
	ds_read_b128 v[90:93], v223 offset:32784
	ds_read_b128 v[178:181], v223 offset:34816
	ds_read_b128 v[184:187], v223 offset:36864
	v_lshl_add_u64 v[182:183], v[182:183], 0, v[48:49]
	s_mov_b64 s[6:7], 0x280
	s_waitcnt vmcnt(5)
	v_lshlrev_b32_e32 v174, 16, v70
	v_and_b32_e32 v175, 0xffff0000, v70
	v_lshlrev_b32_e32 v70, 16, v71
	v_and_b32_e32 v71, 0xffff0000, v71
	s_waitcnt vmcnt(2)
	v_lshlrev_b32_e32 v168, 16, v78
	v_and_b32_e32 v169, 0xffff0000, v78
	v_xor_b32_e32 v197, 0x80000000, v175
	v_xor_b32_e32 v196, 0x80000000, v174
	v_lshlrev_b32_e32 v78, 16, v79
	v_and_b32_e32 v79, 0xffff0000, v79
	v_pk_fma_f32 v[196:197], v[176:177], v[168:169], v[196:197] op_sel_hi:[0,1,1]
	v_xor_b32_e32 v169, 0x80000000, v71
	v_xor_b32_e32 v168, 0x80000000, v70
	v_lshlrev_b32_e32 v188, 16, v66
	v_and_b32_e32 v189, 0xffff0000, v66
	v_lshlrev_b32_e32 v66, 16, v67
	v_and_b32_e32 v67, 0xffff0000, v67
	v_pk_fma_f32 v[78:79], v[176:177], v[78:79], v[168:169] op_sel_hi:[0,1,1]
	s_waitcnt vmcnt(1)
	v_lshlrev_b32_e32 v192, 16, v82
	v_and_b32_e32 v193, 0xffff0000, v82
	v_lshlrev_b32_e32 v82, 16, v83
	v_and_b32_e32 v83, 0xffff0000, v83
	s_waitcnt lgkmcnt(3)
	v_pk_fma_f32 v[168:169], v[172:173], v[78:79], v[70:71]
	v_xor_b32_e32 v71, 0x80000000, v189
	v_xor_b32_e32 v70, 0x80000000, v188
	v_xor_b32_e32 v79, 0x80000000, v67
	v_xor_b32_e32 v78, 0x80000000, v66
	v_pk_fma_f32 v[70:71], v[176:177], v[192:193], v[70:71] op_sel_hi:[0,1,1]
	v_pk_fma_f32 v[78:79], v[176:177], v[82:83], v[78:79] op_sel_hi:[0,1,1]
	v_pk_fma_f32 v[170:171], v[170:171], v[196:197], v[174:175]
	s_waitcnt lgkmcnt(1)
	v_pk_fma_f32 v[172:173], v[180:181], v[78:79], v[66:67]
	v_pk_fma_f32 v[174:175], v[178:179], v[70:71], v[188:189]
	ds_read_b128 v[178:181], v223 offset:38912
	v_lshlrev_b32_e32 v190, 16, v74
	v_and_b32_e32 v191, 0xffff0000, v74
	v_lshlrev_b32_e32 v74, 16, v75
	v_and_b32_e32 v75, 0xffff0000, v75
	s_waitcnt vmcnt(0)
	v_lshlrev_b32_e32 v194, 16, v86
	v_and_b32_e32 v195, 0xffff0000, v86
	v_xor_b32_e32 v67, 0x80000000, v191
	v_xor_b32_e32 v66, 0x80000000, v190
	v_lshlrev_b32_e32 v86, 16, v87
	v_and_b32_e32 v87, 0xffff0000, v87
	v_pk_fma_f32 v[70:71], v[176:177], v[194:195], v[66:67] op_sel_hi:[0,1,1]
	v_xor_b32_e32 v67, 0x80000000, v75
	v_xor_b32_e32 v66, 0x80000000, v74
	v_pk_fma_f32 v[66:67], v[176:177], v[86:87], v[66:67] op_sel_hi:[0,1,1]
	s_waitcnt lgkmcnt(0)
	v_pk_mul_f32 v[178:179], v[178:179], v[174:175]
	v_pk_mul_f32 v[180:181], v[180:181], v[172:173]
	v_pk_fma_f32 v[66:67], v[186:187], v[66:67], v[74:75]
	v_pk_mul_f32 v[74:75], v[180:181], v[180:181]
	v_pk_mul_f32 v[78:79], v[178:179], v[178:179]
	v_lshlrev_b32_e32 v86, 16, v72
	v_pk_mov_b32 v[82:83], v[78:79], v[74:75] op_sel:[1,0]
	v_mov_b32_e32 v79, v75
	v_pk_add_f32 v[74:75], v[82:83], v[78:79]
	v_and_b32_e32 v87, 0xffff0000, v72
	v_pk_fma_f32 v[70:71], v[184:185], v[70:71], v[190:191]
	v_pk_add_f32 v[192:193], v[74:75], v[74:75] op_sel_hi:[0,1]
	v_lshlrev_b32_e32 v184, 16, v73
	v_and_b32_e32 v185, 0xffff0000, v73
	v_lshlrev_b32_e32 v190, 16, v68
	v_and_b32_e32 v191, 0xffff0000, v68
	v_lshlrev_b32_e32 v188, 16, v69
	v_and_b32_e32 v189, 0xffff0000, v69
	v_lshlrev_b32_e32 v68, 16, v76
	v_and_b32_e32 v69, 0xffff0000, v76
	v_lshlrev_b32_e32 v72, 16, v77
	v_and_b32_e32 v73, 0xffff0000, v77
	v_lshlrev_b32_e32 v186, 16, v80
	v_and_b32_e32 v187, 0xffff0000, v80
	v_lshlrev_b32_e32 v76, 16, v88
	v_and_b32_e32 v77, 0xffff0000, v88
	v_lshlrev_b32_e32 v74, 16, v89
	v_and_b32_e32 v75, 0xffff0000, v89
	v_xor_b32_e32 v89, 0x80000000, v87
	v_xor_b32_e32 v88, 0x80000000, v86
	v_lshlrev_b32_e32 v194, 16, v81
	v_and_b32_e32 v195, 0xffff0000, v81
	v_lshlrev_b32_e32 v196, 16, v84
	v_and_b32_e32 v197, 0xffff0000, v84
	v_lshlrev_b32_e32 v198, 16, v85
	v_and_b32_e32 v199, 0xffff0000, v85
	ds_read_b128 v[78:81], v223 offset:34832
	ds_read_b128 v[82:85], v223 offset:36880
	v_pk_fma_f32 v[88:89], v[176:177], v[186:187], v[88:89] op_sel_hi:[0,1,1]
	v_xor_b32_e32 v187, 0x80000000, v185
	v_xor_b32_e32 v186, 0x80000000, v184
	v_pk_fma_f32 v[186:187], v[176:177], v[194:195], v[186:187] op_sel_hi:[0,1,1]
	v_pk_fma_f32 v[184:185], v[92:93], v[186:187], v[184:185]
	v_pk_fma_f32 v[186:187], v[90:91], v[88:89], v[86:87]
	v_xor_b32_e32 v87, 0x80000000, v191
	v_xor_b32_e32 v86, 0x80000000, v190
	v_pk_fma_f32 v[86:87], v[176:177], v[196:197], v[86:87] op_sel_hi:[0,1,1]
	s_waitcnt lgkmcnt(1)
	v_pk_fma_f32 v[190:191], v[78:79], v[86:87], v[190:191]
	v_xor_b32_e32 v79, 0x80000000, v69
	v_xor_b32_e32 v78, 0x80000000, v68
	v_pk_fma_f32 v[76:77], v[176:177], v[76:77], v[78:79] op_sel_hi:[0,1,1]
	v_xor_b32_e32 v79, 0x80000000, v73
	v_xor_b32_e32 v78, 0x80000000, v72
	v_pk_fma_f32 v[74:75], v[176:177], v[74:75], v[78:79] op_sel_hi:[0,1,1]
	s_waitcnt lgkmcnt(0)
	v_pk_fma_f32 v[78:79], v[84:85], v[74:75], v[72:73]
	ds_read_b128 v[72:75], v223 offset:38928
	v_xor_b32_e32 v89, 0x80000000, v189
	v_xor_b32_e32 v88, 0x80000000, v188
	v_pk_fma_f32 v[88:89], v[176:177], v[198:199], v[88:89] op_sel_hi:[0,1,1]
	v_pk_fma_f32 v[188:189], v[80:81], v[88:89], v[188:189]
	s_waitcnt lgkmcnt(0)
	v_pk_mul_f32 v[194:195], v[72:73], v[190:191]
	v_pk_mul_f32 v[196:197], v[74:75], v[188:189]
	v_pk_fma_f32 v[76:77], v[82:83], v[76:77], v[68:69]
	v_pk_mul_f32 v[68:69], v[196:197], v[196:197]
	v_pk_mul_f32 v[72:73], v[194:195], v[194:195]
	s_nop 0
	v_pk_mov_b32 v[74:75], v[72:73], v[68:69] op_sel:[1,0]
	v_mov_b32_e32 v73, v69
	v_pk_add_f32 v[68:69], v[74:75], v[72:73]
	v_lshl_add_u64 v[72:73], v[182:183], 0, s[6:7]
	v_pk_add_f32 v[198:199], v[68:69], v[68:69] op_sel_hi:[0,1]
	v_cvt_pk_bf16_f32 v68, v70, v71
	v_cvt_pk_bf16_f32 v69, v66, v67
	v_cvt_pk_bf16_f32 v70, v76, v77
	v_cvt_pk_bf16_f32 v71, v78, v79
	global_store_dwordx4 v[72:73], v[68:71], off
	s_nop 1
	s_mov_b64 s[6:7], 0x200
	v_lshl_add_u64 v[70:71], v[182:183], 0, s[6:7]
	v_cvt_pk_bf16_f32 v66, v170, v171
	v_cvt_pk_bf16_f32 v67, v168, v169
	v_cvt_pk_bf16_f32 v68, v186, v187
	v_cvt_pk_bf16_f32 v69, v184, v185
	global_store_dwordx4 v[70:71], v[66:69], off
	s_nop 1
	v_lshl_add_u64 v[78:79], v[122:123], 1, v[202:203]
	s_mov_b64 s[6:7], 0x840
	v_cvt_pk_bf16_f32 v66, v160, v161
	v_cvt_pk_bf16_f32 v67, v162, v163
	v_cvt_pk_bf16_f32 v68, v164, v165
	v_cvt_pk_bf16_f32 v69, v166, v167
	global_store_dwordx4 v[182:183], v[66:69], off
	s_nop 1
	v_lshl_add_u64 v[74:75], v[78:79], 0, s[6:7]
	v_lshl_add_u64 v[82:83], v[78:79], 0, v[200:201]
	global_load_dwordx4 v[66:69], v[78:79], off offset:2112
	global_load_dwordx4 v[70:73], v[78:79], off offset:3136
	s_nop 0
	global_load_dwordx4 v[74:77], v[74:75], off offset:2048
	v_lshl_add_u64 v[86:87], v[82:83], 0, s[6:7]
	global_load_dwordx4 v[78:81], v[82:83], off offset:2112
	s_nop 0
	global_load_dwordx4 v[82:85], v[82:83], off offset:3136
	s_nop 0
	global_load_dwordx4 v[86:89], v[86:87], off offset:2048
	ds_read_b128 v[160:163], v223 offset:32896
	ds_read_b128 v[90:93], v223 offset:32912
	ds_read_b128 v[164:167], v223 offset:34944
	ds_read_b128 v[200:203], v223 offset:36992
	s_mov_b64 s[6:7], 0x2c0
	s_waitcnt vmcnt(5)
	v_lshlrev_b32_e32 v212, 16, v66
	v_and_b32_e32 v213, 0xffff0000, v66
	v_lshlrev_b32_e32 v66, 16, v67
	v_and_b32_e32 v67, 0xffff0000, v67
	s_waitcnt vmcnt(4)
	v_lshlrev_b32_e32 v214, 16, v70
	v_and_b32_e32 v215, 0xffff0000, v70
	v_lshlrev_b32_e32 v228, 16, v71
	v_and_b32_e32 v229, 0xffff0000, v71
	s_waitcnt vmcnt(2)
	v_lshlrev_b32_e32 v70, 16, v78
	v_and_b32_e32 v71, 0xffff0000, v78
	v_xor_b32_e32 v237, 0x80000000, v213
	v_xor_b32_e32 v236, 0x80000000, v212
	v_lshlrev_b32_e32 v230, 16, v74
	v_and_b32_e32 v231, 0xffff0000, v74
	v_lshlrev_b32_e32 v232, 16, v75
	v_and_b32_e32 v233, 0xffff0000, v75
	v_lshlrev_b32_e32 v74, 16, v79
	v_and_b32_e32 v75, 0xffff0000, v79
	v_pk_fma_f32 v[70:71], v[176:177], v[70:71], v[236:237] op_sel_hi:[0,1,1]
	v_xor_b32_e32 v237, 0x80000000, v67
	v_xor_b32_e32 v236, 0x80000000, v66
	v_pk_fma_f32 v[74:75], v[176:177], v[74:75], v[236:237] op_sel_hi:[0,1,1]
	s_waitcnt vmcnt(1)
	v_lshlrev_b32_e32 v78, 16, v82
	v_and_b32_e32 v79, 0xffff0000, v82
	v_lshlrev_b32_e32 v82, 16, v83
	v_and_b32_e32 v83, 0xffff0000, v83
	s_waitcnt lgkmcnt(3)
	v_pk_fma_f32 v[66:67], v[162:163], v[74:75], v[66:67]
	v_xor_b32_e32 v75, 0x80000000, v229
	v_xor_b32_e32 v74, 0x80000000, v228
	s_waitcnt vmcnt(0)
	v_lshlrev_b32_e32 v234, 16, v86
	v_and_b32_e32 v235, 0xffff0000, v86
	v_lshlrev_b32_e32 v86, 16, v87
	v_and_b32_e32 v87, 0xffff0000, v87
	v_pk_fma_f32 v[70:71], v[160:161], v[70:71], v[212:213]
	v_pk_fma_f32 v[82:83], v[176:177], v[82:83], v[74:75] op_sel_hi:[0,1,1]
	v_xor_b32_e32 v75, 0x80000000, v215
	v_xor_b32_e32 v74, 0x80000000, v214
	v_xor_b32_e32 v161, 0x80000000, v233
	v_xor_b32_e32 v160, 0x80000000, v232
	v_pk_fma_f32 v[74:75], v[176:177], v[78:79], v[74:75] op_sel_hi:[0,1,1]
	v_pk_fma_f32 v[86:87], v[176:177], v[86:87], v[160:161] op_sel_hi:[0,1,1]
	v_lshlrev_b32_e32 v212, 16, v68
	v_and_b32_e32 v213, 0xffff0000, v68
	s_waitcnt lgkmcnt(1)
	v_pk_fma_f32 v[74:75], v[164:165], v[74:75], v[214:215]
	v_pk_fma_f32 v[78:79], v[166:167], v[82:83], v[228:229]
	v_xor_b32_e32 v83, 0x80000000, v231
	v_xor_b32_e32 v82, 0x80000000, v230
	s_waitcnt lgkmcnt(0)
	v_pk_fma_f32 v[160:161], v[202:203], v[86:87], v[232:233]
	v_lshlrev_b32_e32 v68, 16, v69
	v_and_b32_e32 v69, 0xffff0000, v69
	v_lshlrev_b32_e32 v214, 16, v72
	v_and_b32_e32 v215, 0xffff0000, v72
	v_lshlrev_b32_e32 v232, 16, v73
	v_and_b32_e32 v233, 0xffff0000, v73
	v_lshlrev_b32_e32 v72, 16, v80
	v_and_b32_e32 v73, 0xffff0000, v80
	v_xor_b32_e32 v241, 0x80000000, v213
	v_xor_b32_e32 v240, 0x80000000, v212
	v_pk_fma_f32 v[82:83], v[176:177], v[234:235], v[82:83] op_sel_hi:[0,1,1]
	v_lshlrev_b32_e32 v234, 16, v76
	v_and_b32_e32 v235, 0xffff0000, v76
	v_lshlrev_b32_e32 v236, 16, v77
	v_and_b32_e32 v237, 0xffff0000, v77
	v_lshlrev_b32_e32 v76, 16, v81
	v_and_b32_e32 v77, 0xffff0000, v81
	v_pk_fma_f32 v[72:73], v[176:177], v[72:73], v[240:241] op_sel_hi:[0,1,1]
	v_xor_b32_e32 v241, 0x80000000, v69
	v_xor_b32_e32 v240, 0x80000000, v68
	v_pk_fma_f32 v[162:163], v[200:201], v[82:83], v[230:231]
	ds_read_b128 v[164:167], v223 offset:39040
	ds_read_b128 v[200:203], v223 offset:34960
	ds_read_b128 v[228:231], v223 offset:37008
	v_pk_fma_f32 v[76:77], v[176:177], v[76:77], v[240:241] op_sel_hi:[0,1,1]
	v_lshlrev_b32_e32 v80, 16, v84
	v_and_b32_e32 v81, 0xffff0000, v84
	v_lshlrev_b32_e32 v84, 16, v85
	v_and_b32_e32 v85, 0xffff0000, v85
	v_pk_fma_f32 v[68:69], v[92:93], v[76:77], v[68:69]
	v_xor_b32_e32 v77, 0x80000000, v233
	v_xor_b32_e32 v76, 0x80000000, v232
	v_pk_fma_f32 v[84:85], v[176:177], v[84:85], v[76:77] op_sel_hi:[0,1,1]
	v_xor_b32_e32 v77, 0x80000000, v215
	v_xor_b32_e32 v76, 0x80000000, v214
	v_pk_fma_f32 v[76:77], v[176:177], v[80:81], v[76:77] op_sel_hi:[0,1,1]
	s_waitcnt lgkmcnt(1)
	v_pk_fma_f32 v[76:77], v[200:201], v[76:77], v[214:215]
	v_pk_fma_f32 v[80:81], v[202:203], v[84:85], v[232:233]
	ds_read_b128 v[200:203], v223 offset:39056
	v_pk_mul_f32 v[86:87], v[164:165], v[74:75]
	v_pk_mul_f32 v[82:83], v[166:167], v[78:79]
	v_mul_f32_e32 v164, v86, v86
	v_pk_fma_f32 v[164:165], v[86:87], v[86:87], v[164:165] op_sel_hi:[1,1,0]
	v_lshlrev_b32_e32 v238, 16, v88
	v_and_b32_e32 v239, 0xffff0000, v88
	v_lshlrev_b32_e32 v88, 16, v89
	v_and_b32_e32 v89, 0xffff0000, v89
	v_pk_fma_f32 v[72:73], v[90:91], v[72:73], v[212:213]
	v_xor_b32_e32 v85, 0x80000000, v235
	v_xor_b32_e32 v84, 0x80000000, v234
	v_xor_b32_e32 v91, 0x80000000, v237
	v_xor_b32_e32 v90, 0x80000000, v236
	v_mul_f32_e32 v164, v82, v82
	v_pk_fma_f32 v[84:85], v[176:177], v[238:239], v[84:85] op_sel_hi:[0,1,1]
	v_pk_fma_f32 v[88:89], v[176:177], v[88:89], v[90:91] op_sel_hi:[0,1,1]
	v_pk_fma_f32 v[166:167], v[82:83], v[82:83], v[164:165] op_sel_hi:[1,1,0]
	s_waitcnt lgkmcnt(1)
	v_pk_fma_f32 v[90:91], v[230:231], v[88:89], v[236:237]
	v_pk_fma_f32 v[92:93], v[228:229], v[84:85], v[234:235]
	s_waitcnt lgkmcnt(0)
	v_pk_mul_f32 v[84:85], v[202:203], v[80:81]
	v_pk_mul_f32 v[88:89], v[200:201], v[76:77]
	v_mul_f32_e32 v164, v84, v84
	v_mul_f32_e32 v192, v88, v88
	v_mul_f32_e32 v198, v89, v89
	v_mul_f32_e32 v166, v85, v85
	v_pk_add_f32 v[192:193], v[192:193], v[198:199]
	v_pk_add_f32 v[164:165], v[164:165], v[166:167]
	v_lshl_add_u64 v[166:167], v[182:183], 0, s[6:7]
	v_pk_add_f32 v[164:165], v[192:193], v[164:165]
	v_cvt_pk_bf16_f32 v162, v162, v163
	v_add_f32_e32 v129, v164, v165
	v_cvt_pk_bf16_f32 v163, v160, v161
	v_cvt_pk_bf16_f32 v164, v92, v93
	v_cvt_pk_bf16_f32 v165, v90, v91
	global_store_dwordx4 v[166:167], v[162:165], off
	s_nop 1
	s_mov_b64 s[6:7], 0x240
	v_cvt_pk_bf16_f32 v91, v66, v67
	v_lshl_add_u64 v[160:161], v[182:183], 0, s[6:7]
	v_cvt_pk_bf16_f32 v90, v70, v71
	v_cvt_pk_bf16_f32 v92, v72, v73
	v_cvt_pk_bf16_f32 v93, v68, v69
	global_store_dwordx4 v[160:161], v[90:93], off
	s_nop 1
	v_cvt_pk_bf16_f32 v91, v152, v153
	v_lshl_add_u64 v[160:161], v[182:183], 0, 64
	v_cvt_pk_bf16_f32 v90, v150, v151
	v_cvt_pk_bf16_f32 v92, v156, v157
	v_cvt_pk_bf16_f32 v93, v158, v159
	global_store_dwordx4 v[160:161], v[90:93], off
	s_nop 1
	v_and_b32_e32 v91, 64, v205
	v_xor_b32_e32 v90, 16, v205
	v_add_u32_e32 v91, 64, v91
	v_cmp_lt_i32_e32 vcc, v90, v91
	s_mov_b32 s6, 0xf800000
	v_pk_add_f32 v[166:167], v[148:149], -1.0 op_sel_hi:[1,0]
	v_cndmask_b32_e32 v90, v205, v90, vcc
	v_lshlrev_b32_e32 v131, 2, v90
	s_waitcnt lgkmcnt(0)
	v_mov_b32_e32 v90, v129
	s_nop 1
	v_permlane16_swap_b32_e32 v129, v90
	v_add_f32_e32 v90, v129, v90
	v_mov_b32_e32 v91, v90
	s_nop 1
	v_permlane32_swap_b32_e32 v90, v91
	v_add_f32_e32 v90, v90, v91
	v_cmp_gt_f32_e32 vcc, s6, v90
	v_mul_f32_e32 v91, 0x4f800000, v90
	s_nop 0
	v_cndmask_b32_e32 v90, v90, v91, vcc
	v_sqrt_f32_e32 v91, v90
	s_nop 0
	v_add_u32_e32 v92, -1, v91
	v_fma_f32 v93, -v92, v91, v90
	v_cmp_ge_f32_e64 s[46:47], 0, v93
	v_add_u32_e32 v93, 1, v91
	s_nop 0
	v_cndmask_b32_e64 v92, v91, v92, s[46:47]
	v_fma_f32 v91, -v93, v91, v90
	v_cmp_lt_f32_e64 s[46:47], 0, v91
	s_nop 1
	v_cndmask_b32_e64 v91, v92, v93, s[46:47]
	v_mul_f32_e32 v92, 0x37800000, v91
	v_cndmask_b32_e32 v91, v91, v92, vcc
	v_cmp_class_f32_e32 vcc, v90, v207
	s_nop 1
	v_cndmask_b32_e32 v90, v91, v90, vcc
	v_max_f32_e32 v90, 0x2b8cbccc, v90
	v_div_scale_f32 v91, s[6:7], v90, v90, 1.0
	v_rcp_f32_e32 v92, v91
	s_mov_b64 s[6:7], 0x180
	v_fma_f32 v93, -v91, v92, 1.0
	v_fmac_f32_e32 v92, v93, v92
	v_div_scale_f32 v93, vcc, 1.0, v90, 1.0
	v_mul_f32_e32 v129, v93, v92
	v_fma_f32 v150, -v91, v129, v93
	v_fmac_f32_e32 v129, v150, v92
	v_fma_f32 v91, -v91, v129, v93
	v_div_fmas_f32 v91, v91, v92, v129
	v_div_fixup_f32 v160, v91, v90, 1.0
	ds_read_b128 v[90:93], v223 offset:40960
	ds_read_b128 v[150:153], v223 offset:40976
	ds_read_b128 v[156:159], v223 offset:43008
	v_pk_mul_f32 v[162:163], v[178:179], v[160:161] op_sel_hi:[1,0]
	v_pk_add_f32 v[178:179], v[146:147], -1.0 op_sel_hi:[1,0]
	s_waitcnt lgkmcnt(2)
	v_pk_fma_f32 v[92:93], v[166:167], v[92:93], 1.0 op_sel_hi:[1,1,0]
	v_pk_fma_f32 v[90:91], v[178:179], v[90:91], 1.0 op_sel_hi:[1,1,0]
	v_pk_mul_f32 v[166:167], v[172:173], v[92:93]
	v_pk_mul_f32 v[172:173], v[174:175], v[90:91]
	v_pk_mul_f32 v[92:93], v[168:169], v[166:167]
	v_pk_mul_f32 v[90:91], v[170:171], v[172:173]
	s_waitcnt lgkmcnt(0)
	v_pk_mul_f32 v[92:93], v[158:159], v[92:93]
	v_pk_mul_f32 v[90:91], v[156:157], v[90:91]
	v_pk_mul_f32 v[164:165], v[180:181], v[160:161] op_sel_hi:[1,0]
	v_add_f32_e32 v90, v90, v91
	v_add_f32_e32 v91, v92, v93
	v_add_f32_e32 v90, v90, v91
	v_add_f32_e32 v129, 0, v90
	ds_read_b128 v[90:93], v223 offset:43024
	v_xor_b32_e32 v161, 0x80000000, v165
	v_xor_b32_e32 v168, 0x80000000, v164
	v_xor_b32_e32 v169, 0x80000000, v163
	v_xor_b32_e32 v170, 0x80000000, v162
	v_pk_mul_f32 v[148:149], v[148:149], v[164:165]
	v_pk_mul_f32 v[146:147], v[146:147], v[162:163]
	v_pk_add_f32 v[162:163], v[144:145], -1.0 op_sel_hi:[1,0]
	v_pk_add_f32 v[164:165], v[142:143], -1.0 op_sel_hi:[1,0]
	v_pk_fma_f32 v[152:153], v[162:163], v[152:153], 1.0 op_sel_hi:[1,1,0]
	v_pk_fma_f32 v[150:151], v[164:165], v[150:151], 1.0 op_sel_hi:[1,1,0]
	v_pk_mul_f32 v[152:153], v[188:189], v[152:153]
	v_pk_mul_f32 v[150:151], v[190:191], v[150:151]
	v_pk_mul_f32 v[164:165], v[184:185], v[152:153]
	v_pk_mul_f32 v[162:163], v[186:187], v[150:151]
	s_waitcnt lgkmcnt(0)
	v_pk_mul_f32 v[92:93], v[92:93], v[164:165]
	v_pk_mul_f32 v[90:91], v[90:91], v[162:163]
	v_pk_mul_f32 v[156:157], v[194:195], v[160:161] op_sel_hi:[1,0]
	v_add_f32_e32 v90, v90, v91
	v_add_f32_e32 v91, v92, v93
	v_pk_mul_f32 v[158:159], v[196:197], v[160:161] op_sel_hi:[1,0]
	v_add_f32_e32 v90, v90, v91
	v_add_f32_e32 v129, v129, v90
	v_xor_b32_e32 v162, 0x80000000, v159
	v_xor_b32_e32 v163, 0x80000000, v158
	v_xor_b32_e32 v164, 0x80000000, v157
	v_xor_b32_e32 v165, 0x80000000, v156
	v_pk_mul_f32 v[142:143], v[142:143], v[156:157]
	v_lshl_add_u64 v[156:157], v[182:183], 0, s[30:31]
	v_cvt_pk_bf16_f32 v90, v172, v173
	v_cvt_pk_bf16_f32 v91, v166, v167
	v_cvt_pk_bf16_f32 v92, v150, v151
	v_cvt_pk_bf16_f32 v93, v152, v153
	global_store_dwordx4 v[156:157], v[90:93], off
	s_nop 1
	v_pk_mul_f32 v[144:145], v[144:145], v[158:159]
	v_lshl_add_u64 v[150:151], v[182:183], 0, s[34:35]
	v_cvt_pk_bf16_f32 v90, v170, v169
	v_cvt_pk_bf16_f32 v91, v168, v161
	v_cvt_pk_bf16_f32 v92, v165, v164
	v_cvt_pk_bf16_f32 v93, v163, v162
	global_store_dwordx4 v[150:151], v[90:93], off
	s_nop 1
	v_lshl_add_u64 v[150:151], v[182:183], 0, s[6:7]
	v_cvt_pk_bf16_f32 v90, v146, v147
	v_cvt_pk_bf16_f32 v91, v148, v149
	v_cvt_pk_bf16_f32 v92, v142, v143
	v_cvt_pk_bf16_f32 v93, v144, v145
	global_store_dwordx4 v[150:151], v[90:93], off
	s_nop 1
	ds_read_b128 v[90:93], v223 offset:41088
	ds_read_b128 v[142:145], v223 offset:41104
	ds_read_b128 v[146:149], v223 offset:43136
	v_pk_add_f32 v[150:151], v[140:141], -1.0 op_sel_hi:[1,0]
	v_pk_add_f32 v[152:153], v[138:139], -1.0 op_sel_hi:[1,0]
	s_waitcnt lgkmcnt(2)
	v_pk_fma_f32 v[92:93], v[150:151], v[92:93], 1.0 op_sel_hi:[1,1,0]
	v_pk_fma_f32 v[90:91], v[152:153], v[90:91], 1.0 op_sel_hi:[1,1,0]
	v_pk_mul_f32 v[78:79], v[78:79], v[92:93]
	v_pk_mul_f32 v[74:75], v[74:75], v[90:91]
	v_pk_mul_f32 v[66:67], v[66:67], v[78:79]
	v_pk_mul_f32 v[70:71], v[70:71], v[74:75]
	s_waitcnt lgkmcnt(0)
	v_pk_mul_f32 v[66:67], v[148:149], v[66:67]
	v_pk_mul_f32 v[70:71], v[146:147], v[70:71]
	v_add_f32_e32 v66, v66, v67
	v_add_f32_e32 v70, v70, v71
	v_pk_mul_f32 v[82:83], v[82:83], v[160:161] op_sel_hi:[1,0]
	v_add_f32_e32 v66, v70, v66
	v_add_f32_e32 v129, v129, v66
	v_xor_b32_e32 v146, 0x80000000, v83
	v_xor_b32_e32 v147, 0x80000000, v82
	v_pk_mul_f32 v[70:71], v[140:141], v[82:83]
	v_pk_mul_f32 v[66:67], v[88:89], v[160:161] op_sel_hi:[1,0]
	v_pk_mul_f32 v[88:89], v[84:85], v[160:161] op_sel_hi:[1,0]
	ds_read_b128 v[82:85], v223 offset:43152
	v_pk_add_f32 v[90:91], v[136:137], -1.0 op_sel_hi:[1,0]
	v_pk_add_f32 v[92:93], v[134:135], -1.0 op_sel_hi:[1,0]
	v_pk_fma_f32 v[90:91], v[90:91], v[144:145], 1.0 op_sel_hi:[1,1,0]
	v_pk_fma_f32 v[92:93], v[92:93], v[142:143], 1.0 op_sel_hi:[1,1,0]
	v_pk_mul_f32 v[80:81], v[80:81], v[90:91]
	v_pk_mul_f32 v[76:77], v[76:77], v[92:93]
	v_pk_mul_f32 v[68:69], v[68:69], v[80:81]
	v_pk_mul_f32 v[72:73], v[72:73], v[76:77]
	s_waitcnt lgkmcnt(0)
	v_pk_mul_f32 v[68:69], v[84:85], v[68:69]
	v_pk_mul_f32 v[72:73], v[82:83], v[72:73]
	v_add_f32_e32 v68, v68, v69
	v_add_f32_e32 v72, v72, v73
	v_pk_mul_f32 v[86:87], v[86:87], v[160:161] op_sel_hi:[1,0]
	v_add_f32_e32 v68, v72, v68
	v_xor_b32_e32 v148, 0x80000000, v87
	v_xor_b32_e32 v149, 0x80000000, v86
	v_add_f32_e32 v90, v129, v68
	v_xor_b32_e32 v129, 0x80000000, v66
	v_pk_mul_f32 v[82:83], v[134:135], v[66:67]
	s_mov_b64 s[6:7], 0xc0
	v_cvt_pk_bf16_f32 v66, v74, v75
	v_pk_mul_f32 v[86:87], v[138:139], v[86:87]
	v_xor_b32_e32 v91, 0x80000000, v89
	v_xor_b32_e32 v92, 0x80000000, v88
	v_xor_b32_e32 v93, 0x80000000, v67
	v_lshl_add_u64 v[84:85], v[182:183], 0, s[6:7]
	v_cvt_pk_bf16_f32 v67, v78, v79
	v_cvt_pk_bf16_f32 v68, v76, v77
	v_cvt_pk_bf16_f32 v69, v80, v81
	global_store_dwordx4 v[84:85], v[66:69], off
	s_nop 1
	s_mov_b64 s[6:7], 0x140
	v_cvt_pk_bf16_f32 v66, v149, v148
	v_pk_mul_f32 v[72:73], v[136:137], v[88:89]
	v_lshl_add_u64 v[74:75], v[182:183], 0, s[6:7]
	v_cvt_pk_bf16_f32 v67, v147, v146
	v_cvt_pk_bf16_f32 v68, v129, v93
	v_cvt_pk_bf16_f32 v69, v92, v91
	global_store_dwordx4 v[74:75], v[66:69], off
	s_nop 1
	s_mov_b64 s[6:7], 0x1c0
	v_cvt_pk_bf16_f32 v66, v86, v87
	v_lshl_add_u64 v[74:75], v[182:183], 0, s[6:7]
	v_cvt_pk_bf16_f32 v67, v70, v71
	v_cvt_pk_bf16_f32 v68, v82, v83
	v_cvt_pk_bf16_f32 v69, v72, v73
	global_store_dwordx4 v[74:75], v[66:69], off
	s_nop 1
	ds_bpermute_b32 v66, v131, v90
	s_waitcnt lgkmcnt(0)
	v_add_f32_e32 v66, v90, v66
	v_mov_b32_e32 v67, v66
	s_nop 1
	v_permlane32_swap_b32_e32 v66, v67
	s_and_saveexec_b64 s[46:47], s[44:45]
	s_cbranch_execz .LBB0_912
	v_add_f32_e32 v68, v66, v67
	v_lshlrev_b64 v[66:67], 5, v[132:133]
	v_lshl_add_u64 v[66:67], s[58:59], 0, v[66:67]
	global_store_dword v[66:67], v68, off
.LBB0_912:
	s_or_b64 exec, exec, s[46:47]
	ds_read_b128 v[70:73], v224 offset:8448
	v_add_u32_e32 v66, 16, v132
	v_ashrrev_i32_e32 v67, 31, v66
	s_mov_b64 s[6:7], 0x7800400
	v_or_b32_e32 v68, 16, v128
	s_waitcnt lgkmcnt(0)
	v_mfma_f32_16x16x32_bf16 v[44:47], v[44:47], v[70:73], 0
	v_ashrrev_i32_e32 v69, 31, v68
	v_cmp_lt_i32_e32 vcc, -1, v227
	v_mfma_f32_16x16x32_bf16 v[50:53], v[50:53], v[70:73], 0
	s_nop 0
	v_cndmask_b32_e32 v128, 0, v210, vcc
	v_mfma_f32_16x16x32_bf16 v[54:57], v[54:57], v[70:73], 0
	v_mfma_f32_16x16x32_bf16 v[58:61], v[58:61], v[70:73], 0
	ds_read_b128 v[70:73], v224 offset:8512
	s_waitcnt lgkmcnt(0)
	v_mfma_f32_16x16x32_bf16 v[32:35], v[32:35], v[70:73], v[44:47]
	v_mfma_f32_16x16x32_bf16 v[36:39], v[36:39], v[70:73], v[50:53]
	v_mfma_f32_16x16x32_bf16 v[50:53], v[62:65], v[70:73], v[58:61]
	s_nop 0
	ds_read_b128 v[44:47], v222 offset:45056
	s_nop 0
	ds_read_b128 v[58:61], v222 offset:45072
	s_waitcnt lgkmcnt(1)
	s_nop 0
	v_add_f32_e32 v32, v32, v44
	v_add_f32_e32 v33, v33, v45
	v_mul_f32_e32 v32, 0xbfb8aa3b, v32
	v_mul_f32_e32 v33, 0xbfb8aa3b, v33
	v_exp_f32_e32 v32, v32
	v_exp_f32_e32 v33, v33
	v_mfma_f32_16x16x32_bf16 v[40:43], v[40:43], v[70:73], v[54:57]
	v_cndmask_b32_e64 v72, 0, 1.0, vcc
	v_add_f32_e32 v32, 1.0, v32
	v_add_f32_e32 v33, 1.0, v33
	v_rcp_f32_e32 v32, v32
	v_rcp_f32_e32 v33, v33
	s_nop 0
	v_pk_mul_f32 v[54:55], v[32:33], s[72:73] op_sel_hi:[1,0]
	v_add_f32_e32 v32, v34, v46
	v_add_f32_e32 v33, v35, v47
	v_mul_f32_e32 v32, 0xbfb8aa3b, v32
	v_mul_f32_e32 v33, 0xbfb8aa3b, v33
	v_exp_f32_e32 v32, v32
	v_exp_f32_e32 v33, v33
	v_add_f32_e32 v32, 1.0, v32
	v_add_f32_e32 v33, 1.0, v33
	v_rcp_f32_e32 v32, v32
	v_rcp_f32_e32 v33, v33
	s_nop 0
	v_pk_mul_f32 v[56:57], v[32:33], s[72:73] op_sel_hi:[1,0]
	s_waitcnt lgkmcnt(0)
	v_add_f32_e32 v32, v36, v58
	v_add_f32_e32 v33, v37, v59
	v_mul_f32_e32 v32, 0xbfb8aa3b, v32
	v_mul_f32_e32 v33, 0xbfb8aa3b, v33
	v_exp_f32_e32 v32, v32
	v_exp_f32_e32 v33, v33
	v_add_f32_e32 v32, 1.0, v32
	v_add_f32_e32 v33, 1.0, v33
	v_rcp_f32_e32 v32, v32
	v_rcp_f32_e32 v33, v33
	s_nop 0
	v_pk_mul_f32 v[58:59], v[32:33], s[72:73] op_sel_hi:[1,0]
	v_add_f32_e32 v32, v38, v60
	v_add_f32_e32 v33, v39, v61
	v_mul_f32_e32 v32, 0xbfb8aa3b, v32
	v_mul_f32_e32 v33, 0xbfb8aa3b, v33
	v_exp_f32_e32 v32, v32
	v_exp_f32_e32 v33, v33
	v_add_f32_e32 v32, 1.0, v32
	v_add_f32_e32 v33, 1.0, v33
	v_rcp_f32_e32 v32, v32
	v_rcp_f32_e32 v33, v33
	s_nop 0
	v_pk_mul_f32 v[60:61], v[32:33], s[72:73] op_sel_hi:[1,0]
	ds_read_b128 v[32:35], v222 offset:45184
	s_waitcnt lgkmcnt(0)
	v_add_f32_e32 v32, v40, v32
	v_add_f32_e32 v33, v41, v33
	v_mul_f32_e32 v32, 0xbfb8aa3b, v32
	v_mul_f32_e32 v33, 0xbfb8aa3b, v33
	v_exp_f32_e32 v32, v32
	v_exp_f32_e32 v33, v33
	v_add_f32_e32 v32, 1.0, v32
	v_add_f32_e32 v33, 1.0, v33
	v_rcp_f32_e32 v32, v32
	v_rcp_f32_e32 v33, v33
	s_nop 0
	v_pk_mul_f32 v[44:45], v[32:33], s[72:73] op_sel_hi:[1,0]
	v_add_f32_e32 v32, v42, v34
	v_add_f32_e32 v33, v43, v35
	v_mul_f32_e32 v32, 0xbfb8aa3b, v32
	v_mul_f32_e32 v33, 0xbfb8aa3b, v33
	v_exp_f32_e32 v32, v32
	v_exp_f32_e32 v33, v33
	v_add_f32_e32 v32, 1.0, v32
	v_add_f32_e32 v33, 1.0, v33
	v_rcp_f32_e32 v32, v32
	v_rcp_f32_e32 v33, v33
	s_nop 0
	v_pk_mul_f32 v[46:47], v[32:33], s[72:73] op_sel_hi:[1,0]
	ds_read_b128 v[32:35], v222 offset:45200
	s_waitcnt lgkmcnt(0)
	v_add_f32_e32 v32, v50, v32
	v_add_f32_e32 v33, v51, v33
	v_mul_f32_e32 v32, 0xbfb8aa3b, v32
	v_mul_f32_e32 v33, 0xbfb8aa3b, v33
	v_exp_f32_e32 v32, v32
	v_exp_f32_e32 v33, v33
	v_add_f32_e32 v32, 1.0, v32
	v_add_f32_e32 v33, 1.0, v33
	v_rcp_f32_e32 v32, v32
	v_rcp_f32_e32 v33, v33
	s_nop 0
	v_pk_mul_f32 v[50:51], v[32:33], s[72:73] op_sel_hi:[1,0]
	v_add_f32_e32 v32, v52, v34
	v_add_f32_e32 v33, v53, v35
	v_mul_f32_e32 v32, 0xbfb8aa3b, v32
	v_mul_f32_e32 v33, 0xbfb8aa3b, v33
	v_exp_f32_e32 v32, v32
	v_exp_f32_e32 v33, v33
	v_add_f32_e32 v32, 1.0, v32
	v_add_f32_e32 v33, 1.0, v33
	v_rcp_f32_e32 v32, v32
	v_rcp_f32_e32 v33, v33
	s_nop 0
	v_pk_mul_f32 v[52:53], v[32:33], s[72:73] op_sel_hi:[1,0]
	ds_read_b128 v[32:35], v224 offset:8576
	s_waitcnt lgkmcnt(0)
	v_mfma_f32_16x16x32_bf16 v[0:3], v[0:3], v[32:35], 0
	v_mfma_f32_16x16x32_bf16 v[4:7], v[4:7], v[32:35], 0
	v_mfma_f32_16x16x32_bf16 v[8:11], v[8:11], v[32:35], 0
	v_mfma_f32_16x16x32_bf16 v[12:15], v[12:15], v[32:35], 0
	ds_read_b128 v[32:35], v224 offset:8640
	s_waitcnt lgkmcnt(0)
	v_mfma_f32_16x16x32_bf16 v[0:3], v[16:19], v[32:35], v[0:3]
	ds_read_b128 v[16:19], v222 offset:47104
	v_mfma_f32_16x16x32_bf16 v[4:7], v[20:23], v[32:35], v[4:7]
	global_load_dwordx4 v[20:23], v[112:113], off offset:64
	s_waitcnt lgkmcnt(0)
	s_nop 3
	v_add_f32_e32 v0, v0, v16
	v_mul_f32_e32 v0, 0xbfb8aa3b, v0
	v_exp_f32_e32 v0, v0
	v_mfma_f32_16x16x32_bf16 v[8:11], v[24:27], v[32:35], v[8:11]
	v_add_f32_e32 v0, 1.0, v0
	v_rcp_f32_e32 v40, v0
	v_add_f32_e32 v0, v1, v17
	v_mul_f32_e32 v0, 0xbfb8aa3b, v0
	v_exp_f32_e32 v0, v0
	v_mfma_f32_16x16x32_bf16 v[12:15], v[28:31], v[32:35], v[12:15]
	v_add_f32_e32 v0, 1.0, v0
	v_rcp_f32_e32 v41, v0
	v_add_f32_e32 v0, v2, v18
	v_mul_f32_e32 v0, 0xbfb8aa3b, v0
	v_exp_f32_e32 v0, v0
	s_nop 0
	v_add_f32_e32 v0, 1.0, v0
	v_rcp_f32_e32 v42, v0
	v_add_f32_e32 v0, v3, v19
	v_mul_f32_e32 v0, 0xbfb8aa3b, v0
	v_exp_f32_e32 v0, v0
	global_load_dwordx4 v[16:19], v[118:119], off
	v_add_f32_e32 v0, 1.0, v0
	v_rcp_f32_e32 v43, v0
	ds_read_b128 v[0:3], v222 offset:47120
	s_waitcnt lgkmcnt(0)
	v_add_f32_e32 v0, v4, v0
	v_mul_f32_e32 v0, 0xbfb8aa3b, v0
	v_exp_f32_e32 v0, v0
	s_nop 0
	v_add_f32_e32 v0, 1.0, v0
	v_rcp_f32_e32 v36, v0
	v_add_f32_e32 v0, v5, v1
	v_mul_f32_e32 v0, 0xbfb8aa3b, v0
	v_exp_f32_e32 v0, v0
	s_nop 0
	v_add_f32_e32 v0, 1.0, v0
	v_rcp_f32_e32 v37, v0
	v_add_f32_e32 v0, v6, v2
	v_mul_f32_e32 v0, 0xbfb8aa3b, v0
	v_exp_f32_e32 v0, v0
	s_nop 0
	v_add_f32_e32 v0, 1.0, v0
	v_rcp_f32_e32 v38, v0
	v_add_f32_e32 v0, v7, v3
	v_mul_f32_e32 v0, 0xbfb8aa3b, v0
	v_exp_f32_e32 v0, v0
	global_load_dwordx4 v[4:7], v[112:113], off
	v_add_f32_e32 v0, 1.0, v0
	v_rcp_f32_e32 v39, v0
	ds_read_b128 v[0:3], v222 offset:47232
	s_waitcnt lgkmcnt(0)
	v_add_f32_e32 v0, v8, v0
	v_mul_f32_e32 v0, 0xbfb8aa3b, v0
	v_exp_f32_e32 v0, v0
	s_nop 0
	v_add_f32_e32 v0, 1.0, v0
	v_rcp_f32_e32 v32, v0
	v_add_f32_e32 v0, v9, v1
	v_mul_f32_e32 v0, 0xbfb8aa3b, v0
	v_exp_f32_e32 v0, v0
	s_nop 0
	v_add_f32_e32 v0, 1.0, v0
	v_rcp_f32_e32 v33, v0
	v_add_f32_e32 v0, v10, v2
	v_mul_f32_e32 v0, 0xbfb8aa3b, v0
	v_exp_f32_e32 v0, v0
	s_nop 0
	v_add_f32_e32 v0, 1.0, v0
	v_rcp_f32_e32 v34, v0
	v_add_f32_e32 v0, v11, v3
	v_mul_f32_e32 v0, 0xbfb8aa3b, v0
	v_exp_f32_e32 v0, v0
	global_load_dwordx4 v[8:11], v[114:115], off
	v_add_f32_e32 v0, 1.0, v0
	v_rcp_f32_e32 v35, v0
	ds_read_b128 v[0:3], v222 offset:47248
	s_waitcnt lgkmcnt(0)
	v_add_f32_e32 v0, v12, v0
	v_mul_f32_e32 v0, 0xbfb8aa3b, v0
	v_exp_f32_e32 v0, v0
	s_nop 0
	v_add_f32_e32 v0, 1.0, v0
	v_rcp_f32_e32 v28, v0
	v_add_f32_e32 v0, v13, v1
	v_mul_f32_e32 v0, 0xbfb8aa3b, v0
	v_exp_f32_e32 v0, v0
	s_nop 0
	v_add_f32_e32 v0, 1.0, v0
	v_rcp_f32_e32 v29, v0
	v_add_f32_e32 v0, v14, v2
	v_mul_f32_e32 v0, 0xbfb8aa3b, v0
	v_exp_f32_e32 v0, v0
	s_nop 0
	v_add_f32_e32 v0, 1.0, v0
	v_rcp_f32_e32 v30, v0
	v_add_f32_e32 v0, v15, v3
	global_load_dwordx4 v[12:15], v[116:117], off
	v_mul_f32_e32 v0, 0xbfb8aa3b, v0
	v_exp_f32_e32 v0, v0
	s_nop 0
	v_add_f32_e32 v0, 1.0, v0
	v_rcp_f32_e32 v31, v0
	ds_read_b128 v[0:3], v224 offset:8704
	s_waitcnt vmcnt(2) lgkmcnt(0)
	v_mfma_f32_16x16x32_bf16 v[4:7], v[4:7], v[0:3], 0
	s_waitcnt vmcnt(1)
	v_mfma_f32_16x16x32_bf16 v[8:11], v[8:11], v[0:3], 0
	s_waitcnt vmcnt(0)
	v_mfma_f32_16x16x32_bf16 v[12:15], v[12:15], v[0:3], 0
	v_mfma_f32_16x16x32_bf16 v[0:3], v[16:19], v[0:3], 0
	ds_read_b128 v[16:19], v224 offset:8768
	s_waitcnt lgkmcnt(0)
	v_mfma_f32_16x16x32_bf16 v[4:7], v[20:23], v[16:19], v[4:7]
	global_load_dwordx4 v[20:23], v[114:115], off offset:64
	s_waitcnt vmcnt(0)
	v_mfma_f32_16x16x32_bf16 v[8:11], v[20:23], v[16:19], v[8:11]
	global_load_dwordx4 v[20:23], v[116:117], off offset:64
	s_waitcnt vmcnt(0)
	v_mfma_f32_16x16x32_bf16 v[12:15], v[20:23], v[16:19], v[12:15]
	global_load_dwordx4 v[20:23], v[118:119], off offset:64
	s_waitcnt vmcnt(0)
	v_mfma_f32_16x16x32_bf16 v[0:3], v[20:23], v[16:19], v[0:3]
	global_load_dwordx4 v[20:23], v[112:113], off offset:128
	ds_read_b128 v[16:19], v224 offset:8832
	s_waitcnt vmcnt(0) lgkmcnt(0)
	v_mfma_f32_16x16x32_bf16 v[20:23], v[20:23], v[16:19], v[4:7]
	s_nop 2
	global_load_dwordx4 v[4:7], v[114:115], off offset:128
	s_waitcnt vmcnt(0)
	v_mfma_f32_16x16x32_bf16 v[24:27], v[4:7], v[16:19], v[8:11]
	global_load_dwordx4 v[4:7], v[116:117], off offset:128
	s_nop 1
	global_load_dwordx4 v[8:11], v[112:113], off offset:192
	s_waitcnt vmcnt(1)
	v_mfma_f32_16x16x32_bf16 v[62:65], v[4:7], v[16:19], v[12:15]
	global_load_dwordx4 v[4:7], v[118:119], off offset:128
	s_nop 1
	global_load_dwordx4 v[12:15], v[114:115], off offset:192
	s_waitcnt vmcnt(1)
	v_mfma_f32_16x16x32_bf16 v[0:3], v[4:7], v[16:19], v[0:3]
	ds_read_b128 v[4:7], v224 offset:8896
	global_load_dwordx4 v[16:19], v[116:117], off offset:192
	s_waitcnt lgkmcnt(0)
	v_mfma_f32_16x16x32_bf16 v[8:11], v[8:11], v[4:7], v[20:23]
	s_nop 2
	global_load_dwordx4 v[20:23], v[118:119], off offset:192
	s_waitcnt vmcnt(2)
	v_mfma_f32_16x16x32_bf16 v[12:15], v[12:15], v[4:7], v[24:27]
	s_waitcnt vmcnt(1)
	v_mfma_f32_16x16x32_bf16 v[16:19], v[16:19], v[4:7], v[62:65]
	s_waitcnt vmcnt(0)
	v_mfma_f32_16x16x32_bf16 v[0:3], v[20:23], v[4:7], v[0:3]
	v_lshlrev_b64 v[4:5], 11, v[66:67]
	v_lshl_add_u64 v[4:5], s[2:3], 0, v[4:5]
	v_lshl_add_u64 v[4:5], s[56:57], 1, v[4:5]
	v_lshl_add_u64 v[20:21], v[4:5], 0, v[48:49]
	v_lshl_add_u64 v[22:23], v[20:21], 0, s[6:7]
	v_cvt_pk_bf16_f32 v6, v12, v13
	s_mov_b64 s[6:7], 0x7800440
	v_cvt_pk_bf16_f32 v4, v8, v9
	v_cvt_pk_bf16_f32 v5, v10, v11
	v_cvt_pk_bf16_f32 v7, v14, v15
	global_store_dwordx4 v[22:23], v[4:7], off
	s_nop 1
	v_cvt_pk_bf16_f32 v6, v0, v1
	v_lshl_add_u64 v[0:1], v[20:21], 0, s[6:7]
	v_cvt_pk_bf16_f32 v4, v16, v17
	v_cvt_pk_bf16_f32 v5, v18, v19
	v_cvt_pk_bf16_f32 v7, v2, v3
	global_store_dwordx4 v[0:1], v[4:7], off
	s_nop 1
	v_lshl_add_u64 v[0:1], v[126:127], 0, v[68:69]
	v_mov_b64_e32 v[2:3], s[54:55]
	v_mad_u64_u32 v[78:79], s[6:7], v0, s95, v[2:3]
	v_mad_i32_i24 v79, v1, s95, v79
	v_mov_b64_e32 v[0:1], s[12:13]
	v_mad_i64_i32 v[132:133], s[6:7], v66, s19, v[0:1]
	v_ashrrev_i32_e32 v0, 31, v227
	v_not_b32_e32 v129, v0
	v_lshl_add_u64 v[12:13], v[120:121], 1, v[132:133]
	s_mov_b64 s[6:7], 0x800
	v_lshl_add_u64 v[8:9], v[12:13], 0, s[6:7]
	v_lshl_add_u64 v[16:17], v[12:13], 0, v[128:129]
	global_load_dwordx4 v[4:7], v[12:13], off offset:2048
	global_load_dwordx4 v[0:3], v[12:13], off offset:3072
	s_nop 0
	global_load_dwordx4 v[8:11], v[8:9], off offset:2048
	v_lshl_add_u64 v[20:21], v[16:17], 0, s[6:7]
	global_load_dwordx4 v[12:15], v[16:17], off offset:2048
	s_nop 0
	global_load_dwordx4 v[16:19], v[16:17], off offset:3072
	s_nop 0
	global_load_dwordx4 v[20:23], v[20:21], off offset:2048
	ds_read_b128 v[68:71], v223 offset:32768
	ds_read_b128 v[24:27], v223 offset:32784
	ds_read_b128 v[74:77], v223 offset:34816
	ds_read_b128 v[80:83], v223 offset:36864
	v_lshl_add_u64 v[78:79], v[78:79], 0, v[48:49]
	s_mov_b64 s[6:7], 0x280
	s_waitcnt vmcnt(5)
	v_lshlrev_b32_e32 v64, 16, v4
	v_and_b32_e32 v65, 0xffff0000, v4
	v_lshlrev_b32_e32 v4, 16, v5
	v_and_b32_e32 v5, 0xffff0000, v5
	s_waitcnt vmcnt(2)
	v_lshlrev_b32_e32 v62, 16, v12
	v_and_b32_e32 v63, 0xffff0000, v12
	v_xor_b32_e32 v93, 0x80000000, v65
	v_xor_b32_e32 v92, 0x80000000, v64
	v_lshlrev_b32_e32 v12, 16, v13
	v_and_b32_e32 v13, 0xffff0000, v13
	v_pk_fma_f32 v[92:93], v[72:73], v[62:63], v[92:93] op_sel_hi:[0,1,1]
	v_xor_b32_e32 v63, 0x80000000, v5
	v_xor_b32_e32 v62, 0x80000000, v4
	v_lshlrev_b32_e32 v84, 16, v0
	v_and_b32_e32 v85, 0xffff0000, v0
	v_lshlrev_b32_e32 v0, 16, v1
	v_and_b32_e32 v1, 0xffff0000, v1
	v_pk_fma_f32 v[12:13], v[72:73], v[12:13], v[62:63] op_sel_hi:[0,1,1]
	s_waitcnt vmcnt(1)
	v_lshlrev_b32_e32 v88, 16, v16
	v_and_b32_e32 v89, 0xffff0000, v16
	v_lshlrev_b32_e32 v16, 16, v17
	v_and_b32_e32 v17, 0xffff0000, v17
	s_waitcnt lgkmcnt(3)
	v_pk_fma_f32 v[62:63], v[70:71], v[12:13], v[4:5]
	v_xor_b32_e32 v5, 0x80000000, v85
	v_xor_b32_e32 v4, 0x80000000, v84
	v_xor_b32_e32 v13, 0x80000000, v1
	v_xor_b32_e32 v12, 0x80000000, v0
	v_pk_fma_f32 v[4:5], v[72:73], v[88:89], v[4:5] op_sel_hi:[0,1,1]
	v_pk_fma_f32 v[12:13], v[72:73], v[16:17], v[12:13] op_sel_hi:[0,1,1]
	v_pk_fma_f32 v[64:65], v[68:69], v[92:93], v[64:65]
	s_waitcnt lgkmcnt(1)
	v_pk_fma_f32 v[68:69], v[76:77], v[12:13], v[0:1]
	v_pk_fma_f32 v[70:71], v[74:75], v[4:5], v[84:85]
	ds_read_b128 v[74:77], v223 offset:38912
	v_lshlrev_b32_e32 v86, 16, v8
	v_and_b32_e32 v87, 0xffff0000, v8
	v_lshlrev_b32_e32 v8, 16, v9
	v_and_b32_e32 v9, 0xffff0000, v9
	s_waitcnt vmcnt(0)
	v_lshlrev_b32_e32 v90, 16, v20
	v_and_b32_e32 v91, 0xffff0000, v20
	v_xor_b32_e32 v1, 0x80000000, v87
	v_xor_b32_e32 v0, 0x80000000, v86
	v_lshlrev_b32_e32 v20, 16, v21
	v_and_b32_e32 v21, 0xffff0000, v21
	v_pk_fma_f32 v[4:5], v[72:73], v[90:91], v[0:1] op_sel_hi:[0,1,1]
	v_xor_b32_e32 v1, 0x80000000, v9
	v_xor_b32_e32 v0, 0x80000000, v8
	v_pk_fma_f32 v[0:1], v[72:73], v[20:21], v[0:1] op_sel_hi:[0,1,1]
	s_waitcnt lgkmcnt(0)
	v_pk_mul_f32 v[74:75], v[74:75], v[70:71]
	v_pk_mul_f32 v[76:77], v[76:77], v[68:69]
	v_pk_fma_f32 v[0:1], v[82:83], v[0:1], v[8:9]
	v_pk_mul_f32 v[8:9], v[76:77], v[76:77]
	v_pk_mul_f32 v[12:13], v[74:75], v[74:75]
	v_lshlrev_b32_e32 v20, 16, v6
	v_pk_mov_b32 v[16:17], v[12:13], v[8:9] op_sel:[1,0]
	v_mov_b32_e32 v13, v9
	v_pk_add_f32 v[8:9], v[16:17], v[12:13]
	v_and_b32_e32 v21, 0xffff0000, v6
	v_pk_fma_f32 v[4:5], v[80:81], v[4:5], v[86:87]
	v_pk_add_f32 v[88:89], v[8:9], v[8:9] op_sel_hi:[0,1]
	v_lshlrev_b32_e32 v80, 16, v7
	v_and_b32_e32 v81, 0xffff0000, v7
	v_lshlrev_b32_e32 v86, 16, v2
	v_and_b32_e32 v87, 0xffff0000, v2
	v_lshlrev_b32_e32 v84, 16, v3
	v_and_b32_e32 v85, 0xffff0000, v3
	v_lshlrev_b32_e32 v2, 16, v10
	v_and_b32_e32 v3, 0xffff0000, v10
	v_lshlrev_b32_e32 v6, 16, v11
	v_and_b32_e32 v7, 0xffff0000, v11
	v_lshlrev_b32_e32 v82, 16, v14
	v_and_b32_e32 v83, 0xffff0000, v14
	v_lshlrev_b32_e32 v10, 16, v22
	v_and_b32_e32 v11, 0xffff0000, v22
	v_lshlrev_b32_e32 v8, 16, v23
	v_and_b32_e32 v9, 0xffff0000, v23
	v_xor_b32_e32 v23, 0x80000000, v21
	v_xor_b32_e32 v22, 0x80000000, v20
	v_lshlrev_b32_e32 v90, 16, v15
	v_and_b32_e32 v91, 0xffff0000, v15
	v_lshlrev_b32_e32 v92, 16, v18
	v_and_b32_e32 v93, 0xffff0000, v18
	v_lshlrev_b32_e32 v126, 16, v19
	v_and_b32_e32 v127, 0xffff0000, v19
	ds_read_b128 v[12:15], v223 offset:34832
	ds_read_b128 v[16:19], v223 offset:36880
	v_pk_fma_f32 v[22:23], v[72:73], v[82:83], v[22:23] op_sel_hi:[0,1,1]
	v_xor_b32_e32 v83, 0x80000000, v81
	v_xor_b32_e32 v82, 0x80000000, v80
	v_pk_fma_f32 v[82:83], v[72:73], v[90:91], v[82:83] op_sel_hi:[0,1,1]
	v_pk_fma_f32 v[80:81], v[26:27], v[82:83], v[80:81]
	v_pk_fma_f32 v[82:83], v[24:25], v[22:23], v[20:21]
	v_xor_b32_e32 v21, 0x80000000, v87
	v_xor_b32_e32 v20, 0x80000000, v86
	v_pk_fma_f32 v[20:21], v[72:73], v[92:93], v[20:21] op_sel_hi:[0,1,1]
	s_waitcnt lgkmcnt(1)
	v_pk_fma_f32 v[86:87], v[12:13], v[20:21], v[86:87]
	v_xor_b32_e32 v13, 0x80000000, v3
	v_xor_b32_e32 v12, 0x80000000, v2
	v_pk_fma_f32 v[10:11], v[72:73], v[10:11], v[12:13] op_sel_hi:[0,1,1]
	v_xor_b32_e32 v13, 0x80000000, v7
	v_xor_b32_e32 v12, 0x80000000, v6
	v_pk_fma_f32 v[8:9], v[72:73], v[8:9], v[12:13] op_sel_hi:[0,1,1]
	s_waitcnt lgkmcnt(0)
	v_pk_fma_f32 v[12:13], v[18:19], v[8:9], v[6:7]
	ds_read_b128 v[6:9], v223 offset:38928
	v_xor_b32_e32 v23, 0x80000000, v85
	v_xor_b32_e32 v22, 0x80000000, v84
	v_pk_fma_f32 v[22:23], v[72:73], v[126:127], v[22:23] op_sel_hi:[0,1,1]
	v_pk_fma_f32 v[84:85], v[14:15], v[22:23], v[84:85]
	s_waitcnt lgkmcnt(0)
	v_pk_mul_f32 v[90:91], v[6:7], v[86:87]
	v_pk_mul_f32 v[92:93], v[8:9], v[84:85]
	v_pk_fma_f32 v[10:11], v[16:17], v[10:11], v[2:3]
	v_pk_mul_f32 v[2:3], v[92:93], v[92:93]
	v_pk_mul_f32 v[6:7], v[90:91], v[90:91]
	s_nop 0
	v_pk_mov_b32 v[8:9], v[6:7], v[2:3] op_sel:[1,0]
	v_mov_b32_e32 v7, v3
	v_pk_add_f32 v[2:3], v[8:9], v[6:7]
	v_lshl_add_u64 v[6:7], v[78:79], 0, s[6:7]
	v_pk_add_f32 v[126:127], v[2:3], v[2:3] op_sel_hi:[0,1]
	v_cvt_pk_bf16_f32 v2, v4, v5
	v_cvt_pk_bf16_f32 v3, v0, v1
	v_cvt_pk_bf16_f32 v4, v10, v11
	v_cvt_pk_bf16_f32 v5, v12, v13
	global_store_dwordx4 v[6:7], v[2:5], off
	s_nop 1
	s_mov_b64 s[6:7], 0x200
	v_lshl_add_u64 v[4:5], v[78:79], 0, s[6:7]
	v_cvt_pk_bf16_f32 v0, v64, v65
	v_cvt_pk_bf16_f32 v1, v62, v63
	v_cvt_pk_bf16_f32 v2, v82, v83
	v_cvt_pk_bf16_f32 v3, v80, v81
	global_store_dwordx4 v[4:5], v[0:3], off
	s_nop 1
	v_lshl_add_u64 v[12:13], v[122:123], 1, v[132:133]
	s_mov_b64 s[6:7], 0x840
	v_cvt_pk_bf16_f32 v0, v54, v55
	v_cvt_pk_bf16_f32 v1, v56, v57
	v_cvt_pk_bf16_f32 v2, v58, v59
	v_cvt_pk_bf16_f32 v3, v60, v61
	global_store_dwordx4 v[78:79], v[0:3], off
	s_nop 1
	v_lshl_add_u64 v[8:9], v[12:13], 0, s[6:7]
	v_lshl_add_u64 v[16:17], v[12:13], 0, v[128:129]
	global_load_dwordx4 v[0:3], v[12:13], off offset:2112
	global_load_dwordx4 v[4:7], v[12:13], off offset:3136
	s_nop 0
	global_load_dwordx4 v[8:11], v[8:9], off offset:2048
	v_lshl_add_u64 v[20:21], v[16:17], 0, s[6:7]
	global_load_dwordx4 v[12:15], v[16:17], off offset:2112
	s_nop 0
	global_load_dwordx4 v[16:19], v[16:17], off offset:3136
	s_nop 0
	global_load_dwordx4 v[20:23], v[20:21], off offset:2048
	ds_read_b128 v[54:57], v223 offset:32896
	ds_read_b128 v[24:27], v223 offset:32912
	ds_read_b128 v[58:61], v223 offset:34944
	ds_read_b128 v[132:135], v223 offset:36992
	s_mov_b64 s[6:7], 0x2c0
	s_waitcnt vmcnt(5)
	v_lshlrev_b32_e32 v128, 16, v0
	v_and_b32_e32 v129, 0xffff0000, v0
	v_lshlrev_b32_e32 v0, 16, v1
	v_and_b32_e32 v1, 0xffff0000, v1
	s_waitcnt vmcnt(4)
	v_lshlrev_b32_e32 v136, 16, v4
	v_and_b32_e32 v137, 0xffff0000, v4
	v_lshlrev_b32_e32 v138, 16, v5
	v_and_b32_e32 v139, 0xffff0000, v5
	s_waitcnt vmcnt(2)
	v_lshlrev_b32_e32 v4, 16, v12
	v_and_b32_e32 v5, 0xffff0000, v12
	v_xor_b32_e32 v147, 0x80000000, v129
	v_xor_b32_e32 v146, 0x80000000, v128
	v_lshlrev_b32_e32 v140, 16, v8
	v_and_b32_e32 v141, 0xffff0000, v8
	v_lshlrev_b32_e32 v142, 16, v9
	v_and_b32_e32 v143, 0xffff0000, v9
	v_lshlrev_b32_e32 v8, 16, v13
	v_and_b32_e32 v9, 0xffff0000, v13
	v_pk_fma_f32 v[4:5], v[72:73], v[4:5], v[146:147] op_sel_hi:[0,1,1]
	v_xor_b32_e32 v147, 0x80000000, v1
	v_xor_b32_e32 v146, 0x80000000, v0
	v_pk_fma_f32 v[8:9], v[72:73], v[8:9], v[146:147] op_sel_hi:[0,1,1]
	s_waitcnt vmcnt(1)
	v_lshlrev_b32_e32 v12, 16, v16
	v_and_b32_e32 v13, 0xffff0000, v16
	v_lshlrev_b32_e32 v16, 16, v17
	v_and_b32_e32 v17, 0xffff0000, v17
	s_waitcnt lgkmcnt(3)
	v_pk_fma_f32 v[0:1], v[56:57], v[8:9], v[0:1]
	v_xor_b32_e32 v9, 0x80000000, v139
	v_xor_b32_e32 v8, 0x80000000, v138
	v_pk_fma_f32 v[16:17], v[72:73], v[16:17], v[8:9] op_sel_hi:[0,1,1]
	v_xor_b32_e32 v9, 0x80000000, v137
	v_xor_b32_e32 v8, 0x80000000, v136
	s_waitcnt vmcnt(0)
	v_lshlrev_b32_e32 v144, 16, v20
	v_and_b32_e32 v145, 0xffff0000, v20
	v_lshlrev_b32_e32 v20, 16, v21
	v_and_b32_e32 v21, 0xffff0000, v21
	v_pk_fma_f32 v[4:5], v[54:55], v[4:5], v[128:129]
	v_pk_fma_f32 v[8:9], v[72:73], v[12:13], v[8:9] op_sel_hi:[0,1,1]
	s_waitcnt lgkmcnt(1)
	v_pk_fma_f32 v[12:13], v[60:61], v[16:17], v[138:139]
	v_xor_b32_e32 v17, 0x80000000, v141
	v_xor_b32_e32 v16, 0x80000000, v140
	v_xor_b32_e32 v55, 0x80000000, v143
	v_xor_b32_e32 v54, 0x80000000, v142
	v_pk_fma_f32 v[16:17], v[72:73], v[144:145], v[16:17] op_sel_hi:[0,1,1]
	v_pk_fma_f32 v[20:21], v[72:73], v[20:21], v[54:55] op_sel_hi:[0,1,1]
	v_lshlrev_b32_e32 v128, 16, v2
	v_and_b32_e32 v129, 0xffff0000, v2
	s_waitcnt lgkmcnt(0)
	v_pk_fma_f32 v[54:55], v[134:135], v[20:21], v[142:143]
	v_pk_fma_f32 v[56:57], v[132:133], v[16:17], v[140:141]
	v_lshlrev_b32_e32 v2, 16, v3
	v_and_b32_e32 v3, 0xffff0000, v3
	v_lshlrev_b32_e32 v140, 16, v6
	v_and_b32_e32 v141, 0xffff0000, v6
	v_lshlrev_b32_e32 v142, 16, v7
	v_and_b32_e32 v143, 0xffff0000, v7
	v_lshlrev_b32_e32 v6, 16, v14
	v_and_b32_e32 v7, 0xffff0000, v14
	v_xor_b32_e32 v151, 0x80000000, v129
	v_xor_b32_e32 v150, 0x80000000, v128
	v_lshlrev_b32_e32 v144, 16, v10
	v_and_b32_e32 v145, 0xffff0000, v10
	v_lshlrev_b32_e32 v146, 16, v11
	v_and_b32_e32 v147, 0xffff0000, v11
	v_lshlrev_b32_e32 v10, 16, v15
	v_and_b32_e32 v11, 0xffff0000, v15
	v_pk_fma_f32 v[6:7], v[72:73], v[6:7], v[150:151] op_sel_hi:[0,1,1]
	v_xor_b32_e32 v151, 0x80000000, v3
	v_xor_b32_e32 v150, 0x80000000, v2
	v_pk_fma_f32 v[8:9], v[58:59], v[8:9], v[136:137]
	ds_read_b128 v[58:61], v223 offset:39040
	ds_read_b128 v[132:135], v223 offset:34960
	ds_read_b128 v[136:139], v223 offset:37008
	v_pk_fma_f32 v[10:11], v[72:73], v[10:11], v[150:151] op_sel_hi:[0,1,1]
	v_lshlrev_b32_e32 v14, 16, v18
	v_and_b32_e32 v15, 0xffff0000, v18
	v_lshlrev_b32_e32 v18, 16, v19
	v_and_b32_e32 v19, 0xffff0000, v19
	v_pk_fma_f32 v[2:3], v[26:27], v[10:11], v[2:3]
	v_xor_b32_e32 v11, 0x80000000, v143
	v_xor_b32_e32 v10, 0x80000000, v142
	v_pk_fma_f32 v[18:19], v[72:73], v[18:19], v[10:11] op_sel_hi:[0,1,1]
	v_xor_b32_e32 v11, 0x80000000, v141
	v_xor_b32_e32 v10, 0x80000000, v140
	v_pk_fma_f32 v[10:11], v[72:73], v[14:15], v[10:11] op_sel_hi:[0,1,1]
	s_waitcnt lgkmcnt(1)
	v_pk_fma_f32 v[10:11], v[132:133], v[10:11], v[140:141]
	v_pk_fma_f32 v[14:15], v[134:135], v[18:19], v[142:143]
	ds_read_b128 v[132:135], v223 offset:39056
	v_pk_mul_f32 v[20:21], v[58:59], v[8:9]
	v_pk_mul_f32 v[16:17], v[60:61], v[12:13]
	v_mul_f32_e32 v58, v20, v20
	v_pk_fma_f32 v[58:59], v[20:21], v[20:21], v[58:59] op_sel_hi:[1,1,0]
	v_lshlrev_b32_e32 v148, 16, v22
	v_and_b32_e32 v149, 0xffff0000, v22
	v_lshlrev_b32_e32 v22, 16, v23
	v_and_b32_e32 v23, 0xffff0000, v23
	v_pk_fma_f32 v[6:7], v[24:25], v[6:7], v[128:129]
	v_xor_b32_e32 v19, 0x80000000, v145
	v_xor_b32_e32 v18, 0x80000000, v144
	v_xor_b32_e32 v25, 0x80000000, v147
	v_xor_b32_e32 v24, 0x80000000, v146
	v_mul_f32_e32 v58, v16, v16
	v_pk_fma_f32 v[18:19], v[72:73], v[148:149], v[18:19] op_sel_hi:[0,1,1]
	v_pk_fma_f32 v[22:23], v[72:73], v[22:23], v[24:25] op_sel_hi:[0,1,1]
	v_pk_fma_f32 v[60:61], v[16:17], v[16:17], v[58:59] op_sel_hi:[1,1,0]
	s_waitcnt lgkmcnt(1)
	v_pk_fma_f32 v[24:25], v[138:139], v[22:23], v[146:147]
	v_pk_fma_f32 v[26:27], v[136:137], v[18:19], v[144:145]
	s_waitcnt lgkmcnt(0)
	v_pk_mul_f32 v[18:19], v[134:135], v[14:15]
	v_pk_mul_f32 v[22:23], v[132:133], v[10:11]
	v_mul_f32_e32 v58, v18, v18
	v_mul_f32_e32 v88, v22, v22
	v_mul_f32_e32 v126, v23, v23
	v_mul_f32_e32 v60, v19, v19
	v_pk_add_f32 v[72:73], v[88:89], v[126:127]
	v_pk_add_f32 v[58:59], v[58:59], v[60:61]
	v_lshl_add_u64 v[60:61], v[78:79], 0, s[6:7]
	v_pk_add_f32 v[58:59], v[72:73], v[58:59]
	v_cvt_pk_bf16_f32 v56, v56, v57
	v_add_f32_e32 v72, v58, v59
	v_cvt_pk_bf16_f32 v57, v54, v55
	v_cvt_pk_bf16_f32 v58, v26, v27
	v_cvt_pk_bf16_f32 v59, v24, v25
	global_store_dwordx4 v[60:61], v[56:59], off
	s_nop 1
	s_mov_b64 s[6:7], 0x240
	v_cvt_pk_bf16_f32 v24, v4, v5
	v_lshl_add_u64 v[54:55], v[78:79], 0, s[6:7]
	v_cvt_pk_bf16_f32 v25, v0, v1
	v_cvt_pk_bf16_f32 v26, v6, v7
	v_cvt_pk_bf16_f32 v27, v2, v3
	global_store_dwordx4 v[54:55], v[24:27], off
	s_nop 1
	v_cvt_pk_bf16_f32 v24, v44, v45
	v_lshl_add_u64 v[54:55], v[78:79], 0, 64
	v_cvt_pk_bf16_f32 v25, v46, v47
	v_cvt_pk_bf16_f32 v26, v50, v51
	v_cvt_pk_bf16_f32 v27, v52, v53
	global_store_dwordx4 v[54:55], v[24:27], off
	s_nop 1
	s_mov_b32 s6, 0xf800000
	v_pk_add_f32 v[60:61], v[42:43], -1.0 op_sel_hi:[1,0]
	s_waitcnt lgkmcnt(0)
	v_mov_b32_e32 v24, v72
	s_nop 1
	v_permlane16_swap_b32_e32 v72, v24
	v_add_f32_e32 v24, v72, v24
	v_mov_b32_e32 v25, v24
	s_nop 1
	v_permlane32_swap_b32_e32 v24, v25
	v_add_f32_e32 v24, v24, v25
	v_cmp_gt_f32_e32 vcc, s6, v24
	v_mul_f32_e32 v25, 0x4f800000, v24
	v_pk_add_f32 v[72:73], v[40:41], -1.0 op_sel_hi:[1,0]
	v_cndmask_b32_e32 v24, v24, v25, vcc
	v_sqrt_f32_e32 v25, v24
	s_nop 0
	v_add_u32_e32 v26, -1, v25
	v_fma_f32 v27, -v26, v25, v24
	v_cmp_ge_f32_e64 s[46:47], 0, v27
	v_add_u32_e32 v27, 1, v25
	s_nop 0
	v_cndmask_b32_e64 v26, v25, v26, s[46:47]
	v_fma_f32 v25, -v27, v25, v24
	v_cmp_lt_f32_e64 s[46:47], 0, v25
	s_nop 1
	v_cndmask_b32_e64 v25, v26, v27, s[46:47]
	v_mul_f32_e32 v26, 0x37800000, v25
	v_cndmask_b32_e32 v25, v25, v26, vcc
	v_cmp_class_f32_e32 vcc, v24, v207
	s_nop 1
	v_cndmask_b32_e32 v24, v25, v24, vcc
	v_max_f32_e32 v24, 0x2b8cbccc, v24
	v_div_scale_f32 v25, s[6:7], v24, v24, 1.0
	v_rcp_f32_e32 v26, v25
	s_mov_b64 s[6:7], 0x180
	v_fma_f32 v27, -v25, v26, 1.0
	v_fmac_f32_e32 v26, v27, v26
	v_div_scale_f32 v27, vcc, 1.0, v24, 1.0
	v_mul_f32_e32 v44, v27, v26
	v_fma_f32 v45, -v25, v44, v27
	v_fmac_f32_e32 v44, v45, v26
	v_fma_f32 v25, -v25, v44, v27
	v_div_fmas_f32 v25, v25, v26, v44
	v_div_fixup_f32 v54, v25, v24, 1.0
	ds_read_b128 v[24:27], v223 offset:40960
	ds_read_b128 v[44:47], v223 offset:40976
	ds_read_b128 v[50:53], v223 offset:43008
	v_pk_mul_f32 v[56:57], v[74:75], v[54:55] op_sel_hi:[1,0]
	v_pk_mul_f32 v[58:59], v[76:77], v[54:55] op_sel_hi:[1,0]
	s_waitcnt lgkmcnt(2)
	v_pk_fma_f32 v[24:25], v[72:73], v[24:25], 1.0 op_sel_hi:[1,1,0]
	v_pk_fma_f32 v[26:27], v[60:61], v[26:27], 1.0 op_sel_hi:[1,1,0]
	v_pk_mul_f32 v[42:43], v[42:43], v[58:59]
	v_pk_mul_f32 v[60:61], v[68:69], v[26:27]
	v_pk_mul_f32 v[68:69], v[70:71], v[24:25]
	v_pk_mul_f32 v[26:27], v[62:63], v[60:61]
	v_pk_mul_f32 v[24:25], v[64:65], v[68:69]
	s_waitcnt lgkmcnt(0)
	v_pk_mul_f32 v[26:27], v[52:53], v[26:27]
	v_pk_mul_f32 v[24:25], v[50:51], v[24:25]
	v_xor_b32_e32 v62, 0x80000000, v59
	v_add_f32_e32 v24, v24, v25
	v_add_f32_e32 v25, v26, v27
	v_add_f32_e32 v24, v24, v25
	v_add_f32_e32 v55, 0, v24
	ds_read_b128 v[24:27], v223 offset:43024
	v_xor_b32_e32 v63, 0x80000000, v58
	v_xor_b32_e32 v64, 0x80000000, v57
	v_xor_b32_e32 v65, 0x80000000, v56
	v_pk_mul_f32 v[40:41], v[40:41], v[56:57]
	v_pk_add_f32 v[56:57], v[38:39], -1.0 op_sel_hi:[1,0]
	v_pk_add_f32 v[58:59], v[36:37], -1.0 op_sel_hi:[1,0]
	v_pk_fma_f32 v[46:47], v[56:57], v[46:47], 1.0 op_sel_hi:[1,1,0]
	v_pk_fma_f32 v[44:45], v[58:59], v[44:45], 1.0 op_sel_hi:[1,1,0]
	v_pk_mul_f32 v[46:47], v[84:85], v[46:47]
	v_pk_mul_f32 v[44:45], v[86:87], v[44:45]
	v_pk_mul_f32 v[58:59], v[80:81], v[46:47]
	v_pk_mul_f32 v[56:57], v[82:83], v[44:45]
	s_waitcnt lgkmcnt(0)
	v_pk_mul_f32 v[26:27], v[26:27], v[58:59]
	v_pk_mul_f32 v[24:25], v[24:25], v[56:57]
	v_pk_mul_f32 v[50:51], v[90:91], v[54:55] op_sel_hi:[1,0]
	v_add_f32_e32 v24, v24, v25
	v_add_f32_e32 v25, v26, v27
	v_pk_mul_f32 v[52:53], v[92:93], v[54:55] op_sel_hi:[1,0]
	v_add_f32_e32 v24, v24, v25
	v_add_f32_e32 v55, v55, v24
	v_xor_b32_e32 v56, 0x80000000, v53
	v_xor_b32_e32 v57, 0x80000000, v52
	v_xor_b32_e32 v58, 0x80000000, v51
	v_xor_b32_e32 v59, 0x80000000, v50
	v_pk_mul_f32 v[36:37], v[36:37], v[50:51]
	v_lshl_add_u64 v[50:51], v[78:79], 0, s[30:31]
	v_cvt_pk_bf16_f32 v24, v68, v69
	v_cvt_pk_bf16_f32 v25, v60, v61
	v_cvt_pk_bf16_f32 v26, v44, v45
	v_cvt_pk_bf16_f32 v27, v46, v47
	global_store_dwordx4 v[50:51], v[24:27], off
	s_nop 1
	v_pk_mul_f32 v[38:39], v[38:39], v[52:53]
	v_lshl_add_u64 v[44:45], v[78:79], 0, s[34:35]
	v_cvt_pk_bf16_f32 v24, v65, v64
	v_cvt_pk_bf16_f32 v25, v63, v62
	v_cvt_pk_bf16_f32 v26, v59, v58
	v_cvt_pk_bf16_f32 v27, v57, v56
	global_store_dwordx4 v[44:45], v[24:27], off
	s_nop 1
	v_lshl_add_u64 v[44:45], v[78:79], 0, s[6:7]
	v_cvt_pk_bf16_f32 v24, v40, v41
	v_cvt_pk_bf16_f32 v25, v42, v43
	v_cvt_pk_bf16_f32 v26, v36, v37
	v_cvt_pk_bf16_f32 v27, v38, v39
	global_store_dwordx4 v[44:45], v[24:27], off
	s_nop 1
	ds_read_b128 v[24:27], v223 offset:41088
	ds_read_b128 v[36:39], v223 offset:41104
	ds_read_b128 v[40:43], v223 offset:43136
	v_pk_add_f32 v[44:45], v[34:35], -1.0 op_sel_hi:[1,0]
	v_pk_add_f32 v[46:47], v[32:33], -1.0 op_sel_hi:[1,0]
	s_waitcnt lgkmcnt(2)
	v_pk_fma_f32 v[26:27], v[44:45], v[26:27], 1.0 op_sel_hi:[1,1,0]
	v_pk_fma_f32 v[24:25], v[46:47], v[24:25], 1.0 op_sel_hi:[1,1,0]
	v_pk_mul_f32 v[12:13], v[12:13], v[26:27]
	v_pk_mul_f32 v[8:9], v[8:9], v[24:25]
	v_pk_mul_f32 v[0:1], v[0:1], v[12:13]
	v_pk_mul_f32 v[4:5], v[4:5], v[8:9]
	s_waitcnt lgkmcnt(0)
	v_pk_mul_f32 v[0:1], v[42:43], v[0:1]
	v_pk_mul_f32 v[4:5], v[40:41], v[4:5]
	v_add_f32_e32 v0, v0, v1
	v_add_f32_e32 v4, v4, v5
	v_pk_mul_f32 v[16:17], v[16:17], v[54:55] op_sel_hi:[1,0]
	v_add_f32_e32 v0, v4, v0
	v_add_f32_e32 v40, v55, v0
	v_xor_b32_e32 v41, 0x80000000, v17
	v_xor_b32_e32 v42, 0x80000000, v16
	v_pk_mul_f32 v[4:5], v[34:35], v[16:17]
	v_pk_mul_f32 v[0:1], v[22:23], v[54:55] op_sel_hi:[1,0]
	v_pk_mul_f32 v[22:23], v[18:19], v[54:55] op_sel_hi:[1,0]
	ds_read_b128 v[16:19], v223 offset:43152
	v_pk_add_f32 v[24:25], v[30:31], -1.0 op_sel_hi:[1,0]
	v_pk_add_f32 v[26:27], v[28:29], -1.0 op_sel_hi:[1,0]
	v_pk_fma_f32 v[24:25], v[24:25], v[38:39], 1.0 op_sel_hi:[1,1,0]
	v_pk_fma_f32 v[26:27], v[26:27], v[36:37], 1.0 op_sel_hi:[1,1,0]
	v_pk_mul_f32 v[14:15], v[14:15], v[24:25]
	v_pk_mul_f32 v[10:11], v[10:11], v[26:27]
	v_pk_mul_f32 v[2:3], v[2:3], v[14:15]
	v_pk_mul_f32 v[6:7], v[6:7], v[10:11]
	s_waitcnt lgkmcnt(0)
	v_pk_mul_f32 v[2:3], v[18:19], v[2:3]
	v_pk_mul_f32 v[6:7], v[16:17], v[6:7]
	v_pk_mul_f32 v[20:21], v[20:21], v[54:55] op_sel_hi:[1,0]
	v_add_f32_e32 v6, v6, v7
	v_add_f32_e32 v2, v2, v3
	v_xor_b32_e32 v43, 0x80000000, v21
	v_xor_b32_e32 v44, 0x80000000, v20
	v_pk_mul_f32 v[20:21], v[32:33], v[20:21]
	v_add_f32_e32 v2, v6, v2
	v_xor_b32_e32 v32, 0x80000000, v0
	v_pk_mul_f32 v[16:17], v[28:29], v[0:1]
	s_mov_b64 s[6:7], 0xc0
	v_cvt_pk_bf16_f32 v0, v8, v9
	v_add_f32_e32 v24, v40, v2
	v_xor_b32_e32 v25, 0x80000000, v23
	v_xor_b32_e32 v26, 0x80000000, v22
	v_xor_b32_e32 v27, 0x80000000, v1
	v_lshl_add_u64 v[18:19], v[78:79], 0, s[6:7]
	v_cvt_pk_bf16_f32 v1, v12, v13
	v_cvt_pk_bf16_f32 v2, v10, v11
	v_cvt_pk_bf16_f32 v3, v14, v15
	global_store_dwordx4 v[18:19], v[0:3], off
	s_nop 1
	s_mov_b64 s[6:7], 0x140
	v_cvt_pk_bf16_f32 v0, v44, v43
	v_pk_mul_f32 v[6:7], v[30:31], v[22:23]
	v_lshl_add_u64 v[8:9], v[78:79], 0, s[6:7]
	v_cvt_pk_bf16_f32 v1, v42, v41
	v_cvt_pk_bf16_f32 v2, v32, v27
	v_cvt_pk_bf16_f32 v3, v26, v25
	global_store_dwordx4 v[8:9], v[0:3], off
	s_nop 1
	s_mov_b64 s[6:7], 0x1c0
	v_cvt_pk_bf16_f32 v0, v20, v21
	v_lshl_add_u64 v[8:9], v[78:79], 0, s[6:7]
	v_cvt_pk_bf16_f32 v1, v4, v5
	v_cvt_pk_bf16_f32 v2, v16, v17
	v_cvt_pk_bf16_f32 v3, v6, v7
	global_store_dwordx4 v[8:9], v[0:3], off
	s_nop 1
	ds_bpermute_b32 v0, v131, v24
	s_waitcnt lgkmcnt(0)
	v_add_f32_e32 v0, v24, v0
	v_mov_b32_e32 v1, v0
	s_nop 1
	v_permlane32_swap_b32_e32 v0, v1
	s_and_saveexec_b64 s[46:47], s[44:45]
	s_cbranch_execz .LBB0_901
	v_add_f32_e32 v2, v0, v1
	v_lshlrev_b64 v[0:1], 5, v[66:67]
	v_lshl_add_u64 v[0:1], s[58:59], 0, v[0:1]
	global_store_dword v[0:1], v2, off
	s_branch .LBB0_901

.LBB0_1414:
	v_lshl_add_u32 v177, s38, 8, v172
	v_add_u32_e32 v48, v177, v174
	v_add_u32_e32 v140, 0x40a0, v48
	v_mov_b32_e32 v141, v49
	v_lshl_add_u64 v[138:139], v[48:49], 2, s[22:23]
	v_lshl_add_u64 v[140:141], v[140:141], 2, s[22:23]
	global_load_dword v168, v[138:139], off
	global_load_dword v152, v[140:141], off
	v_add_u32_e32 v138, 0x4000, v48
	v_mov_b32_e32 v139, v49
	v_add_u32_e32 v156, 0x40b0, v48
	v_mov_b32_e32 v157, v49
	v_lshl_add_u64 v[138:139], v[138:139], 2, s[22:23]
	v_lshl_add_u64 v[156:157], v[156:157], 2, s[22:23]
	global_load_dword v170, v[138:139], off
	v_add_u32_e32 v140, 0x80a0, v48
	global_load_dword v156, v[156:157], off
	v_add_u32_e32 v138, 0x8000, v48
	v_mov_b32_e32 v139, v49
	v_lshl_add_u64 v[138:139], v[138:139], 2, s[22:23]
	global_load_dword v169, v[138:139], off
	v_add_u32_e32 v138, 0xc000, v48
	v_mov_b32_e32 v139, v49
	v_lshl_add_u64 v[138:139], v[138:139], 2, s[22:23]
	global_load_dword v171, v[138:139], off
	v_or_b32_e32 v138, 16, v48
	v_mov_b32_e32 v139, v49
	v_lshl_add_u64 v[138:139], v[138:139], 2, s[22:23]
	global_load_dword v150, v[138:139], off
	v_add_u32_e32 v138, 0x4010, v48
	v_mov_b32_e32 v139, v49
	v_lshl_add_u64 v[138:139], v[138:139], 2, s[22:23]
	global_load_dword v166, v[138:139], off
	v_add_u32_e32 v138, 0x8010, v48
	v_mov_b32_e32 v139, v49
	v_lshl_add_u64 v[138:139], v[138:139], 2, s[22:23]
	global_load_dword v151, v[138:139], off
	v_add_u32_e32 v138, 0xc010, v48
	v_mov_b32_e32 v139, v49
	v_lshl_add_u64 v[138:139], v[138:139], 2, s[22:23]
	global_load_dword v167, v[138:139], off
	v_or_b32_e32 v138, 32, v48
	v_mov_b32_e32 v139, v49
	v_lshl_add_u64 v[138:139], v[138:139], 2, s[22:23]
	global_load_dword v146, v[138:139], off
	v_add_u32_e32 v138, 0x4020, v48
	v_mov_b32_e32 v139, v49
	v_lshl_add_u64 v[138:139], v[138:139], 2, s[22:23]
	global_load_dword v162, v[138:139], off
	v_add_u32_e32 v138, 0x8020, v48
	v_mov_b32_e32 v139, v49
	v_lshl_add_u64 v[138:139], v[138:139], 2, s[22:23]
	global_load_dword v147, v[138:139], off
	v_add_u32_e32 v138, 0xc020, v48
	v_mov_b32_e32 v139, v49
	v_lshl_add_u64 v[138:139], v[138:139], 2, s[22:23]
	global_load_dword v163, v[138:139], off
	v_or_b32_e32 v138, 48, v48
	v_mov_b32_e32 v139, v49
	v_lshl_add_u64 v[138:139], v[138:139], 2, s[22:23]
	global_load_dword v148, v[138:139], off
	v_add_u32_e32 v138, 0x4030, v48
	v_mov_b32_e32 v139, v49
	v_lshl_add_u64 v[138:139], v[138:139], 2, s[22:23]
	global_load_dword v164, v[138:139], off
	v_add_u32_e32 v138, 0x8030, v48
	v_mov_b32_e32 v139, v49
	v_lshl_add_u64 v[138:139], v[138:139], 2, s[22:23]
	global_load_dword v149, v[138:139], off
	v_add_u32_e32 v138, 0xc030, v48
	v_mov_b32_e32 v139, v49
	v_lshl_add_u64 v[138:139], v[138:139], 2, s[22:23]
	global_load_dword v165, v[138:139], off
	v_add_u32_e32 v138, 0x80, v48
	v_mov_b32_e32 v139, v49
	v_lshl_add_u64 v[138:139], v[138:139], 2, s[22:23]
	global_load_dword v142, v[138:139], off
	v_add_u32_e32 v138, 0x4080, v48
	v_mov_b32_e32 v139, v49
	v_lshl_add_u64 v[138:139], v[138:139], 2, s[22:23]
	global_load_dword v158, v[138:139], off
	v_add_u32_e32 v138, 0x8080, v48
	v_mov_b32_e32 v139, v49
	v_lshl_add_u64 v[138:139], v[138:139], 2, s[22:23]
	global_load_dword v143, v[138:139], off
	v_add_u32_e32 v138, 0xc080, v48
	v_mov_b32_e32 v139, v49
	v_lshl_add_u64 v[138:139], v[138:139], 2, s[22:23]
	global_load_dword v159, v[138:139], off
	v_add_u32_e32 v138, 0x90, v48
	v_mov_b32_e32 v139, v49
	v_lshl_add_u64 v[138:139], v[138:139], 2, s[22:23]
	global_load_dword v144, v[138:139], off
	v_add_u32_e32 v138, 0x4090, v48
	v_mov_b32_e32 v139, v49
	v_lshl_add_u64 v[138:139], v[138:139], 2, s[22:23]
	global_load_dword v160, v[138:139], off
	v_add_u32_e32 v138, 0x8090, v48
	v_mov_b32_e32 v139, v49
	v_lshl_add_u64 v[138:139], v[138:139], 2, s[22:23]
	global_load_dword v145, v[138:139], off
	v_add_u32_e32 v138, 0xc090, v48
	v_mov_b32_e32 v139, v49
	v_lshl_add_u64 v[138:139], v[138:139], 2, s[22:23]
	global_load_dword v161, v[138:139], off
	v_add_u32_e32 v138, 0xa0, v48
	v_mov_b32_e32 v139, v49
	v_mov_b32_e32 v141, v49
	v_lshl_add_u64 v[138:139], v[138:139], 2, s[22:23]
	v_lshl_add_u64 v[140:141], v[140:141], 2, s[22:23]
	global_load_dword v138, v[138:139], off
	v_add_u32_e32 v178, 0x80b0, v48
	global_load_dword v139, v[140:141], off
	v_add_u32_e32 v140, 0xc0a0, v48
	v_mov_b32_e32 v141, v49
	v_lshl_add_u64 v[140:141], v[140:141], 2, s[22:23]
	global_load_dword v153, v[140:141], off
	v_add_u32_e32 v140, 0xb0, v48
	v_mov_b32_e32 v141, v49
	v_mov_b32_e32 v179, v49
	v_lshl_add_u64 v[140:141], v[140:141], 2, s[22:23]
	v_lshl_add_u64 v[178:179], v[178:179], 2, s[22:23]
	v_add_u32_e32 v48, 0xc0b0, v48
	global_load_dword v140, v[140:141], off
	s_waitcnt vmcnt(0)
	v_pk_add_f32 v[168:169], v[168:169], v[170:171]
	global_load_dword v141, v[178:179], off
	v_lshl_add_u64 v[178:179], v[48:49], 2, s[22:23]
	global_load_dword v157, v[178:179], off
	v_and_b32_e32 v178, 64, v205
	v_xor_b32_e32 v48, 16, v205
	v_add_u32_e32 v178, 64, v178
	v_cmp_lt_i32_e32 vcc, v48, v178
	v_pk_add_f32 v[150:151], v[150:151], v[166:167]
	s_mov_b32 s6, 0x358637bd
	v_cndmask_b32_e32 v48, v205, v48, vcc
	v_lshlrev_b32_e32 v178, 2, v48
	v_add_f32_e32 v48, v168, v169
	ds_bpermute_b32 v168, v178, v48
	v_pk_add_f32 v[146:147], v[146:147], v[162:163]
	v_mov_b64_e32 v[166:167], s[6:7]
	v_add_f32_e32 v146, v146, v147
	ds_bpermute_b32 v147, v178, v146
	s_waitcnt lgkmcnt(1)
	v_add_f32_e32 v169, v48, v168
	v_add_f32_e32 v48, v150, v151
	ds_bpermute_b32 v150, v178, v48
	v_mov_b32_e32 v171, v169
	s_waitcnt lgkmcnt(1)
	v_add_f32_e32 v147, v146, v147
	v_permlane32_swap_b32_e32 v169, v171
	s_waitcnt lgkmcnt(0)
	v_add_f32_e32 v168, v48, v150
	v_mov_b32_e32 v170, v168
	s_nop 1
	v_permlane32_swap_b32_e32 v168, v170
	v_pk_add_f32 v[148:149], v[148:149], v[164:165]
	v_pk_add_f32 v[150:151], v[168:169], v[170:171]
	v_add_f32_e32 v146, v148, v149
	v_pk_fma_f32 v[168:169], v[150:151], s[36:37], v[166:167] op_sel_hi:[1,0,0]
	v_mov_b32_e32 v163, v147
	v_mul_f32_e32 v48, 0x4b800000, v169
	v_cmp_gt_f32_e64 s[38:39], s75, v169
	s_waitcnt lgkmcnt(0)
	v_mov_b32_e32 v148, v146
	s_nop 1
	v_permlane16_swap_b32_e32 v146, v148
	v_add_f32_e32 v146, v146, v148
	v_mov_b32_e32 v162, v146
	v_cndmask_b32_e64 v48, v169, v48, s[38:39]
	v_rsq_f32_e32 v48, v48
	v_permlane32_swap_b32_e32 v147, v163
	v_permlane32_swap_b32_e32 v146, v162
	v_pk_add_f32 v[142:143], v[142:143], v[158:159]
	v_pk_add_f32 v[146:147], v[146:147], v[162:163]
	v_add_f32_e32 v142, v142, v143
	v_mul_f32_e32 v150, 0x45800000, v48
	v_pk_fma_f32 v[146:147], v[146:147], s[36:37], v[166:167] op_sel_hi:[1,0,0]
	v_cmp_gt_f32_e32 vcc, s75, v168
	v_cndmask_b32_e64 v150, v48, v150, s[38:39]
	s_waitcnt lgkmcnt(0)
	v_mov_b32_e32 v143, v142
	s_nop 1
	v_permlane16_swap_b32_e32 v142, v143
	v_add_f32_e32 v143, v142, v143
	v_mul_f32_e32 v48, 0x4b800000, v168
	v_mul_f32_e32 v148, 0x4b800000, v147
	v_cmp_gt_f32_e64 s[38:39], s75, v147
	v_cndmask_b32_e32 v48, v168, v48, vcc
	v_rsq_f32_e32 v48, v48
	v_cndmask_b32_e64 v147, v147, v148, s[38:39]
	v_pk_add_f32 v[144:145], v[144:145], v[160:161]
	v_rsq_f32_e32 v147, v147
	v_add_f32_e32 v142, v144, v145
	v_mov_b32_e32 v159, v143
	s_nop 1
	v_permlane32_swap_b32_e32 v143, v159
	v_mul_f32_e32 v151, 0x45800000, v48
	s_waitcnt lgkmcnt(0)
	v_mov_b32_e32 v144, v142
	s_nop 1
	v_permlane16_swap_b32_e32 v142, v144
	v_add_f32_e32 v142, v142, v144
	v_mov_b32_e32 v158, v142
	s_nop 1
	v_permlane32_swap_b32_e32 v142, v158
	v_pk_add_f32 v[138:139], v[138:139], v[152:153]
	v_pk_add_f32 v[142:143], v[142:143], v[158:159]
	v_add_f32_e32 v138, v138, v139
	v_mul_f32_e32 v148, 0x45800000, v147
	v_pk_fma_f32 v[142:143], v[142:143], s[36:37], v[166:167] op_sel_hi:[1,0,0]
	v_cndmask_b32_e32 v48, v48, v151, vcc
	v_cmp_gt_f32_e32 vcc, s75, v146
	s_waitcnt lgkmcnt(0)
	v_mov_b32_e32 v139, v138
	s_nop 1
	v_permlane16_swap_b32_e32 v138, v139
	v_add_f32_e32 v139, v138, v139
	v_cndmask_b32_e64 v148, v147, v148, s[38:39]
	v_mul_f32_e32 v147, 0x4b800000, v146
	s_waitcnt vmcnt(0)
	v_pk_add_f32 v[140:141], v[140:141], v[156:157]
	v_mul_f32_e32 v144, 0x4b800000, v143
	v_add_f32_e32 v138, v140, v141
	v_cmp_gt_f32_e64 s[38:39], s75, v143
	v_cndmask_b32_e32 v146, v146, v147, vcc
	v_rsq_f32_e32 v146, v146
	v_cndmask_b32_e64 v143, v143, v144, s[38:39]
	v_rsq_f32_e32 v143, v143
	s_waitcnt lgkmcnt(0)
	v_mov_b32_e32 v140, v138
	s_nop 1
	v_permlane16_swap_b32_e32 v138, v140
	v_add_f32_e32 v138, v138, v140
	v_mov_b32_e32 v153, v139
	v_mov_b32_e32 v152, v138
	s_nop 0
	v_permlane32_swap_b32_e32 v139, v153
	v_permlane32_swap_b32_e32 v138, v152
	v_pk_add_f32 v[138:139], v[138:139], v[152:153]
	v_mul_f32_e32 v147, 0x45800000, v146
	v_mul_f32_e32 v144, 0x45800000, v143
	v_pk_fma_f32 v[138:139], v[138:139], s[36:37], v[166:167] op_sel_hi:[1,0,0]
	v_cndmask_b32_e32 v146, v146, v147, vcc
	v_cmp_gt_f32_e32 vcc, s75, v142
	v_cndmask_b32_e64 v144, v143, v144, s[38:39]
	v_mul_f32_e32 v143, 0x4b800000, v142
	v_mul_f32_e32 v140, 0x4b800000, v139
	v_cmp_gt_f32_e64 s[38:39], s75, v139
	v_cndmask_b32_e32 v142, v142, v143, vcc
	v_rsq_f32_e32 v142, v142
	v_cndmask_b32_e64 v139, v139, v140, s[38:39]
	v_rsq_f32_e32 v139, v139
	v_pk_mul_f32 v[126:127], v[126:127], v[150:151] op_sel_hi:[1,0]
	v_mul_f32_e32 v143, 0x45800000, v142
	v_cndmask_b32_e32 v142, v142, v143, vcc
	v_mul_f32_e32 v140, 0x45800000, v139
	v_cmp_gt_f32_e32 vcc, s75, v138
	v_cndmask_b32_e64 v140, v139, v140, s[38:39]
	v_mul_f32_e32 v139, 0x4b800000, v138
	v_cndmask_b32_e32 v138, v138, v139, vcc
	v_rsq_f32_e32 v138, v138
	v_pk_mul_f32 v[122:123], v[122:123], v[150:151] op_sel_hi:[1,0]
	v_pk_mul_f32 v[124:125], v[124:125], v[150:151] op_sel_hi:[1,0]
	v_pk_mul_f32 v[122:123], v[126:127], v[122:123]
	v_mul_f32_e32 v139, 0x45800000, v138
	v_cndmask_b32_e32 v138, v138, v139, vcc
	v_mul_f32_e32 v139, 0xbfb8aa3b, v126
	v_mul_f32_e32 v126, 0xbfb8aa3b, v127
	v_exp_f32_e32 v126, v126
	v_exp_f32_e32 v139, v139
	v_pk_mul_f32 v[118:119], v[118:119], v[150:151] op_sel_hi:[1,0]
	v_pk_mul_f32 v[114:115], v[114:115], v[150:151] op_sel_hi:[1,0]
	v_add_f32_e32 v126, 1.0, v126
	v_rcp_f32_e32 v157, v126
	v_pk_mul_f32 v[126:127], v[128:129], v[150:151] op_sel_hi:[1,0]
	v_add_f32_e32 v139, 1.0, v139
	v_mul_f32_e32 v128, 0xbfb8aa3b, v126
	v_pk_mul_f32 v[124:125], v[126:127], v[124:125]
	v_mul_f32_e32 v126, 0xbfb8aa3b, v127
	v_exp_f32_e32 v128, v128
	v_exp_f32_e32 v126, v126
	v_rcp_f32_e32 v156, v139
	v_pk_mul_f32 v[114:115], v[118:119], v[114:115]
	v_add_f32_e32 v128, 1.0, v128
	v_add_f32_e32 v126, 1.0, v126
	v_rcp_f32_e32 v128, v128
	v_rcp_f32_e32 v129, v126
	v_pk_mul_f32 v[122:123], v[122:123], v[156:157]
	v_pk_mul_f32 v[116:117], v[116:117], v[150:151] op_sel_hi:[1,0]
	v_cvt_pk_bf16_f32 v122, v122, v123
	v_pk_mul_f32 v[124:125], v[124:125], v[128:129]
	v_lshl_or_b32 v152, s18, 7, v175
	v_cvt_pk_bf16_f32 v123, v124, v125
	v_mul_f32_e32 v124, 0xbfb8aa3b, v118
	v_mul_f32_e32 v118, 0xbfb8aa3b, v119
	v_exp_f32_e32 v118, v118
	v_exp_f32_e32 v124, v124
	s_movk_i32 s6, 0xb00
	v_pk_mul_f32 v[110:111], v[110:111], v[48:49] op_sel_hi:[1,0]
	v_add_f32_e32 v118, 1.0, v118
	v_rcp_f32_e32 v125, v118
	v_pk_mul_f32 v[118:119], v[120:121], v[150:151] op_sel_hi:[1,0]
	v_add_f32_e32 v124, 1.0, v124
	v_mul_f32_e32 v120, 0xbfb8aa3b, v118
	v_pk_mul_f32 v[116:117], v[118:119], v[116:117]
	v_mul_f32_e32 v118, 0xbfb8aa3b, v119
	v_exp_f32_e32 v120, v120
	v_exp_f32_e32 v118, v118
	v_rcp_f32_e32 v124, v124
	v_pk_mul_f32 v[106:107], v[106:107], v[48:49] op_sel_hi:[1,0]
	v_add_f32_e32 v120, 1.0, v120
	v_add_f32_e32 v118, 1.0, v118
	v_rcp_f32_e32 v120, v120
	v_rcp_f32_e32 v121, v118
	v_pk_mul_f32 v[114:115], v[114:115], v[124:125]
	v_pk_mul_f32 v[106:107], v[110:111], v[106:107]
	v_cvt_pk_bf16_f32 v124, v114, v115
	v_mad_u64_u32 v[114:115], s[20:21], v177, s6, v[152:153]
	v_pk_mul_f32 v[116:117], v[116:117], v[120:121]
	v_mov_b32_e32 v115, v49
	v_cvt_pk_bf16_f32 v125, v116, v117
	v_lshl_add_u64 v[116:117], v[114:115], 1, s[12:13]
	v_mul_f32_e32 v115, 0xbfb8aa3b, v110
	v_mul_f32_e32 v110, 0xbfb8aa3b, v111
	v_exp_f32_e32 v110, v110
	global_store_dwordx4 v[116:117], v[122:125], off
	s_nop 1
	v_pk_mul_f32 v[108:109], v[108:109], v[48:49] op_sel_hi:[1,0]
	v_exp_f32_e32 v115, v115
	v_add_f32_e32 v110, 1.0, v110
	v_rcp_f32_e32 v117, v110
	v_pk_mul_f32 v[110:111], v[112:113], v[48:49] op_sel_hi:[1,0]
	v_add_f32_e32 v115, 1.0, v115
	v_mul_f32_e32 v112, 0xbfb8aa3b, v110
	v_pk_mul_f32 v[108:109], v[110:111], v[108:109]
	v_mul_f32_e32 v110, 0xbfb8aa3b, v111
	v_exp_f32_e32 v112, v112
	v_exp_f32_e32 v110, v110
	v_rcp_f32_e32 v116, v115
	v_pk_mul_f32 v[102:103], v[102:103], v[48:49] op_sel_hi:[1,0]
	v_add_f32_e32 v112, 1.0, v112
	v_add_f32_e32 v110, 1.0, v110
	v_rcp_f32_e32 v112, v112
	v_rcp_f32_e32 v113, v110
	v_pk_mul_f32 v[106:107], v[106:107], v[116:117]
	v_pk_mul_f32 v[98:99], v[98:99], v[48:49] op_sel_hi:[1,0]
	v_cvt_pk_bf16_f32 v106, v106, v107
	v_pk_mul_f32 v[108:109], v[108:109], v[112:113]
	v_pk_mul_f32 v[98:99], v[102:103], v[98:99]
	v_cvt_pk_bf16_f32 v107, v108, v109
	v_mul_f32_e32 v108, 0xbfb8aa3b, v102
	v_mul_f32_e32 v102, 0xbfb8aa3b, v103
	v_exp_f32_e32 v102, v102
	v_exp_f32_e32 v108, v108
	v_pk_mul_f32 v[100:101], v[100:101], v[48:49] op_sel_hi:[1,0]
	v_pk_mul_f32 v[94:95], v[94:95], v[148:149] op_sel_hi:[1,0]
	v_add_f32_e32 v102, 1.0, v102
	v_rcp_f32_e32 v109, v102
	v_pk_mul_f32 v[102:103], v[104:105], v[48:49] op_sel_hi:[1,0]
	v_add_f32_e32 v108, 1.0, v108
	v_mul_f32_e32 v48, 0xbfb8aa3b, v103
	v_exp_f32_e32 v48, v48
	v_rcp_f32_e32 v108, v108
	v_mul_f32_e32 v104, 0xbfb8aa3b, v102
	v_exp_f32_e32 v104, v104
	v_add_f32_e32 v48, 1.0, v48
	v_pk_mul_f32 v[98:99], v[98:99], v[108:109]
	v_rcp_f32_e32 v105, v48
	v_add_u32_e32 v48, 0xb000, v114
	v_add_f32_e32 v104, 1.0, v104
	v_cvt_pk_bf16_f32 v108, v98, v99
	v_lshl_add_u64 v[98:99], v[48:49], 1, s[12:13]
	v_mul_f32_e32 v48, 0xbfb8aa3b, v94
	v_rcp_f32_e32 v104, v104
	v_exp_f32_e32 v48, v48
	v_pk_mul_f32 v[100:101], v[102:103], v[100:101]
	v_pk_mul_f32 v[90:91], v[90:91], v[148:149] op_sel_hi:[1,0]
	v_pk_mul_f32 v[100:101], v[100:101], v[104:105]
	v_add_f32_e32 v48, 1.0, v48
	v_cvt_pk_bf16_f32 v109, v100, v101
	global_store_dwordx4 v[98:99], v[106:109], off
	s_nop 1
	v_rcp_f32_e32 v98, v48
	v_mul_f32_e32 v48, 0xbfb8aa3b, v95
	v_exp_f32_e32 v48, v48
	v_pk_mul_f32 v[90:91], v[94:95], v[90:91]
	v_pk_mul_f32 v[94:95], v[96:97], v[148:149] op_sel_hi:[1,0]
	v_pk_mul_f32 v[86:87], v[86:87], v[148:149] op_sel_hi:[1,0]
	v_add_f32_e32 v48, 1.0, v48
	v_rcp_f32_e32 v99, v48
	v_mul_f32_e32 v48, 0xbfb8aa3b, v94
	v_exp_f32_e32 v48, v48
	v_pk_mul_f32 v[92:93], v[92:93], v[148:149] op_sel_hi:[1,0]
	v_pk_mul_f32 v[90:91], v[90:91], v[98:99]
	v_pk_mul_f32 v[92:93], v[94:95], v[92:93]
	v_add_f32_e32 v48, 1.0, v48
	v_rcp_f32_e32 v96, v48
	v_mul_f32_e32 v48, 0xbfb8aa3b, v95
	v_exp_f32_e32 v48, v48
	v_cvt_pk_bf16_f32 v90, v90, v91
	v_pk_mul_f32 v[82:83], v[82:83], v[148:149] op_sel_hi:[1,0]
	v_pk_mul_f32 v[78:79], v[78:79], v[146:147] op_sel_hi:[1,0]
	v_add_f32_e32 v48, 1.0, v48
	v_rcp_f32_e32 v97, v48
	v_mul_f32_e32 v48, 0xbfb8aa3b, v86
	v_exp_f32_e32 v48, v48
	v_pk_mul_f32 v[82:83], v[86:87], v[82:83]
	v_pk_mul_f32 v[92:93], v[92:93], v[96:97]
	v_pk_mul_f32 v[84:85], v[84:85], v[148:149] op_sel_hi:[1,0]
	v_add_f32_e32 v48, 1.0, v48
	v_cvt_pk_bf16_f32 v91, v92, v93
	v_rcp_f32_e32 v92, v48
	v_mul_f32_e32 v48, 0xbfb8aa3b, v87
	v_exp_f32_e32 v48, v48
	v_pk_mul_f32 v[86:87], v[88:89], v[148:149] op_sel_hi:[1,0]
	v_pk_mul_f32 v[74:75], v[74:75], v[146:147] op_sel_hi:[1,0]
	v_pk_mul_f32 v[84:85], v[86:87], v[84:85]
	v_add_f32_e32 v48, 1.0, v48
	v_rcp_f32_e32 v93, v48
	v_mul_f32_e32 v48, 0xbfb8aa3b, v86
	v_exp_f32_e32 v48, v48
	v_pk_mul_f32 v[74:75], v[78:79], v[74:75]
	v_pk_mul_f32 v[82:83], v[82:83], v[92:93]
	v_pk_mul_f32 v[70:71], v[70:71], v[146:147] op_sel_hi:[1,0]
	v_add_f32_e32 v48, 1.0, v48
	v_rcp_f32_e32 v88, v48
	v_mul_f32_e32 v48, 0xbfb8aa3b, v87
	v_exp_f32_e32 v48, v48
	v_cvt_pk_bf16_f32 v92, v82, v83
	v_pk_mul_f32 v[76:77], v[76:77], v[146:147] op_sel_hi:[1,0]
	v_pk_mul_f32 v[66:67], v[66:67], v[146:147] op_sel_hi:[1,0]
	v_add_f32_e32 v48, 1.0, v48
	v_rcp_f32_e32 v89, v48
	v_add_u32_e32 v48, 0x16000, v114
	v_lshl_add_u64 v[82:83], v[48:49], 1, s[12:13]
	v_mul_f32_e32 v48, 0xbfb8aa3b, v78
	v_exp_f32_e32 v48, v48
	v_pk_mul_f32 v[84:85], v[84:85], v[88:89]
	v_pk_mul_f32 v[66:67], v[70:71], v[66:67]
	v_cvt_pk_bf16_f32 v93, v84, v85
	v_add_f32_e32 v48, 1.0, v48
	global_store_dwordx4 v[82:83], v[90:93], off
	s_nop 1
	v_rcp_f32_e32 v82, v48
	v_mul_f32_e32 v48, 0xbfb8aa3b, v79
	v_exp_f32_e32 v48, v48
	v_pk_mul_f32 v[78:79], v[80:81], v[146:147] op_sel_hi:[1,0]
	v_pk_mul_f32 v[62:63], v[62:63], v[144:145] op_sel_hi:[1,0]
	v_pk_mul_f32 v[76:77], v[78:79], v[76:77]
	v_add_f32_e32 v48, 1.0, v48
	v_rcp_f32_e32 v83, v48
	v_mul_f32_e32 v48, 0xbfb8aa3b, v78
	v_exp_f32_e32 v48, v48
	v_pk_mul_f32 v[68:69], v[68:69], v[146:147] op_sel_hi:[1,0]
	v_pk_mul_f32 v[74:75], v[74:75], v[82:83]
	v_pk_mul_f32 v[58:59], v[58:59], v[144:145] op_sel_hi:[1,0]
	v_add_f32_e32 v48, 1.0, v48
	v_rcp_f32_e32 v80, v48
	v_mul_f32_e32 v48, 0xbfb8aa3b, v79
	v_exp_f32_e32 v48, v48
	v_cvt_pk_bf16_f32 v74, v74, v75
	v_pk_mul_f32 v[58:59], v[62:63], v[58:59]
	v_pk_mul_f32 v[54:55], v[54:55], v[144:145] op_sel_hi:[1,0]
	v_add_f32_e32 v48, 1.0, v48
	v_rcp_f32_e32 v81, v48
	v_mul_f32_e32 v48, 0xbfb8aa3b, v70
	v_exp_f32_e32 v48, v48
	v_pk_mul_f32 v[60:61], v[60:61], v[144:145] op_sel_hi:[1,0]
	v_pk_mul_f32 v[76:77], v[76:77], v[80:81]
	v_pk_mul_f32 v[50:51], v[50:51], v[144:145] op_sel_hi:[1,0]
	v_add_f32_e32 v48, 1.0, v48
	v_cvt_pk_bf16_f32 v75, v76, v77
	v_rcp_f32_e32 v76, v48
	v_mul_f32_e32 v48, 0xbfb8aa3b, v71
	v_exp_f32_e32 v48, v48
	v_pk_mul_f32 v[70:71], v[72:73], v[146:147] op_sel_hi:[1,0]
	v_pk_mul_f32 v[50:51], v[54:55], v[50:51]
	v_pk_mul_f32 v[68:69], v[70:71], v[68:69]
	v_add_f32_e32 v48, 1.0, v48
	v_rcp_f32_e32 v77, v48
	v_mul_f32_e32 v48, 0xbfb8aa3b, v70
	v_exp_f32_e32 v48, v48
	v_pk_mul_f32 v[44:45], v[44:45], v[142:143] op_sel_hi:[1,0]
	v_pk_mul_f32 v[66:67], v[66:67], v[76:77]
	v_pk_mul_f32 v[40:41], v[40:41], v[142:143] op_sel_hi:[1,0]
	v_add_f32_e32 v48, 1.0, v48
	v_rcp_f32_e32 v72, v48
	v_mul_f32_e32 v48, 0xbfb8aa3b, v71
	v_exp_f32_e32 v48, v48
	v_cvt_pk_bf16_f32 v76, v66, v67
	v_pk_mul_f32 v[40:41], v[44:45], v[40:41]
	v_pk_mul_f32 v[52:53], v[52:53], v[144:145] op_sel_hi:[1,0]
	v_add_f32_e32 v48, 1.0, v48
	v_rcp_f32_e32 v73, v48
	v_add_u32_e32 v48, 0x21000, v114
	v_lshl_add_u64 v[66:67], v[48:49], 1, s[12:13]
	v_mul_f32_e32 v48, 0xbfb8aa3b, v62
	v_exp_f32_e32 v48, v48
	v_pk_mul_f32 v[68:69], v[68:69], v[72:73]
	v_pk_mul_f32 v[42:43], v[42:43], v[142:143] op_sel_hi:[1,0]
	v_cvt_pk_bf16_f32 v77, v68, v69
	v_add_f32_e32 v48, 1.0, v48
	global_store_dwordx4 v[66:67], v[74:77], off
	s_nop 1
	v_rcp_f32_e32 v66, v48
	v_mul_f32_e32 v48, 0xbfb8aa3b, v63
	v_exp_f32_e32 v48, v48
	v_pk_mul_f32 v[62:63], v[64:65], v[144:145] op_sel_hi:[1,0]
	v_pk_mul_f32 v[36:37], v[36:37], v[142:143] op_sel_hi:[1,0]
	v_pk_mul_f32 v[60:61], v[62:63], v[60:61]
	v_add_f32_e32 v48, 1.0, v48
	v_rcp_f32_e32 v67, v48
	v_mul_f32_e32 v48, 0xbfb8aa3b, v62
	v_exp_f32_e32 v48, v48
	v_pk_mul_f32 v[32:33], v[32:33], v[142:143] op_sel_hi:[1,0]
	v_pk_mul_f32 v[58:59], v[58:59], v[66:67]
	v_pk_mul_f32 v[32:33], v[36:37], v[32:33]
	v_add_f32_e32 v48, 1.0, v48
	v_rcp_f32_e32 v64, v48
	v_mul_f32_e32 v48, 0xbfb8aa3b, v63
	v_exp_f32_e32 v48, v48
	v_cvt_pk_bf16_f32 v58, v58, v59
	v_pk_mul_f32 v[34:35], v[34:35], v[142:143] op_sel_hi:[1,0]
	v_pk_mul_f32 v[28:29], v[28:29], v[140:141] op_sel_hi:[1,0]
	v_add_f32_e32 v48, 1.0, v48
	v_rcp_f32_e32 v65, v48
	v_mul_f32_e32 v48, 0xbfb8aa3b, v54
	v_exp_f32_e32 v48, v48
	v_pk_mul_f32 v[24:25], v[24:25], v[140:141] op_sel_hi:[1,0]
	v_pk_mul_f32 v[60:61], v[60:61], v[64:65]
	v_pk_mul_f32 v[24:25], v[28:29], v[24:25]
	v_add_f32_e32 v48, 1.0, v48
	v_cvt_pk_bf16_f32 v59, v60, v61
	v_rcp_f32_e32 v60, v48
	v_mul_f32_e32 v48, 0xbfb8aa3b, v55
	v_exp_f32_e32 v48, v48
	v_pk_mul_f32 v[54:55], v[56:57], v[144:145] op_sel_hi:[1,0]
	v_pk_mul_f32 v[26:27], v[26:27], v[140:141] op_sel_hi:[1,0]
	v_pk_mul_f32 v[52:53], v[54:55], v[52:53]
	v_add_f32_e32 v48, 1.0, v48
	v_rcp_f32_e32 v61, v48
	v_mul_f32_e32 v48, 0xbfb8aa3b, v54
	v_exp_f32_e32 v48, v48
	v_pk_mul_f32 v[20:21], v[20:21], v[140:141] op_sel_hi:[1,0]
	v_pk_mul_f32 v[50:51], v[50:51], v[60:61]
	v_pk_mul_f32 v[16:17], v[16:17], v[140:141] op_sel_hi:[1,0]
	v_add_f32_e32 v48, 1.0, v48
	v_rcp_f32_e32 v56, v48
	v_mul_f32_e32 v48, 0xbfb8aa3b, v55
	v_exp_f32_e32 v48, v48
	v_cvt_pk_bf16_f32 v60, v50, v51
	v_pk_mul_f32 v[16:17], v[20:21], v[16:17]
	v_pk_mul_f32 v[18:19], v[18:19], v[140:141] op_sel_hi:[1,0]
	v_add_f32_e32 v48, 1.0, v48
	v_rcp_f32_e32 v57, v48
	v_add_u32_e32 v48, 0x58000, v114
	v_lshl_add_u64 v[50:51], v[48:49], 1, s[12:13]
	v_mul_f32_e32 v48, 0xbfb8aa3b, v44
	v_mul_f32_e32 v44, 0xbfb8aa3b, v45
	v_exp_f32_e32 v44, v44
	v_pk_mul_f32 v[52:53], v[52:53], v[56:57]
	v_exp_f32_e32 v48, v48
	v_cvt_pk_bf16_f32 v61, v52, v53
	v_add_f32_e32 v44, 1.0, v44
	global_store_dwordx4 v[50:51], v[58:61], off
	s_nop 1
	v_rcp_f32_e32 v51, v44
	v_pk_mul_f32 v[44:45], v[46:47], v[142:143] op_sel_hi:[1,0]
	v_add_f32_e32 v48, 1.0, v48
	v_mul_f32_e32 v46, 0xbfb8aa3b, v44
	v_pk_mul_f32 v[42:43], v[44:45], v[42:43]
	v_mul_f32_e32 v44, 0xbfb8aa3b, v45
	v_exp_f32_e32 v46, v46
	v_exp_f32_e32 v44, v44
	v_rcp_f32_e32 v50, v48
	v_add_u32_e32 v48, 0x63000, v114
	v_add_f32_e32 v46, 1.0, v46
	v_add_f32_e32 v44, 1.0, v44
	v_rcp_f32_e32 v46, v46
	v_rcp_f32_e32 v47, v44
	v_pk_mul_f32 v[40:41], v[40:41], v[50:51]
	v_pk_mul_f32 v[12:13], v[12:13], v[138:139] op_sel_hi:[1,0]
	v_cvt_pk_bf16_f32 v40, v40, v41
	v_pk_mul_f32 v[42:43], v[42:43], v[46:47]
	v_pk_mul_f32 v[8:9], v[8:9], v[138:139] op_sel_hi:[1,0]
	v_cvt_pk_bf16_f32 v41, v42, v43
	v_mul_f32_e32 v42, 0xbfb8aa3b, v36
	v_mul_f32_e32 v36, 0xbfb8aa3b, v37
	v_exp_f32_e32 v36, v36
	v_exp_f32_e32 v42, v42
	v_pk_mul_f32 v[8:9], v[12:13], v[8:9]
	v_pk_mul_f32 v[10:11], v[10:11], v[138:139] op_sel_hi:[1,0]
	v_add_f32_e32 v36, 1.0, v36
	v_rcp_f32_e32 v43, v36
	v_pk_mul_f32 v[36:37], v[38:39], v[142:143] op_sel_hi:[1,0]
	v_add_f32_e32 v42, 1.0, v42
	v_mul_f32_e32 v38, 0xbfb8aa3b, v36
	v_pk_mul_f32 v[34:35], v[36:37], v[34:35]
	v_mul_f32_e32 v36, 0xbfb8aa3b, v37
	v_exp_f32_e32 v38, v38
	v_exp_f32_e32 v36, v36
	v_rcp_f32_e32 v42, v42
	v_pk_mul_f32 v[4:5], v[4:5], v[138:139] op_sel_hi:[1,0]
	v_add_f32_e32 v38, 1.0, v38
	v_add_f32_e32 v36, 1.0, v36
	v_rcp_f32_e32 v38, v38
	v_rcp_f32_e32 v39, v36
	v_pk_mul_f32 v[32:33], v[32:33], v[42:43]
	v_pk_mul_f32 v[0:1], v[0:1], v[138:139] op_sel_hi:[1,0]
	v_cvt_pk_bf16_f32 v42, v32, v33
	v_pk_mul_f32 v[34:35], v[34:35], v[38:39]
	v_lshl_add_u64 v[32:33], v[48:49], 1, s[12:13]
	v_cvt_pk_bf16_f32 v43, v34, v35
	global_store_dwordx4 v[32:33], v[40:43], off
	s_nop 1
	v_mul_f32_e32 v32, 0xbfb8aa3b, v28
	v_mul_f32_e32 v28, 0xbfb8aa3b, v29
	v_exp_f32_e32 v28, v28
	v_exp_f32_e32 v32, v32
	v_add_u32_e32 v48, 0x6e000, v114
	v_pk_mul_f32 v[0:1], v[4:5], v[0:1]
	v_add_f32_e32 v28, 1.0, v28
	v_rcp_f32_e32 v33, v28
	v_pk_mul_f32 v[28:29], v[30:31], v[140:141] op_sel_hi:[1,0]
	v_add_f32_e32 v32, 1.0, v32
	v_mul_f32_e32 v30, 0xbfb8aa3b, v28
	v_pk_mul_f32 v[26:27], v[28:29], v[26:27]
	v_mul_f32_e32 v28, 0xbfb8aa3b, v29
	v_exp_f32_e32 v30, v30
	v_exp_f32_e32 v28, v28
	v_rcp_f32_e32 v32, v32
	v_pk_mul_f32 v[2:3], v[2:3], v[138:139] op_sel_hi:[1,0]
	v_add_f32_e32 v30, 1.0, v30
	v_add_f32_e32 v28, 1.0, v28
	v_rcp_f32_e32 v30, v30
	v_rcp_f32_e32 v31, v28
	v_pk_mul_f32 v[24:25], v[24:25], v[32:33]
	s_mov_b64 s[38:39], -1
	v_cvt_pk_bf16_f32 v24, v24, v25
	v_pk_mul_f32 v[26:27], v[26:27], v[30:31]
	s_andn2_b64 vcc, exec, s[46:47]
	v_cvt_pk_bf16_f32 v25, v26, v27
	v_mul_f32_e32 v26, 0xbfb8aa3b, v20
	v_mul_f32_e32 v20, 0xbfb8aa3b, v21
	v_exp_f32_e32 v20, v20
	v_exp_f32_e32 v26, v26
	v_add_f32_e32 v20, 1.0, v20
	v_rcp_f32_e32 v27, v20
	v_pk_mul_f32 v[20:21], v[22:23], v[140:141] op_sel_hi:[1,0]
	v_add_f32_e32 v26, 1.0, v26
	v_mul_f32_e32 v22, 0xbfb8aa3b, v20
	v_pk_mul_f32 v[18:19], v[20:21], v[18:19]
	v_mul_f32_e32 v20, 0xbfb8aa3b, v21
	v_exp_f32_e32 v22, v22
	v_exp_f32_e32 v20, v20
	v_rcp_f32_e32 v26, v26
	v_add_f32_e32 v22, 1.0, v22
	v_add_f32_e32 v20, 1.0, v20
	v_rcp_f32_e32 v22, v22
	v_rcp_f32_e32 v23, v20
	v_pk_mul_f32 v[16:17], v[16:17], v[26:27]
	v_pk_mul_f32 v[18:19], v[18:19], v[22:23]
	v_cvt_pk_bf16_f32 v26, v16, v17
	v_lshl_add_u64 v[16:17], v[48:49], 1, s[12:13]
	v_cvt_pk_bf16_f32 v27, v18, v19
	global_store_dwordx4 v[16:17], v[24:27], off
	s_nop 1
	v_mul_f32_e32 v16, 0xbfb8aa3b, v12
	v_mul_f32_e32 v12, 0xbfb8aa3b, v13
	v_exp_f32_e32 v12, v12
	v_exp_f32_e32 v16, v16
	v_add_u32_e32 v48, 0x79000, v114
	v_add_f32_e32 v12, 1.0, v12
	v_rcp_f32_e32 v17, v12
	v_pk_mul_f32 v[12:13], v[14:15], v[138:139] op_sel_hi:[1,0]
	v_add_f32_e32 v16, 1.0, v16
	v_mul_f32_e32 v14, 0xbfb8aa3b, v12
	v_pk_mul_f32 v[10:11], v[12:13], v[10:11]
	v_mul_f32_e32 v12, 0xbfb8aa3b, v13
	v_exp_f32_e32 v14, v14
	v_exp_f32_e32 v12, v12
	v_rcp_f32_e32 v16, v16
	v_add_f32_e32 v14, 1.0, v14
	v_add_f32_e32 v12, 1.0, v12
	v_rcp_f32_e32 v14, v14
	v_rcp_f32_e32 v15, v12
	v_pk_mul_f32 v[8:9], v[8:9], v[16:17]
	v_pk_mul_f32 v[10:11], v[10:11], v[14:15]
	v_cvt_pk_bf16_f32 v8, v8, v9
	v_cvt_pk_bf16_f32 v9, v10, v11
	v_mul_f32_e32 v10, 0xbfb8aa3b, v4
	v_mul_f32_e32 v4, 0xbfb8aa3b, v5
	v_exp_f32_e32 v4, v4
	v_exp_f32_e32 v10, v10
	v_add_f32_e32 v4, 1.0, v4
	v_rcp_f32_e32 v11, v4
	v_pk_mul_f32 v[4:5], v[6:7], v[138:139] op_sel_hi:[1,0]
	v_add_f32_e32 v10, 1.0, v10
	v_mul_f32_e32 v6, 0xbfb8aa3b, v4
	v_pk_mul_f32 v[2:3], v[4:5], v[2:3]
	v_mul_f32_e32 v4, 0xbfb8aa3b, v5
	v_exp_f32_e32 v6, v6
	v_exp_f32_e32 v4, v4
	v_rcp_f32_e32 v10, v10
	v_add_f32_e32 v6, 1.0, v6
	v_add_f32_e32 v4, 1.0, v4
	v_rcp_f32_e32 v6, v6
	v_rcp_f32_e32 v7, v4
	v_pk_mul_f32 v[0:1], v[0:1], v[10:11]
	v_pk_mul_f32 v[2:3], v[2:3], v[6:7]
	v_cvt_pk_bf16_f32 v10, v0, v1
	v_cvt_pk_bf16_f32 v11, v2, v3
	v_lshl_add_u64 v[0:1], v[48:49], 1, s[12:13]
	global_store_dwordx4 v[0:1], v[8:11], off
	s_nop 1
	s_cbranch_vccnz .LBB0_1407
	s_andn2_b64 vcc, exec, s[2:3]
	s_cbranch_vccnz .LBB0_1406
	s_barrier
	s_branch .LBB0_1406
